# hazard-pad cleanup: removed 33 XNACK-replay s_nop 0 between back-to-back global loads (attention gathers, epilogues)
# speedup vs baseline: 1.0014x; 1.0014x over previous
; #define LAS __attribute__((address_space(3)))
; #define QK_LOAD(set, st) do { _Pragma("unroll") for (int i = 0; i < 4; ++i) { const int row = widx[(st) * 32 + i * 8 + (lane >> 3)] & 4095; R[set][i] = *(const u32x4*)(kg + (size_t)row * 512); } __builtin_amdgcn_sched_barrier(0); } while (0)
; __device__ __forceinline__ void attn_phase(const int TID, const int BID, PP p, LAS unsigned char* lds) {
;     ...
;                 { const unsigned char* qp = (const unsigned char*)Qb + (size_t)tok * 2048 + (g * 4 + (lane & 3)) * 128 + fq * 8;
; #pragma unroll
;                   for (int ks = 0; ks < 4; ++ks) q8[ks] = *(const long*)(qp + ks * 32); }
;                 u32x4 R[3][4];
;                 const unsigned char* kg = (const unsigned char*)Kb + (size_t)(b * SEQ) * 512 + g * 128 + (lane & 7) * 16;
;                 LAS unsigned char* ktw = vt + (lane >> 3) * 144 + (lane & 7) * 16;
;                 const LAS unsigned char* ktr = vt + fr * 144 + fq * 8;
;                 const int nst = nsel >> 5;
;     ...
;                 QK_LOAD(0, 0); QK_LOAD(1, 1); QK_LOAD(2, 2);
;                 QK_STEP(0, 0, true); QK_STEP(1, 1, true); QK_STEP(2, 2, true); QK_STEP(0, 3, true); QK_STEP(1, 4, true);
.LBB0_693:
	ds_read_u16 v2, v125
	v_lshl_add_u64 v[0:1], s[2:3], 0, v[88:89]
	global_load_dwordx2 v[100:101], v[0:1], off offset:-64
	global_load_dwordx2 v[94:95], v[0:1], off offset:-32
	global_load_dwordx2 v[96:97], v[0:1], off
	global_load_dwordx2 v[92:93], v[0:1], off offset:32
	ds_read_u16 v3, v125 offset:16
	ds_read_u16 v8, v125 offset:32
	ds_read_u16 v10, v125 offset:48
	s_waitcnt lgkmcnt(3)
	v_and_b32_e32 v0, 0xfff, v2
	v_lshlrev_b32_sdwa v160, v191, v0 dst_sel:DWORD dst_unused:UNUSED_PAD src0_sel:DWORD src1_sel:WORD_0
	v_lshl_add_u64 v[0:1], v[86:87], 0, v[160:161]
	s_waitcnt lgkmcnt(2)
	v_and_b32_e32 v2, 0xfff, v3
	v_lshl_add_u64 v[0:1], s[2:3], 0, v[0:1]
	v_lshlrev_b32_sdwa v160, v191, v2 dst_sel:DWORD dst_unused:UNUSED_PAD src0_sel:DWORD src1_sel:WORD_0
	v_add_co_u32_e32 v0, vcc, s63, v0
	v_lshl_add_u64 v[2:3], v[86:87], 0, v[160:161]
	s_waitcnt lgkmcnt(1)
	v_and_b32_e32 v8, 0xfff, v8
	v_addc_co_u32_e32 v1, vcc, 0, v1, vcc
	v_lshl_add_u64 v[2:3], s[2:3], 0, v[2:3]
	v_lshlrev_b32_sdwa v160, v191, v8 dst_sel:DWORD dst_unused:UNUSED_PAD src0_sel:DWORD src1_sel:WORD_0
	v_add_co_u32_e32 v4, vcc, s63, v2
	v_lshl_add_u64 v[8:9], v[86:87], 0, v[160:161]
	s_waitcnt lgkmcnt(0)
	v_and_b32_e32 v10, 0xfff, v10
	v_addc_co_u32_e32 v5, vcc, 0, v3, vcc
	v_lshl_add_u64 v[8:9], s[2:3], 0, v[8:9]
	v_lshlrev_b32_sdwa v160, v191, v10 dst_sel:DWORD dst_unused:UNUSED_PAD src0_sel:DWORD src1_sel:WORD_0
	v_add_co_u32_e32 v8, vcc, s63, v8
	v_lshl_add_u64 v[10:11], v[86:87], 0, v[160:161]
	s_nop 0
	v_addc_co_u32_e32 v9, vcc, 0, v9, vcc
	v_lshl_add_u64 v[10:11], s[2:3], 0, v[10:11]
	v_add_co_u32_e32 v12, vcc, s63, v10
	global_load_dwordx4 v[0:3], v[0:1], off
	global_load_dwordx4 v[4:7], v[4:5], off
	v_addc_co_u32_e32 v13, vcc, 0, v11, vcc
	global_load_dwordx4 v[8:11], v[8:9], off
	global_load_dwordx4 v[12:15], v[12:13], off
	ds_read_u16 v16, v125 offset:64
	ds_read_u16 v18, v125 offset:80
	ds_read_u16 v24, v125 offset:96
	ds_read_u16 v26, v125 offset:112
	s_waitcnt lgkmcnt(3)
	v_and_b32_e32 v16, 0xfff, v16
	v_lshlrev_b32_sdwa v160, v191, v16 dst_sel:DWORD dst_unused:UNUSED_PAD src0_sel:DWORD src1_sel:WORD_0
	v_lshl_add_u64 v[16:17], v[86:87], 0, v[160:161]
	s_waitcnt lgkmcnt(2)
	v_and_b32_e32 v18, 0xfff, v18
	v_lshl_add_u64 v[16:17], s[2:3], 0, v[16:17]
	v_lshlrev_b32_sdwa v160, v191, v18 dst_sel:DWORD dst_unused:UNUSED_PAD src0_sel:DWORD src1_sel:WORD_0
	v_add_co_u32_e32 v16, vcc, s63, v16
	v_lshl_add_u64 v[18:19], v[86:87], 0, v[160:161]
	s_waitcnt lgkmcnt(1)
	v_and_b32_e32 v24, 0xfff, v24
	v_addc_co_u32_e32 v17, vcc, 0, v17, vcc
	v_lshl_add_u64 v[18:19], s[2:3], 0, v[18:19]
	v_lshlrev_b32_sdwa v160, v191, v24 dst_sel:DWORD dst_unused:UNUSED_PAD src0_sel:DWORD src1_sel:WORD_0
	v_add_co_u32_e32 v20, vcc, s63, v18
	v_lshl_add_u64 v[24:25], v[86:87], 0, v[160:161]
	s_waitcnt lgkmcnt(0)
	v_and_b32_e32 v26, 0xfff, v26
	v_addc_co_u32_e32 v21, vcc, 0, v19, vcc
	v_lshl_add_u64 v[24:25], s[2:3], 0, v[24:25]
	v_lshlrev_b32_sdwa v160, v191, v26 dst_sel:DWORD dst_unused:UNUSED_PAD src0_sel:DWORD src1_sel:WORD_0
	v_add_co_u32_e32 v24, vcc, s63, v24
	v_lshl_add_u64 v[26:27], v[86:87], 0, v[160:161]
	s_nop 0
	v_addc_co_u32_e32 v25, vcc, 0, v25, vcc
	v_lshl_add_u64 v[26:27], s[2:3], 0, v[26:27]
	v_add_co_u32_e32 v28, vcc, s63, v26
	global_load_dwordx4 v[16:19], v[16:17], off
	global_load_dwordx4 v[20:23], v[20:21], off
	v_addc_co_u32_e32 v29, vcc, 0, v27, vcc
	global_load_dwordx4 v[24:27], v[24:25], off
	global_load_dwordx4 v[28:31], v[28:29], off
	ds_read_u16 v32, v125 offset:128
	ds_read_u16 v34, v125 offset:144
	ds_read_u16 v40, v125 offset:160
	ds_read_u16 v42, v125 offset:176
	s_waitcnt lgkmcnt(3)
	v_and_b32_e32 v32, 0xfff, v32
	v_lshlrev_b32_sdwa v160, v191, v32 dst_sel:DWORD dst_unused:UNUSED_PAD src0_sel:DWORD src1_sel:WORD_0
	v_lshl_add_u64 v[32:33], v[86:87], 0, v[160:161]
	s_waitcnt lgkmcnt(2)
	v_and_b32_e32 v34, 0xfff, v34
	v_lshl_add_u64 v[32:33], s[2:3], 0, v[32:33]
	v_lshlrev_b32_sdwa v160, v191, v34 dst_sel:DWORD dst_unused:UNUSED_PAD src0_sel:DWORD src1_sel:WORD_0
	v_add_co_u32_e32 v32, vcc, s63, v32
	v_lshl_add_u64 v[34:35], v[86:87], 0, v[160:161]
	s_waitcnt lgkmcnt(1)
	v_and_b32_e32 v40, 0xfff, v40
	v_addc_co_u32_e32 v33, vcc, 0, v33, vcc
	v_lshl_add_u64 v[34:35], s[2:3], 0, v[34:35]
	v_lshlrev_b32_sdwa v160, v191, v40 dst_sel:DWORD dst_unused:UNUSED_PAD src0_sel:DWORD src1_sel:WORD_0
	v_add_co_u32_e32 v36, vcc, s63, v34
	v_lshl_add_u64 v[40:41], v[86:87], 0, v[160:161]
	s_waitcnt lgkmcnt(0)
	v_and_b32_e32 v42, 0xfff, v42
	v_addc_co_u32_e32 v37, vcc, 0, v35, vcc
	v_lshl_add_u64 v[40:41], s[2:3], 0, v[40:41]
	v_lshlrev_b32_sdwa v160, v191, v42 dst_sel:DWORD dst_unused:UNUSED_PAD src0_sel:DWORD src1_sel:WORD_0
	v_add_co_u32_e32 v40, vcc, s63, v40
	v_lshl_add_u64 v[42:43], v[86:87], 0, v[160:161]
	s_nop 0
	v_addc_co_u32_e32 v41, vcc, 0, v41, vcc
	v_lshl_add_u64 v[42:43], s[2:3], 0, v[42:43]
	v_add_co_u32_e32 v44, vcc, s63, v42
	global_load_dwordx4 v[32:35], v[32:33], off
	global_load_dwordx4 v[36:39], v[36:37], off
	v_addc_co_u32_e32 v45, vcc, 0, v43, vcc
	global_load_dwordx4 v[40:43], v[40:41], off
	global_load_dwordx4 v[44:47], v[44:45], off
	s_waitcnt vmcnt(11)
	ds_write_b128 v135, v[0:3] offset:4096
	s_waitcnt vmcnt(10)
	ds_write_b128 v135, v[4:7] offset:5248
	s_waitcnt vmcnt(9)
	ds_write_b128 v135, v[8:11] offset:6400
	s_waitcnt vmcnt(8)
	ds_write_b128 v135, v[12:15] offset:7552
	ds_read_u16 v0, v125 offset:192
	ds_read_u16 v2, v125 offset:208
	ds_read_u16 v4, v125 offset:224
	ds_read_u16 v5, v125 offset:240
	s_waitcnt lgkmcnt(3)
	v_and_b32_e32 v0, 0xfff, v0
	v_lshlrev_b32_sdwa v160, v191, v0 dst_sel:DWORD dst_unused:UNUSED_PAD src0_sel:DWORD src1_sel:WORD_0
	v_lshl_add_u64 v[0:1], v[86:87], 0, v[160:161]
	s_waitcnt lgkmcnt(2)
; #define QK_LOAD(set, st) do { _Pragma("unroll") for (int i = 0; i < 4; ++i) { const int row = widx[(st) * 32 + i * 8 + (lane >> 3)] & 4095; R[set][i] = *(const u32x4*)(kg + (size_t)row * 512); } __builtin_amdgcn_sched_barrier(0); } while (0)
; __device__ __forceinline__ void attn_phase(const int TID, const int BID, PP p, LAS unsigned char* lds) {
;     ...
;                 QK_LOAD(0, 0); QK_LOAD(1, 1); QK_LOAD(2, 2);
;                 QK_STEP(0, 0, true); QK_STEP(1, 1, true); QK_STEP(2, 2, true); QK_STEP(0, 3, true); QK_STEP(1, 4, true);
	v_and_b32_e32 v2, 0xfff, v2
	v_lshl_add_u64 v[0:1], s[2:3], 0, v[0:1]
	v_lshlrev_b32_sdwa v160, v191, v2 dst_sel:DWORD dst_unused:UNUSED_PAD src0_sel:DWORD src1_sel:WORD_0
	v_add_co_u32_e32 v0, vcc, s63, v0
	v_lshl_add_u64 v[2:3], v[86:87], 0, v[160:161]
	s_nop 0
	v_addc_co_u32_e32 v1, vcc, 0, v1, vcc
	v_lshl_add_u64 v[2:3], s[2:3], 0, v[2:3]
	v_add_co_u32_e32 v2, vcc, s63, v2
	s_nop 1
	v_addc_co_u32_e32 v3, vcc, 0, v3, vcc
	global_load_dwordx4 v[48:51], v[0:1], off
	global_load_dwordx4 v[56:59], v[2:3], off
	s_waitcnt lgkmcnt(1)
	v_and_b32_e32 v0, 0xfff, v4
	v_lshlrev_b32_sdwa v160, v191, v0 dst_sel:DWORD dst_unused:UNUSED_PAD src0_sel:DWORD src1_sel:WORD_0
	v_lshl_add_u64 v[0:1], v[86:87], 0, v[160:161]
	s_waitcnt lgkmcnt(0)
	v_and_b32_e32 v2, 0xfff, v5
	v_lshl_add_u64 v[0:1], s[2:3], 0, v[0:1]
	v_lshlrev_b32_sdwa v160, v191, v2 dst_sel:DWORD dst_unused:UNUSED_PAD src0_sel:DWORD src1_sel:WORD_0
	v_add_co_u32_e32 v0, vcc, s63, v0
	v_lshl_add_u64 v[2:3], v[86:87], 0, v[160:161]
	s_nop 0
	v_addc_co_u32_e32 v1, vcc, 0, v1, vcc
	v_lshl_add_u64 v[2:3], s[2:3], 0, v[2:3]
	v_add_co_u32_e32 v2, vcc, s63, v2
	s_nop 1
	v_addc_co_u32_e32 v3, vcc, 0, v3, vcc
	global_load_dwordx4 v[72:75], v[0:1], off
	global_load_dwordx4 v[76:79], v[2:3], off
	v_add_u32_e32 v143, 0x1000, v136
	v_add_u32_e32 v144, 0x1800, v136
	ds_read2_b64 v[0:3], v143 offset1:4
	ds_read2_b64 v[10:13], v144 offset0:32 offset1:36
	ds_read2_b64 v[60:63], v143 offset0:8 offset1:12
	ds_read2_b64 v[68:71], v144 offset0:40 offset1:44
	s_waitcnt lgkmcnt(3)
	v_mfma_f32_16x16x32_fp8_fp8 v[4:7], v[0:1], v[100:101], 0
	s_waitcnt lgkmcnt(2)
	v_mfma_f32_16x16x32_fp8_fp8 v[52:55], v[10:11], v[100:101], 0
	s_waitcnt lgkmcnt(1)
	v_mfma_f32_16x16x32_fp8_fp8 v[64:67], v[60:61], v[96:97], 0
	s_waitcnt lgkmcnt(0)
	v_mfma_f32_16x16x32_fp8_fp8 v[102:105], v[68:69], v[96:97], 0
	v_mfma_f32_16x16x32_fp8_fp8 v[8:11], v[2:3], v[94:95], v[4:7]
	v_mfma_f32_16x16x32_fp8_fp8 v[0:3], v[12:13], v[94:95], v[52:55]
	v_mfma_f32_16x16x32_fp8_fp8 v[12:15], v[62:63], v[92:93], v[64:67]
	v_mfma_f32_16x16x32_fp8_fp8 v[4:7], v[70:71], v[92:93], v[102:105]
	s_waitcnt vmcnt(11)
	ds_write_b128 v135, v[16:19] offset:4096
	s_waitcnt vmcnt(10)
	ds_write_b128 v135, v[20:23] offset:5248
	s_waitcnt vmcnt(9)
	ds_write_b128 v135, v[24:27] offset:6400
	s_waitcnt vmcnt(8)
	ds_write_b128 v135, v[28:31] offset:7552
	ds_read_u16 v16, v125 offset:256
	ds_read_u16 v18, v125 offset:272
	ds_read_u16 v20, v125 offset:288
	ds_read_u16 v21, v125 offset:304
	s_waitcnt lgkmcnt(3)
	v_and_b32_e32 v16, 0xfff, v16
	v_lshlrev_b32_sdwa v160, v191, v16 dst_sel:DWORD dst_unused:UNUSED_PAD src0_sel:DWORD src1_sel:WORD_0
	v_lshl_add_u64 v[16:17], v[86:87], 0, v[160:161]
	s_waitcnt lgkmcnt(2)
	v_and_b32_e32 v18, 0xfff, v18
	v_lshl_add_u64 v[16:17], s[2:3], 0, v[16:17]
	v_lshlrev_b32_sdwa v160, v191, v18 dst_sel:DWORD dst_unused:UNUSED_PAD src0_sel:DWORD src1_sel:WORD_0
	v_add_co_u32_e32 v16, vcc, s63, v16
	v_lshl_add_u64 v[18:19], v[86:87], 0, v[160:161]
	s_nop 0
	v_addc_co_u32_e32 v17, vcc, 0, v17, vcc
	v_lshl_add_u64 v[18:19], s[2:3], 0, v[18:19]
	v_add_co_u32_e32 v18, vcc, s63, v18
	s_nop 1
	v_addc_co_u32_e32 v19, vcc, 0, v19, vcc
	global_load_dwordx4 v[52:55], v[16:17], off
	global_load_dwordx4 v[60:63], v[18:19], off
	s_waitcnt lgkmcnt(1)
	v_and_b32_e32 v16, 0xfff, v20
	v_lshlrev_b32_sdwa v160, v191, v16 dst_sel:DWORD dst_unused:UNUSED_PAD src0_sel:DWORD src1_sel:WORD_0
	v_lshl_add_u64 v[16:17], v[86:87], 0, v[160:161]
	s_waitcnt lgkmcnt(0)
	v_and_b32_e32 v18, 0xfff, v21
	v_lshl_add_u64 v[16:17], s[2:3], 0, v[16:17]
	v_lshlrev_b32_sdwa v160, v191, v18 dst_sel:DWORD dst_unused:UNUSED_PAD src0_sel:DWORD src1_sel:WORD_0
	v_add_co_u32_e32 v16, vcc, s63, v16
	v_lshl_add_u64 v[18:19], v[86:87], 0, v[160:161]
	s_nop 0
	v_addc_co_u32_e32 v17, vcc, 0, v17, vcc
	v_lshl_add_u64 v[18:19], s[2:3], 0, v[18:19]
	v_add_co_u32_e32 v18, vcc, s63, v18
	s_nop 1
	v_addc_co_u32_e32 v19, vcc, 0, v19, vcc
	global_load_dwordx4 v[64:67], v[16:17], off
	global_load_dwordx4 v[68:71], v[18:19], off
	ds_read2_b64 v[16:19], v143 offset1:4
	ds_read2_b64 v[26:29], v144 offset0:32 offset1:36
	ds_read2_b64 v[106:109], v143 offset0:8 offset1:12
	ds_read2_b64 v[114:117], v144 offset0:40 offset1:44
	s_waitcnt lgkmcnt(3)
	v_mfma_f32_16x16x32_fp8_fp8 v[20:23], v[16:17], v[100:101], 0
	s_waitcnt lgkmcnt(2)
	v_mfma_f32_16x16x32_fp8_fp8 v[102:105], v[26:27], v[100:101], 0
	s_waitcnt lgkmcnt(1)
	v_mfma_f32_16x16x32_fp8_fp8 v[110:113], v[106:107], v[96:97], 0
	s_waitcnt lgkmcnt(0)
	v_mfma_f32_16x16x32_fp8_fp8 v[118:121], v[114:115], v[96:97], 0
	v_mfma_f32_16x16x32_fp8_fp8 v[24:27], v[18:19], v[94:95], v[20:23]
	v_mfma_f32_16x16x32_fp8_fp8 v[16:19], v[28:29], v[94:95], v[102:105]
	v_mfma_f32_16x16x32_fp8_fp8 v[28:31], v[108:109], v[92:93], v[110:113]
	v_mfma_f32_16x16x32_fp8_fp8 v[20:23], v[116:117], v[92:93], v[118:121]
	s_waitcnt vmcnt(11)
	ds_write_b128 v135, v[32:35] offset:4096
	s_waitcnt vmcnt(10)
	ds_write_b128 v135, v[36:39] offset:5248
	s_waitcnt vmcnt(9)
	ds_write_b128 v135, v[40:43] offset:6400
	s_waitcnt vmcnt(8)
	ds_write_b128 v135, v[44:47] offset:7552
	ds_read_u16 v32, v125 offset:320
	ds_read_u16 v34, v125 offset:336
	ds_read_u16 v40, v125 offset:352
	ds_read_u16 v42, v125 offset:368
	s_waitcnt lgkmcnt(3)
	v_and_b32_e32 v32, 0xfff, v32
	v_lshlrev_b32_sdwa v160, v191, v32 dst_sel:DWORD dst_unused:UNUSED_PAD src0_sel:DWORD src1_sel:WORD_0
	v_lshl_add_u64 v[32:33], v[86:87], 0, v[160:161]
	s_waitcnt lgkmcnt(2)
	v_and_b32_e32 v34, 0xfff, v34
	v_lshl_add_u64 v[32:33], s[2:3], 0, v[32:33]
	v_lshlrev_b32_sdwa v160, v191, v34 dst_sel:DWORD dst_unused:UNUSED_PAD src0_sel:DWORD src1_sel:WORD_0
	v_add_co_u32_e32 v32, vcc, s63, v32
	v_lshl_add_u64 v[34:35], v[86:87], 0, v[160:161]
	s_waitcnt lgkmcnt(1)
; #define QK_LOAD(set, st) do { _Pragma("unroll") for (int i = 0; i < 4; ++i) { const int row = widx[(st) * 32 + i * 8 + (lane >> 3)] & 4095; R[set][i] = *(const u32x4*)(kg + (size_t)row * 512); } __builtin_amdgcn_sched_barrier(0); } while (0)
; __device__ __forceinline__ void attn_phase(const int TID, const int BID, PP p, LAS unsigned char* lds) {
;     ...
;                 QK_LOAD(0, 0); QK_LOAD(1, 1); QK_LOAD(2, 2);
;                 QK_STEP(0, 0, true); QK_STEP(1, 1, true); QK_STEP(2, 2, true); QK_STEP(0, 3, true); QK_STEP(1, 4, true);
;                 QK_STEP(2, 5, false); QK_STEP(0, 6, false); QK_STEP(1, 7, false);
	v_and_b32_e32 v40, 0xfff, v40
	v_addc_co_u32_e32 v33, vcc, 0, v33, vcc
	v_lshl_add_u64 v[34:35], s[2:3], 0, v[34:35]
	v_lshlrev_b32_sdwa v160, v191, v40 dst_sel:DWORD dst_unused:UNUSED_PAD src0_sel:DWORD src1_sel:WORD_0
	v_add_co_u32_e32 v36, vcc, s63, v34
	v_lshl_add_u64 v[40:41], v[86:87], 0, v[160:161]
	s_waitcnt lgkmcnt(0)
	v_and_b32_e32 v42, 0xfff, v42
	v_addc_co_u32_e32 v37, vcc, 0, v35, vcc
	v_lshl_add_u64 v[40:41], s[2:3], 0, v[40:41]
	v_lshlrev_b32_sdwa v160, v191, v42 dst_sel:DWORD dst_unused:UNUSED_PAD src0_sel:DWORD src1_sel:WORD_0
	v_add_co_u32_e32 v40, vcc, s63, v40
	v_lshl_add_u64 v[42:43], v[86:87], 0, v[160:161]
	s_nop 0
	v_addc_co_u32_e32 v41, vcc, 0, v41, vcc
	v_lshl_add_u64 v[42:43], s[2:3], 0, v[42:43]
	v_add_co_u32_e32 v44, vcc, 0x25d00000, v42
	global_load_dwordx4 v[32:35], v[32:33], off
	global_load_dwordx4 v[36:39], v[36:37], off
	v_addc_co_u32_e32 v45, vcc, 0, v43, vcc
	global_load_dwordx4 v[40:43], v[40:41], off
	global_load_dwordx4 v[44:47], v[44:45], off
	v_cndmask_b32_e64 v91, 0, 1, s[14:15]
	v_mov_b32_e32 v90, 0xff800000
	v_cmp_ne_u32_e64 s[10:11], 1, v91
	s_andn2_b64 vcc, exec, s[14:15]
	v_mov_b32_e32 v106, 0xff800000
	v_mov_b32_e32 v107, 0xff800000
	v_mov_b32_e32 v104, 0xff800000
	v_mov_b32_e32 v105, 0xff800000
	v_mov_b32_e32 v102, 0xff800000
	v_mov_b32_e32 v103, 0xff800000
	v_mov_b32_e32 v98, 0xff800000
	v_mov_b32_e32 v99, 0xff800000
	s_cbranch_vccnz .LBB0_695
	ds_read2_b64 v[102:105], v143 offset1:4
	ds_read2_b64 v[110:113], v144 offset0:32 offset1:36
	ds_read2_b64 v[118:121], v143 offset0:8 offset1:12
	ds_read2_b64 v[150:153], v144 offset0:40 offset1:44
	s_waitcnt lgkmcnt(3)
	v_mfma_f32_16x16x32_fp8_fp8 v[106:109], v[102:103], v[100:101], 0
	s_waitcnt lgkmcnt(2)
	v_mfma_f32_16x16x32_fp8_fp8 v[114:117], v[110:111], v[100:101], 0
	s_waitcnt lgkmcnt(1)
	v_mfma_f32_16x16x32_fp8_fp8 v[146:149], v[118:119], v[96:97], 0
	s_waitcnt lgkmcnt(0)
	v_mfma_f32_16x16x32_fp8_fp8 v[154:157], v[150:151], v[96:97], 0
	v_mfma_f32_16x16x32_fp8_fp8 v[102:105], v[104:105], v[94:95], v[106:109]
	v_mfma_f32_16x16x32_fp8_fp8 v[108:111], v[112:113], v[94:95], v[114:117]
	v_mfma_f32_16x16x32_fp8_fp8 v[112:115], v[120:121], v[92:93], v[146:149]
	s_nop 7
	v_pk_add_f32 v[104:105], v[104:105], v[114:115]
	v_pk_add_f32 v[106:107], v[102:103], v[112:113]
	v_mfma_f32_16x16x32_fp8_fp8 v[112:115], v[152:153], v[92:93], v[154:157]
	s_nop 7
	v_pk_add_f32 v[98:99], v[110:111], v[114:115]
	v_pk_add_f32 v[102:103], v[108:109], v[112:113]
.LBB0_695:
	s_waitcnt vmcnt(11)
	ds_write_b128 v135, v[48:51] offset:4096
	s_waitcnt vmcnt(10)
	ds_write_b128 v135, v[56:59] offset:5248
	s_waitcnt vmcnt(9)
	ds_write_b128 v135, v[72:75] offset:6400
	s_waitcnt vmcnt(8)
	ds_write_b128 v135, v[76:79] offset:7552
	ds_read_u16 v48, v125 offset:384
	ds_read_u16 v50, v125 offset:400
	ds_read_u16 v72, v125 offset:416
	ds_read_u16 v74, v125 offset:432
	s_waitcnt lgkmcnt(3)
	v_and_b32_e32 v48, 0xfff, v48
	v_lshlrev_b32_sdwa v160, v191, v48 dst_sel:DWORD dst_unused:UNUSED_PAD src0_sel:DWORD src1_sel:WORD_0
	v_lshl_add_u64 v[48:49], v[86:87], 0, v[160:161]
	s_waitcnt lgkmcnt(2)
	v_and_b32_e32 v50, 0xfff, v50
	v_lshl_add_u64 v[48:49], s[2:3], 0, v[48:49]
	v_lshlrev_b32_sdwa v160, v191, v50 dst_sel:DWORD dst_unused:UNUSED_PAD src0_sel:DWORD src1_sel:WORD_0
	v_add_co_u32_e32 v48, vcc, s63, v48
	v_lshl_add_u64 v[50:51], v[86:87], 0, v[160:161]
	s_waitcnt lgkmcnt(1)
	v_and_b32_e32 v72, 0xfff, v72
	v_addc_co_u32_e32 v49, vcc, 0, v49, vcc
	v_lshl_add_u64 v[50:51], s[2:3], 0, v[50:51]
	v_lshlrev_b32_sdwa v160, v191, v72 dst_sel:DWORD dst_unused:UNUSED_PAD src0_sel:DWORD src1_sel:WORD_0
	v_add_co_u32_e32 v56, vcc, s63, v50
	v_lshl_add_u64 v[72:73], v[86:87], 0, v[160:161]
	s_waitcnt lgkmcnt(0)
	v_and_b32_e32 v74, 0xfff, v74
	v_addc_co_u32_e32 v57, vcc, 0, v51, vcc
	v_lshl_add_u64 v[72:73], s[2:3], 0, v[72:73]
	v_lshlrev_b32_sdwa v160, v191, v74 dst_sel:DWORD dst_unused:UNUSED_PAD src0_sel:DWORD src1_sel:WORD_0
	v_add_co_u32_e32 v72, vcc, s63, v72
	v_lshl_add_u64 v[74:75], v[86:87], 0, v[160:161]
	s_nop 0
	v_addc_co_u32_e32 v73, vcc, 0, v73, vcc
	v_lshl_add_u64 v[74:75], s[2:3], 0, v[74:75]
	v_add_co_u32_e32 v76, vcc, 0x25d00000, v74
	global_load_dwordx4 v[48:51], v[48:49], off
	global_load_dwordx4 v[56:59], v[56:57], off
	v_addc_co_u32_e32 v77, vcc, 0, v75, vcc
	global_load_dwordx4 v[72:75], v[72:73], off
	global_load_dwordx4 v[76:79], v[76:77], off
	s_and_b64 vcc, exec, s[10:11]
	v_mov_b32_e32 v91, 0xff800000
	v_mov_b32_e32 v114, 0xff800000
	v_mov_b32_e32 v115, 0xff800000
	v_mov_b32_e32 v110, 0xff800000
	v_mov_b32_e32 v111, 0xff800000
	v_mov_b32_e32 v108, 0xff800000
	v_mov_b32_e32 v109, 0xff800000
	s_cbranch_vccnz .LBB0_697
	ds_read2_b64 v[108:111], v143 offset1:4
	ds_read2_b64 v[146:149], v143 offset0:8 offset1:12
	ds_read2_b64 v[116:119], v144 offset0:32 offset1:36
	ds_read2_b64 v[154:157], v144 offset0:40 offset1:44
	s_waitcnt lgkmcnt(3)
	v_mfma_f32_16x16x32_fp8_fp8 v[112:115], v[108:109], v[100:101], 0
	s_waitcnt lgkmcnt(2)
	v_mfma_f32_16x16x32_fp8_fp8 v[150:153], v[146:147], v[96:97], 0
	s_waitcnt lgkmcnt(1)
	v_mfma_f32_16x16x32_fp8_fp8 v[120:123], v[116:117], v[100:101], 0
	s_waitcnt lgkmcnt(0)
	v_mfma_f32_16x16x32_fp8_fp8 v[166:169], v[154:155], v[96:97], 0
	v_mfma_f32_16x16x32_fp8_fp8 v[108:111], v[110:111], v[94:95], v[112:115]
	v_mfma_f32_16x16x32_fp8_fp8 v[112:115], v[148:149], v[92:93], v[150:153]
	v_mfma_f32_16x16x32_fp8_fp8 v[116:119], v[118:119], v[94:95], v[120:123]
	s_nop 6
	v_add_f32_e64 v114, v110, v114
	v_add_f32_e64 v115, v111, v115
	v_pk_add_f32 v[90:91], v[108:109], v[112:113]
	v_mfma_f32_16x16x32_fp8_fp8 v[110:113], v[156:157], v[92:93], v[166:169]
	s_nop 7
	v_pk_add_f32 v[108:109], v[118:119], v[112:113]
	v_pk_add_f32 v[110:111], v[116:117], v[110:111]
; #define QK_LOAD(set, st) do { _Pragma("unroll") for (int i = 0; i < 4; ++i) { const int row = widx[(st) * 32 + i * 8 + (lane >> 3)] & 4095; R[set][i] = *(const u32x4*)(kg + (size_t)row * 512); } __builtin_amdgcn_sched_barrier(0); } while (0)
; __device__ __forceinline__ void attn_phase(const int TID, const int BID, PP p, LAS unsigned char* lds) {
;     ...
;                 QK_LOAD(0, 0); QK_LOAD(1, 1); QK_LOAD(2, 2);
;                 QK_STEP(0, 0, true); QK_STEP(1, 1, true); QK_STEP(2, 2, true); QK_STEP(0, 3, true); QK_STEP(1, 4, true);
;                 QK_STEP(2, 5, false); QK_STEP(0, 6, false); QK_STEP(1, 7, false);
.LBB0_697:
	s_waitcnt vmcnt(11)
	ds_write_b128 v135, v[52:55] offset:4096
	s_waitcnt vmcnt(10)
	ds_write_b128 v135, v[60:63] offset:5248
	s_waitcnt vmcnt(9)
	ds_write_b128 v135, v[64:67] offset:6400
	s_waitcnt vmcnt(8)
	ds_write_b128 v135, v[68:71] offset:7552
	ds_read_u16 v52, v125 offset:448
	ds_read_u16 v54, v125 offset:464
	ds_read_u16 v64, v125 offset:480
	ds_read_u16 v66, v125 offset:496
	s_waitcnt lgkmcnt(3)
	v_and_b32_e32 v52, 0xfff, v52
	v_lshlrev_b32_sdwa v160, v191, v52 dst_sel:DWORD dst_unused:UNUSED_PAD src0_sel:DWORD src1_sel:WORD_0
	v_lshl_add_u64 v[52:53], v[86:87], 0, v[160:161]
	s_waitcnt lgkmcnt(2)
	v_and_b32_e32 v54, 0xfff, v54
	v_lshl_add_u64 v[52:53], s[2:3], 0, v[52:53]
	v_lshlrev_b32_sdwa v160, v191, v54 dst_sel:DWORD dst_unused:UNUSED_PAD src0_sel:DWORD src1_sel:WORD_0
	v_add_co_u32_e32 v52, vcc, s63, v52
	v_lshl_add_u64 v[54:55], v[86:87], 0, v[160:161]
	s_waitcnt lgkmcnt(1)
	v_and_b32_e32 v64, 0xfff, v64
	v_addc_co_u32_e32 v53, vcc, 0, v53, vcc
	v_lshl_add_u64 v[54:55], s[2:3], 0, v[54:55]
	v_lshlrev_b32_sdwa v160, v191, v64 dst_sel:DWORD dst_unused:UNUSED_PAD src0_sel:DWORD src1_sel:WORD_0
	v_add_co_u32_e32 v60, vcc, s63, v54
	v_lshl_add_u64 v[64:65], v[86:87], 0, v[160:161]
	s_waitcnt lgkmcnt(0)
	v_and_b32_e32 v66, 0xfff, v66
	v_addc_co_u32_e32 v61, vcc, 0, v55, vcc
	v_lshl_add_u64 v[64:65], s[2:3], 0, v[64:65]
	v_lshlrev_b32_sdwa v160, v191, v66 dst_sel:DWORD dst_unused:UNUSED_PAD src0_sel:DWORD src1_sel:WORD_0
	v_add_co_u32_e32 v64, vcc, s63, v64
	v_lshl_add_u64 v[66:67], v[86:87], 0, v[160:161]
	s_nop 0
	v_addc_co_u32_e32 v65, vcc, 0, v65, vcc
	v_lshl_add_u64 v[66:67], s[2:3], 0, v[66:67]
	v_add_co_u32_e32 v68, vcc, 0x25d00000, v66
	global_load_dwordx4 v[52:55], v[52:53], off
	global_load_dwordx4 v[60:63], v[60:61], off
	v_addc_co_u32_e32 v69, vcc, 0, v67, vcc
	global_load_dwordx4 v[64:67], v[64:65], off
	global_load_dwordx4 v[68:71], v[68:69], off
	v_mov_b32_e32 v112, 0xff800000
	s_andn2_b64 vcc, exec, s[16:17]
	v_mov_b32_e32 v122, 0xff800000
	v_mov_b32_e32 v123, 0xff800000
	v_mov_b32_e32 v120, 0xff800000
	v_mov_b32_e32 v121, 0xff800000
	v_mov_b32_e32 v118, 0xff800000
	v_mov_b32_e32 v119, 0xff800000
	v_mov_b32_e32 v116, 0xff800000
	v_mov_b32_e32 v117, 0xff800000
	s_cbranch_vccnz .LBB0_699
	ds_read2_b64 v[116:119], v143 offset1:4
	ds_read2_b64 v[146:149], v144 offset0:32 offset1:36
	ds_read2_b64 v[154:157], v143 offset0:8 offset1:12
	ds_read2_b64 v[170:173], v144 offset0:40 offset1:44
	s_waitcnt lgkmcnt(3)
	v_mfma_f32_16x16x32_fp8_fp8 v[120:123], v[116:117], v[100:101], 0
	s_waitcnt lgkmcnt(2)
	v_mfma_f32_16x16x32_fp8_fp8 v[150:153], v[146:147], v[100:101], 0
	s_waitcnt lgkmcnt(1)
	v_mfma_f32_16x16x32_fp8_fp8 v[166:169], v[154:155], v[96:97], 0
	s_waitcnt lgkmcnt(0)
	v_mfma_f32_16x16x32_fp8_fp8 v[174:177], v[170:171], v[96:97], 0
	v_mfma_f32_16x16x32_fp8_fp8 v[116:119], v[118:119], v[94:95], v[120:123]
	v_mfma_f32_16x16x32_fp8_fp8 v[146:149], v[148:149], v[94:95], v[150:153]
	v_mfma_f32_16x16x32_fp8_fp8 v[150:153], v[156:157], v[92:93], v[166:169]
	s_nop 7
	v_pk_add_f32 v[120:121], v[118:119], v[152:153]
	v_pk_add_f32 v[122:123], v[116:117], v[150:151]
	v_mfma_f32_16x16x32_fp8_fp8 v[150:153], v[172:173], v[92:93], v[174:177]
	s_nop 7
	v_pk_add_f32 v[116:117], v[148:149], v[152:153]
	v_pk_add_f32 v[118:119], v[146:147], v[150:151]

; __device__ __forceinline__ float max1(float a, float b) { return __builtin_amdgcn_fmed3f(a, b, 3.0e38f); }
; __device__ __forceinline__ void attn_phase(const int TID, const int BID, PP p, LAS unsigned char* lds) {
;     ...
;             float mx = -INFINITY;
; #pragma unroll
;             for (int kt = 0; kt < 16; ++kt)
; #pragma unroll
;                 for (int i = 0; i < 4; ++i) mx = max1(mx, sc[kt][i]);
;             mx = fmaxf(mx, __shfl_xor(mx, 16)); mx = fmaxf(mx, __shfl_xor(mx, 32));
;             const float sl2 = 0.08838834764831845f * 1.4426950408889634f;
;             float sum = 0.f; const float nmxs = -mx * sl2;
; #pragma unroll
;             for (int kt = 0; kt < 16; ++kt)
; #pragma unroll
;                 for (int i = 0; i < 4; ++i) { const float e = __builtin_amdgcn_exp2f(fmaf(sc[kt][i], sl2, nmxs)); sc[kt][i] = e; sum += e; }
;             sum += __shfl_xor(sum, 16); sum += __shfl_xor(sum, 32);
.LBB0_705:
	v_pk_add_f32 v[10:11], v[10:11], v[14:15]
	v_pk_add_f32 v[8:9], v[8:9], v[12:13]
	v_pk_add_f32 v[12:13], v[2:3], v[6:7]
	v_pk_add_f32 v[14:15], v[0:1], v[4:5]
	v_pk_add_f32 v[26:27], v[26:27], v[30:31]
	v_pk_add_f32 v[24:25], v[24:25], v[28:29]
	v_pk_add_f32 v[0:1], v[18:19], v[22:23]
	v_pk_add_f32 v[16:17], v[16:17], v[20:21]
	v_min_f32_e32 v2, 0x7f61b1e6, v8
	v_med3_f32 v2, v2, v9, s33
	v_med3_f32 v2, v2, v10, s33
	v_med3_f32 v2, v2, v11, s33
	v_med3_f32 v2, v2, v14, s33
	v_med3_f32 v2, v2, v15, s33
	v_med3_f32 v2, v2, v12, s33
	v_med3_f32 v2, v2, v13, s33
	v_med3_f32 v2, v2, v24, s33
	v_med3_f32 v2, v2, v25, s33
	v_med3_f32 v2, v2, v26, s33
	v_med3_f32 v2, v2, v27, s33
	v_med3_f32 v2, v2, v16, s33
	v_med3_f32 v2, v2, v17, s33
	v_med3_f32 v2, v2, v0, s33
	v_med3_f32 v2, v2, v1, s33
	v_med3_f32 v2, v2, v106, s33
	v_med3_f32 v2, v2, v107, s33
	v_med3_f32 v2, v2, v104, s33
	v_med3_f32 v2, v2, v105, s33
	v_med3_f32 v2, v2, v102, s33
	v_med3_f32 v2, v2, v103, s33
	v_med3_f32 v2, v2, v98, s33
	v_med3_f32 v2, v2, v99, s33
	v_med3_f32 v2, v2, v90, s33
	v_med3_f32 v2, v2, v91, s33
	v_med3_f32 v2, v2, v114, s33
	v_med3_f32 v2, v2, v115, s33
	v_med3_f32 v2, v2, v110, s33
	v_med3_f32 v2, v2, v111, s33
	v_med3_f32 v2, v2, v108, s33
	v_med3_f32 v2, v2, v109, s33
	v_med3_f32 v2, v2, v122, s33
	v_med3_f32 v2, v2, v123, s33
	v_med3_f32 v2, v2, v120, s33
	v_med3_f32 v2, v2, v121, s33
	v_med3_f32 v2, v2, v118, s33
	v_med3_f32 v2, v2, v119, s33
	v_med3_f32 v2, v2, v116, s33
	v_med3_f32 v2, v2, v117, s33
	v_med3_f32 v2, v2, v112, s33
	v_med3_f32 v2, v2, v113, s33
	v_med3_f32 v2, v2, v46, s33
	v_med3_f32 v2, v2, v47, s33
	v_med3_f32 v2, v2, v40, s33
	v_med3_f32 v2, v2, v41, s33
	v_med3_f32 v2, v2, v34, s33
	v_med3_f32 v2, v2, v35, s33
	v_med3_f32 v2, v2, v56, s33
	v_med3_f32 v2, v2, v57, s33
	v_med3_f32 v2, v2, v48, s33
	v_med3_f32 v2, v2, v49, s33
	v_med3_f32 v2, v2, v42, s33
	v_med3_f32 v2, v2, v43, s33
	v_med3_f32 v2, v2, v36, s33
	v_med3_f32 v2, v2, v37, s33
	v_med3_f32 v2, v2, v32, s33
	v_med3_f32 v2, v2, v33, s33
	v_med3_f32 v2, v2, v50, s33
	v_med3_f32 v2, v2, v51, s33
	v_med3_f32 v2, v2, v44, s33
	v_med3_f32 v2, v2, v45, s33
	v_med3_f32 v2, v2, v38, s33
	v_med3_f32 v2, v2, v39, s33
	ds_bpermute_b32 v3, v137, v2
	v_mov_b32_e32 v29, v161
	s_waitcnt lgkmcnt(0)
	v_max_f32_e32 v3, v3, v3
	v_max_f32_e32 v2, v2, v3
	ds_bpermute_b32 v3, v138, v2
	s_waitcnt lgkmcnt(0)
	v_max_f32_e32 v3, v3, v3
	v_max_f32_e32 v2, v2, v3
	v_mul_f32_e32 v6, 0xbe0293ee, v2
	v_fmamk_f32 v2, v8, 0x3e0293ee, v6
	v_exp_f32_e32 v2, v2
	v_fmamk_f32 v3, v9, 0x3e0293ee, v6
	v_exp_f32_e32 v3, v3
	v_fmamk_f32 v16, v16, 0x3e0293ee, v6
	v_add_f32_e32 v4, 0, v2
	v_exp_f32_e32 v16, v16
	v_add_f32_e32 v5, v3, v4
	v_fmamk_f32 v4, v10, 0x3e0293ee, v6
	v_exp_f32_e32 v4, v4
	v_fmamk_f32 v17, v17, 0x3e0293ee, v6
	v_exp_f32_e32 v17, v17
	v_fmamk_f32 v0, v0, 0x3e0293ee, v6
	v_add_f32_e32 v7, v4, v5
	v_fmamk_f32 v5, v11, 0x3e0293ee, v6
	v_exp_f32_e32 v5, v5
	v_exp_f32_e32 v0, v0
	v_fmamk_f32 v1, v1, 0x3e0293ee, v6
	v_exp_f32_e32 v1, v1
	v_add_f32_e32 v8, v5, v7
	v_fmamk_f32 v7, v14, 0x3e0293ee, v6
	v_exp_f32_e32 v7, v7
	v_fmamk_f32 v18, v106, 0x3e0293ee, v6
	v_exp_f32_e32 v18, v18
	v_fmamk_f32 v19, v107, 0x3e0293ee, v6
	v_add_f32_e32 v9, v7, v8
	v_fmamk_f32 v8, v15, 0x3e0293ee, v6
	v_exp_f32_e32 v8, v8
	v_exp_f32_e32 v19, v19
	v_fmamk_f32 v20, v104, 0x3e0293ee, v6
	v_exp_f32_e32 v20, v20
	v_add_f32_e32 v10, v8, v9
	v_fmamk_f32 v9, v12, 0x3e0293ee, v6
	v_exp_f32_e32 v9, v9
	v_fmamk_f32 v21, v105, 0x3e0293ee, v6
	v_exp_f32_e32 v21, v21
	v_fmamk_f32 v22, v102, 0x3e0293ee, v6
	v_add_f32_e32 v11, v9, v10
	v_fmamk_f32 v10, v13, 0x3e0293ee, v6
	v_exp_f32_e32 v10, v10
	v_exp_f32_e32 v22, v22
	v_fmamk_f32 v23, v103, 0x3e0293ee, v6
	v_exp_f32_e32 v23, v23
	v_add_f32_e32 v12, v10, v11
	v_fmamk_f32 v11, v24, 0x3e0293ee, v6
	v_exp_f32_e32 v11, v11
	v_fmamk_f32 v24, v98, 0x3e0293ee, v6
	v_exp_f32_e32 v30, v24
	v_fmamk_f32 v24, v99, 0x3e0293ee, v6
	v_add_f32_e32 v13, v11, v12
	v_fmamk_f32 v12, v25, 0x3e0293ee, v6
	v_exp_f32_e32 v12, v12
	v_exp_f32_e32 v31, v24
	v_fmamk_f32 v24, v90, 0x3e0293ee, v6
	v_exp_f32_e32 v52, v24
	v_add_f32_e32 v14, v12, v13
	v_fmamk_f32 v13, v26, 0x3e0293ee, v6
	v_exp_f32_e32 v13, v13
	v_fmamk_f32 v24, v91, 0x3e0293ee, v6
	v_exp_f32_e32 v53, v24
	v_fmamk_f32 v24, v114, 0x3e0293ee, v6
	v_add_f32_e32 v15, v13, v14
	v_fmamk_f32 v14, v27, 0x3e0293ee, v6
	v_exp_f32_e32 v14, v14
	v_exp_f32_e32 v54, v24
	v_fmamk_f32 v24, v115, 0x3e0293ee, v6
	v_exp_f32_e32 v55, v24
	v_add_f32_e32 v15, v14, v15
	v_add_f32_e32 v15, v16, v15
	v_add_f32_e32 v15, v17, v15
	v_add_f32_e32 v15, v0, v15
	v_add_f32_e32 v15, v1, v15
	v_add_f32_e32 v15, v18, v15
	v_add_f32_e32 v15, v19, v15
	v_add_f32_e32 v15, v20, v15
	v_add_f32_e32 v15, v21, v15
	v_add_f32_e32 v15, v22, v15
	v_add_f32_e32 v15, v23, v15
	v_add_f32_e32 v15, v30, v15
	v_add_f32_e32 v15, v31, v15
	v_fmamk_f32 v24, v110, 0x3e0293ee, v6
	v_add_f32_e32 v15, v52, v15
	v_exp_f32_e32 v58, v24
	v_fmamk_f32 v24, v111, 0x3e0293ee, v6
	v_add_f32_e32 v15, v53, v15
	v_exp_f32_e32 v59, v24
	v_fmamk_f32 v24, v108, 0x3e0293ee, v6
	v_add_f32_e32 v15, v54, v15
	v_exp_f32_e32 v60, v24
	v_fmamk_f32 v24, v109, 0x3e0293ee, v6
	v_add_f32_e32 v15, v55, v15
	v_exp_f32_e32 v61, v24
	v_fmamk_f32 v24, v122, 0x3e0293ee, v6
	v_add_f32_e32 v15, v58, v15
	v_exp_f32_e32 v62, v24
	v_fmamk_f32 v24, v123, 0x3e0293ee, v6
	v_add_f32_e32 v15, v59, v15
	v_exp_f32_e32 v63, v24
	v_fmamk_f32 v24, v120, 0x3e0293ee, v6
	v_add_f32_e32 v15, v60, v15
	v_exp_f32_e32 v64, v24
	v_fmamk_f32 v24, v121, 0x3e0293ee, v6
	v_add_f32_e32 v15, v61, v15
	v_exp_f32_e32 v65, v24
	v_fmamk_f32 v24, v118, 0x3e0293ee, v6
; #define LAS __attribute__((address_space(3)))
; __device__ __forceinline__ void attn_phase(const int TID, const int BID, PP p, LAS unsigned char* lds) {
;     ...
;             float sum = 0.f; const float nmxs = -mx * sl2;
; #pragma unroll
;             for (int kt = 0; kt < 16; ++kt)
; #pragma unroll
;                 for (int i = 0; i < 4; ++i) { const float e = __builtin_amdgcn_exp2f(fmaf(sc[kt][i], sl2, nmxs)); sc[kt][i] = e; sum += e; }
;             sum += __shfl_xor(sum, 16); sum += __shfl_xor(sum, 32);
;             const float inv = 1.0f / sum;
;             float invh[4];
; #pragma unroll
;             for (int i = 0; i < 4; ++i) invh[i] = __shfl(inv, i);
;             long Af[8];
; #pragma unroll
;             for (int s2 = 0; s2 < 8; ++s2) {
;                 int lo = __builtin_amdgcn_cvt_pk_fp8_f32(sc[2 * s2][0], sc[2 * s2][1], 0, false); lo = __builtin_amdgcn_cvt_pk_fp8_f32(sc[2 * s2][2], sc[2 * s2][3], lo, true);
;                 int hi = __builtin_amdgcn_cvt_pk_fp8_f32(sc[2 * s2 + 1][0], sc[2 * s2 + 1][1], 0, false); hi = __builtin_amdgcn_cvt_pk_fp8_f32(sc[2 * s2 + 1][2], sc[2 * s2 + 1][3], hi, true);
;                 Af[s2] = (long)(((unsigned long long)(unsigned)hi << 32) | (unsigned)lo);
;             }
;             f32x4 acc[8];
; #pragma unroll
;             for (int nt = 0; nt < 8; ++nt) acc[nt] = (f32x4){0.f, 0.f, 0.f, 0.f};
;             u32x4 R[3][4];
;             const unsigned char* vg = (const unsigned char*)Vb + (size_t)(b * SEQ) * 512 + g * 128 + (lane & 7) * 16;
;             LAS unsigned char* vtw = vt + (lane >> 3) * 144 + (lane & 7) * 16;
;             const int rho0 = lane >> 3;
;             const int slot0 = 16 * (rho0 >> 2) + (rho0 & 3);
;             const unsigned trb = (unsigned)(size_t)(vt + (fq * 8 + (fr >> 1)) * 144 + (fr & 1) * 8);
	v_add_f32_e32 v15, v62, v15
	v_exp_f32_e32 v66, v24
	v_fmamk_f32 v24, v119, 0x3e0293ee, v6
	v_add_f32_e32 v15, v63, v15
	v_exp_f32_e32 v67, v24
	v_fmamk_f32 v24, v116, 0x3e0293ee, v6
	v_add_f32_e32 v15, v64, v15
	v_exp_f32_e32 v68, v24
	v_fmamk_f32 v24, v117, 0x3e0293ee, v6
	v_add_f32_e32 v15, v65, v15
	v_exp_f32_e32 v69, v24
	v_fmamk_f32 v24, v112, 0x3e0293ee, v6
	v_add_f32_e32 v15, v66, v15
	v_exp_f32_e32 v70, v24
	v_fmamk_f32 v24, v113, 0x3e0293ee, v6
	v_add_f32_e32 v15, v67, v15
	v_exp_f32_e32 v71, v24
	v_fmamk_f32 v24, v46, 0x3e0293ee, v6
	v_add_f32_e32 v15, v68, v15
	v_exp_f32_e32 v46, v24
	v_fmamk_f32 v24, v47, 0x3e0293ee, v6
	v_add_f32_e32 v15, v69, v15
	v_exp_f32_e32 v47, v24
	v_fmamk_f32 v24, v40, 0x3e0293ee, v6
	v_add_f32_e32 v15, v70, v15
	v_exp_f32_e32 v40, v24
	v_fmamk_f32 v24, v41, 0x3e0293ee, v6
	v_add_f32_e32 v15, v71, v15
	v_exp_f32_e32 v41, v24
	v_fmamk_f32 v24, v34, 0x3e0293ee, v6
	v_add_f32_e32 v15, v46, v15
	v_exp_f32_e32 v72, v24
	v_fmamk_f32 v24, v35, 0x3e0293ee, v6
	v_add_f32_e32 v15, v47, v15
	v_exp_f32_e32 v73, v24
	v_fmamk_f32 v24, v56, 0x3e0293ee, v6
	v_add_f32_e32 v15, v40, v15
	v_exp_f32_e32 v56, v24
	v_fmamk_f32 v24, v57, 0x3e0293ee, v6
	v_add_f32_e32 v15, v41, v15
	v_exp_f32_e32 v57, v24
	v_fmamk_f32 v24, v48, 0x3e0293ee, v6
	v_add_f32_e32 v15, v72, v15
	v_exp_f32_e32 v48, v24
	v_fmamk_f32 v24, v49, 0x3e0293ee, v6
	v_add_f32_e32 v15, v73, v15
	v_exp_f32_e32 v49, v24
	v_fmamk_f32 v24, v42, 0x3e0293ee, v6
	v_add_f32_e32 v15, v56, v15
	v_exp_f32_e32 v42, v24
	v_fmamk_f32 v24, v43, 0x3e0293ee, v6
	v_add_f32_e32 v15, v57, v15
	v_exp_f32_e32 v43, v24
	v_fmamk_f32 v24, v36, 0x3e0293ee, v6
	v_add_f32_e32 v15, v48, v15
	v_exp_f32_e32 v74, v24
	v_fmamk_f32 v24, v37, 0x3e0293ee, v6
	v_add_f32_e32 v15, v49, v15
	v_exp_f32_e32 v75, v24
	v_fmamk_f32 v24, v32, 0x3e0293ee, v6
	v_add_f32_e32 v15, v42, v15
	v_exp_f32_e32 v76, v24
	v_fmamk_f32 v24, v33, 0x3e0293ee, v6
	v_add_f32_e32 v15, v43, v15
	v_exp_f32_e32 v33, v24
	v_fmamk_f32 v24, v50, 0x3e0293ee, v6
	v_add_f32_e32 v15, v74, v15
	v_exp_f32_e32 v50, v24
	v_fmamk_f32 v24, v51, 0x3e0293ee, v6
	v_add_f32_e32 v15, v75, v15
	v_exp_f32_e32 v51, v24
	v_fmamk_f32 v24, v44, 0x3e0293ee, v6
	v_add_f32_e32 v15, v76, v15
	v_exp_f32_e32 v44, v24
	v_fmamk_f32 v24, v45, 0x3e0293ee, v6
	v_add_f32_e32 v15, v33, v15
	v_exp_f32_e32 v45, v24
	v_fmamk_f32 v24, v38, 0x3e0293ee, v6
	v_add_f32_e32 v15, v50, v15
	v_exp_f32_e32 v38, v24
	v_fmac_f32_e32 v6, 0x3e0293ee, v39
	v_add_f32_e32 v15, v51, v15
	v_exp_f32_e32 v6, v6
	v_add_f32_e32 v15, v44, v15
	v_add_f32_e32 v15, v45, v15
	v_add_f32_e32 v15, v38, v15
	v_add_f32_e32 v15, v6, v15
	ds_bpermute_b32 v24, v137, v15
	v_cvt_pk_fp8_f32 v29, v7, v8
	v_mov_b32_e32 v32, v161
	v_cvt_pk_fp8_f32 v32, v76, v33
	v_mov_b32_e32 v33, v161
	s_waitcnt lgkmcnt(0)
	v_add_f32_e32 v15, v15, v24
	ds_bpermute_b32 v24, v138, v15
	v_cvt_pk_fp8_f32 v29, v9, v10 op_sel:[0,0,1]
	v_cvt_pk_fp8_f32 v33, v44, v45
	v_cvt_pk_fp8_f32 v32, v50, v51 op_sel:[0,0,1]
	s_waitcnt lgkmcnt(0)
	v_add_f32_e32 v15, v15, v24
	v_div_scale_f32 v24, s[0:1], v15, v15, 1.0
	v_rcp_f32_e32 v25, v24
	v_cvt_pk_fp8_f32 v33, v38, v6 op_sel:[0,0,1]
	v_fma_f32 v26, -v24, v25, 1.0
	v_fmac_f32_e32 v25, v26, v25
	v_div_scale_f32 v26, vcc, 1.0, v15, 1.0
	v_mul_f32_e32 v27, v26, v25
	v_fma_f32 v28, -v24, v27, v26
	v_fmac_f32_e32 v27, v28, v25
	v_fma_f32 v24, -v24, v27, v26
	v_div_fmas_f32 v24, v24, v25, v27
	v_mov_b32_e32 v28, v161
	v_mov_b32_e32 v27, v161
	v_cvt_pk_fp8_f32 v28, v2, v3
	v_cvt_pk_fp8_f32 v27, v16, v17
	v_mov_b32_e32 v26, v161
	v_cvt_pk_fp8_f32 v26, v11, v12
	v_cvt_pk_fp8_f32 v28, v4, v5 op_sel:[0,0,1]
	v_cvt_pk_fp8_f32 v27, v0, v1 op_sel:[0,0,1]
	ds_read_u16 v0, v127
	ds_read_u16 v4, v127 offset:8
	ds_read_u16 v8, v127 offset:16
	ds_read_u16 v12, v127 offset:24
	v_cvt_pk_fp8_f32 v26, v13, v14 op_sel:[0,0,1]
	s_waitcnt lgkmcnt(3)
	v_and_b32_e32 v0, 0xfff, v0
	v_lshlrev_b32_sdwa v160, v191, v0 dst_sel:DWORD dst_unused:UNUSED_PAD src0_sel:DWORD src1_sel:WORD_0
	v_lshl_add_u64 v[0:1], v[86:87], 0, v[160:161]
	s_waitcnt lgkmcnt(2)
	v_and_b32_e32 v4, 0xfff, v4
	v_lshl_add_u64 v[0:1], s[2:3], 0, v[0:1]
	v_lshlrev_b32_sdwa v160, v191, v4 dst_sel:DWORD dst_unused:UNUSED_PAD src0_sel:DWORD src1_sel:WORD_0
	v_add_co_u32_e32 v0, vcc, s4, v0
	v_lshl_add_u64 v[4:5], v[86:87], 0, v[160:161]
	s_waitcnt lgkmcnt(1)
	v_and_b32_e32 v8, 0xfff, v8
	v_addc_co_u32_e32 v1, vcc, 0, v1, vcc
	v_lshl_add_u64 v[4:5], s[2:3], 0, v[4:5]
	v_lshlrev_b32_sdwa v160, v191, v8 dst_sel:DWORD dst_unused:UNUSED_PAD src0_sel:DWORD src1_sel:WORD_0
	v_add_co_u32_e32 v4, vcc, s4, v4
	v_lshl_add_u64 v[8:9], v[86:87], 0, v[160:161]
	s_waitcnt lgkmcnt(0)
; #define LAS __attribute__((address_space(3)))
; #define PV_LOAD(set, st) do { _Pragma("unroll") for (int i = 0; i < 4; ++i) { const int row = widx[(st) * 32 + slot0 + 4 * i] & 4095; R[set][i] = *(const u32x4*)(vg + (size_t)row * 512); } __builtin_amdgcn_sched_barrier(0); } while (0)
; __device__ __forceinline__ void attn_phase(const int TID, const int BID, PP p, LAS unsigned char* lds) {
;     ...
;             const float inv = 1.0f / sum;
;             float invh[4];
; #pragma unroll
;             for (int i = 0; i < 4; ++i) invh[i] = __shfl(inv, i);
;             long Af[8];
; #pragma unroll
;             for (int s2 = 0; s2 < 8; ++s2) {
;                 int lo = __builtin_amdgcn_cvt_pk_fp8_f32(sc[2 * s2][0], sc[2 * s2][1], 0, false); lo = __builtin_amdgcn_cvt_pk_fp8_f32(sc[2 * s2][2], sc[2 * s2][3], lo, true);
;                 int hi = __builtin_amdgcn_cvt_pk_fp8_f32(sc[2 * s2 + 1][0], sc[2 * s2 + 1][1], 0, false); hi = __builtin_amdgcn_cvt_pk_fp8_f32(sc[2 * s2 + 1][2], sc[2 * s2 + 1][3], hi, true);
;                 Af[s2] = (long)(((unsigned long long)(unsigned)hi << 32) | (unsigned)lo);
;             }
;             f32x4 acc[8];
; #pragma unroll
;             for (int nt = 0; nt < 8; ++nt) acc[nt] = (f32x4){0.f, 0.f, 0.f, 0.f};
;             u32x4 R[3][4];
;             const unsigned char* vg = (const unsigned char*)Vb + (size_t)(b * SEQ) * 512 + g * 128 + (lane & 7) * 16;
;             LAS unsigned char* vtw = vt + (lane >> 3) * 144 + (lane & 7) * 16;
;             const int rho0 = lane >> 3;
;             const int slot0 = 16 * (rho0 >> 2) + (rho0 & 3);
;             const unsigned trb = (unsigned)(size_t)(vt + (fq * 8 + (fr >> 1)) * 144 + (fr & 1) * 8);
;     ...
;             PV_LOAD(0, 0); PV_LOAD(1, 1); PV_LOAD(2, 2);
;             PV_STEP(0, 0, true); PV_STEP(1, 1, true); PV_STEP(2, 2, true); PV_STEP(0, 3, true); PV_STEP(1, 4, true);
	v_and_b32_e32 v12, 0xfff, v12
	v_addc_co_u32_e32 v5, vcc, 0, v5, vcc
	v_lshl_add_u64 v[8:9], s[2:3], 0, v[8:9]
	v_lshlrev_b32_sdwa v160, v191, v12 dst_sel:DWORD dst_unused:UNUSED_PAD src0_sel:DWORD src1_sel:WORD_0
	v_add_co_u32_e32 v8, vcc, s4, v8
	v_lshl_add_u64 v[12:13], v[86:87], 0, v[160:161]
	s_nop 0
	v_addc_co_u32_e32 v9, vcc, 0, v9, vcc
	v_lshl_add_u64 v[12:13], s[2:3], 0, v[12:13]
	v_add_co_u32_e32 v12, vcc, s4, v12
	v_div_fixup_f32 v15, v24, v15, 1.0
	s_nop 0
	v_addc_co_u32_e32 v13, vcc, 0, v13, vcc
	ds_bpermute_b32 v37, v139, v15
	ds_bpermute_b32 v36, v140, v15
	ds_bpermute_b32 v35, v141, v15
	ds_bpermute_b32 v34, v142, v15
	global_load_dwordx4 v[0:3], v[0:1], off
	v_mov_b32_e32 v24, v161
	global_load_dwordx4 v[4:7], v[4:5], off
	v_cvt_pk_fp8_f32 v24, v18, v19
	global_load_dwordx4 v[8:11], v[8:9], off
	v_mov_b32_e32 v25, v161
	global_load_dwordx4 v[12:15], v[12:13], off
	v_cvt_pk_fp8_f32 v24, v20, v21 op_sel:[0,0,1]
	v_cvt_pk_fp8_f32 v25, v22, v23
	v_mov_b32_e32 v22, v161
	v_mov_b32_e32 v23, v161
	v_mov_b32_e32 v20, v161
	v_mov_b32_e32 v21, v161
	v_mov_b32_e32 v18, v161
	v_mov_b32_e32 v19, v161
	v_mov_b32_e32 v16, v161
	v_mov_b32_e32 v17, v161
	v_cvt_pk_fp8_f32 v22, v52, v53
	v_cvt_pk_fp8_f32 v23, v58, v59
	v_cvt_pk_fp8_f32 v20, v62, v63
	v_cvt_pk_fp8_f32 v21, v66, v67
	v_cvt_pk_fp8_f32 v18, v70, v71
	v_cvt_pk_fp8_f32 v19, v40, v41
	v_cvt_pk_fp8_f32 v16, v56, v57
	v_cvt_pk_fp8_f32 v17, v42, v43
	v_cvt_pk_fp8_f32 v25, v30, v31 op_sel:[0,0,1]
	v_cvt_pk_fp8_f32 v22, v54, v55 op_sel:[0,0,1]
	v_cvt_pk_fp8_f32 v23, v60, v61 op_sel:[0,0,1]
	v_cvt_pk_fp8_f32 v20, v64, v65 op_sel:[0,0,1]
	v_cvt_pk_fp8_f32 v21, v68, v69 op_sel:[0,0,1]
	v_cvt_pk_fp8_f32 v18, v46, v47 op_sel:[0,0,1]
	v_cvt_pk_fp8_f32 v19, v72, v73 op_sel:[0,0,1]
	v_cvt_pk_fp8_f32 v16, v48, v49 op_sel:[0,0,1]
	v_cvt_pk_fp8_f32 v17, v74, v75 op_sel:[0,0,1]
	ds_read_u16 v30, v127 offset:64
	ds_read_u16 v38, v127 offset:72
	ds_read_u16 v46, v127 offset:80
	ds_read_u16 v47, v127 offset:88
	s_waitcnt lgkmcnt(3)
	v_and_b32_e32 v30, 0xfff, v30
	v_lshlrev_b32_sdwa v160, v191, v30 dst_sel:DWORD dst_unused:UNUSED_PAD src0_sel:DWORD src1_sel:WORD_0
	v_lshl_add_u64 v[30:31], v[86:87], 0, v[160:161]
	s_waitcnt lgkmcnt(2)
	v_and_b32_e32 v38, 0xfff, v38
	v_lshl_add_u64 v[30:31], s[2:3], 0, v[30:31]
	v_lshlrev_b32_sdwa v160, v191, v38 dst_sel:DWORD dst_unused:UNUSED_PAD src0_sel:DWORD src1_sel:WORD_0
	v_add_co_u32_e32 v30, vcc, s4, v30
	v_lshl_add_u64 v[38:39], v[86:87], 0, v[160:161]
	s_nop 0
	v_addc_co_u32_e32 v31, vcc, 0, v31, vcc
	v_lshl_add_u64 v[38:39], s[2:3], 0, v[38:39]
	v_add_co_u32_e32 v42, vcc, s4, v38
	s_nop 1
	v_addc_co_u32_e32 v43, vcc, 0, v39, vcc
	global_load_dwordx4 v[38:41], v[30:31], off
	global_load_dwordx4 v[42:45], v[42:43], off
	s_waitcnt lgkmcnt(1)
	v_and_b32_e32 v30, 0xfff, v46
	v_lshlrev_b32_sdwa v160, v191, v30 dst_sel:DWORD dst_unused:UNUSED_PAD src0_sel:DWORD src1_sel:WORD_0
	v_lshl_add_u64 v[30:31], v[86:87], 0, v[160:161]
	s_waitcnt lgkmcnt(0)
	v_and_b32_e32 v46, 0xfff, v47
	v_lshl_add_u64 v[30:31], s[2:3], 0, v[30:31]
	v_lshlrev_b32_sdwa v160, v191, v46 dst_sel:DWORD dst_unused:UNUSED_PAD src0_sel:DWORD src1_sel:WORD_0
	v_add_co_u32_e32 v30, vcc, s4, v30
	v_lshl_add_u64 v[46:47], v[86:87], 0, v[160:161]
	s_nop 0
	v_addc_co_u32_e32 v31, vcc, 0, v31, vcc
	v_lshl_add_u64 v[46:47], s[2:3], 0, v[46:47]
	v_add_co_u32_e32 v50, vcc, s4, v46
	s_nop 1
	v_addc_co_u32_e32 v51, vcc, 0, v47, vcc
	global_load_dwordx4 v[46:49], v[30:31], off
	global_load_dwordx4 v[50:53], v[50:51], off
	ds_read_u16 v30, v127 offset:128
	ds_read_u16 v54, v127 offset:136
	ds_read_u16 v62, v127 offset:144
	ds_read_u16 v63, v127 offset:152
	s_waitcnt lgkmcnt(3)
	v_and_b32_e32 v30, 0xfff, v30
	v_lshlrev_b32_sdwa v160, v191, v30 dst_sel:DWORD dst_unused:UNUSED_PAD src0_sel:DWORD src1_sel:WORD_0
	v_lshl_add_u64 v[30:31], v[86:87], 0, v[160:161]
	s_waitcnt lgkmcnt(2)
	v_and_b32_e32 v54, 0xfff, v54
	v_lshl_add_u64 v[30:31], s[2:3], 0, v[30:31]
	v_lshlrev_b32_sdwa v160, v191, v54 dst_sel:DWORD dst_unused:UNUSED_PAD src0_sel:DWORD src1_sel:WORD_0
	v_add_co_u32_e32 v30, vcc, s4, v30
	v_lshl_add_u64 v[54:55], v[86:87], 0, v[160:161]
	s_nop 0
	v_addc_co_u32_e32 v31, vcc, 0, v31, vcc
	v_lshl_add_u64 v[54:55], s[2:3], 0, v[54:55]
	v_add_co_u32_e32 v58, vcc, s4, v54
	s_nop 1
	v_addc_co_u32_e32 v59, vcc, 0, v55, vcc
	global_load_dwordx4 v[54:57], v[30:31], off
	global_load_dwordx4 v[58:61], v[58:59], off
	s_waitcnt lgkmcnt(1)
	v_and_b32_e32 v30, 0xfff, v62
	v_lshlrev_b32_sdwa v160, v191, v30 dst_sel:DWORD dst_unused:UNUSED_PAD src0_sel:DWORD src1_sel:WORD_0
	v_lshl_add_u64 v[30:31], v[86:87], 0, v[160:161]
	s_waitcnt lgkmcnt(0)
	v_and_b32_e32 v62, 0xfff, v63
	v_lshl_add_u64 v[30:31], s[2:3], 0, v[30:31]
	v_lshlrev_b32_sdwa v160, v191, v62 dst_sel:DWORD dst_unused:UNUSED_PAD src0_sel:DWORD src1_sel:WORD_0
	v_add_co_u32_e32 v30, vcc, s4, v30
	v_lshl_add_u64 v[62:63], v[86:87], 0, v[160:161]
	s_nop 0
	v_addc_co_u32_e32 v31, vcc, 0, v31, vcc
	v_lshl_add_u64 v[62:63], s[2:3], 0, v[62:63]
	v_add_co_u32_e32 v66, vcc, s4, v62
	s_nop 1
	v_addc_co_u32_e32 v67, vcc, 0, v63, vcc
	global_load_dwordx4 v[62:65], v[30:31], off
	global_load_dwordx4 v[66:69], v[66:67], off
	s_waitcnt vmcnt(11)
	ds_write_b128 v135, v[0:3] offset:4096
	s_waitcnt vmcnt(10)
	ds_write_b128 v135, v[4:7] offset:5248
	s_waitcnt vmcnt(9)
	ds_write_b128 v135, v[8:11] offset:6400
	s_waitcnt vmcnt(8)
	ds_write_b128 v135, v[12:15] offset:7552
	ds_read_u16 v0, v127 offset:192
	ds_read_u16 v2, v127 offset:200
	ds_read_u16 v8, v127 offset:208
	ds_read_u16 v10, v127 offset:216
	s_waitcnt lgkmcnt(3)
; #define PV_LOAD(set, st) do { _Pragma("unroll") for (int i = 0; i < 4; ++i) { const int row = widx[(st) * 32 + slot0 + 4 * i] & 4095; R[set][i] = *(const u32x4*)(vg + (size_t)row * 512); } __builtin_amdgcn_sched_barrier(0); } while (0)
; __device__ __forceinline__ void attn_phase(const int TID, const int BID, PP p, LAS unsigned char* lds) {
;     ...
;             PV_LOAD(0, 0); PV_LOAD(1, 1); PV_LOAD(2, 2);
;             PV_STEP(0, 0, true); PV_STEP(1, 1, true); PV_STEP(2, 2, true); PV_STEP(0, 3, true); PV_STEP(1, 4, true);
;             PV_STEP(2, 5, false); PV_STEP(0, 6, false); PV_STEP(1, 7, false);
	v_and_b32_e32 v0, 0xfff, v0
	v_lshlrev_b32_sdwa v160, v191, v0 dst_sel:DWORD dst_unused:UNUSED_PAD src0_sel:DWORD src1_sel:WORD_0
	v_lshl_add_u64 v[0:1], v[86:87], 0, v[160:161]
	s_waitcnt lgkmcnt(2)
	v_and_b32_e32 v2, 0xfff, v2
	v_lshl_add_u64 v[0:1], s[2:3], 0, v[0:1]
	v_lshlrev_b32_sdwa v160, v191, v2 dst_sel:DWORD dst_unused:UNUSED_PAD src0_sel:DWORD src1_sel:WORD_0
	v_add_co_u32_e32 v0, vcc, s4, v0
	v_lshl_add_u64 v[2:3], v[86:87], 0, v[160:161]
	s_waitcnt lgkmcnt(1)
	v_and_b32_e32 v8, 0xfff, v8
	v_addc_co_u32_e32 v1, vcc, 0, v1, vcc
	v_lshl_add_u64 v[2:3], s[2:3], 0, v[2:3]
	v_lshlrev_b32_sdwa v160, v191, v8 dst_sel:DWORD dst_unused:UNUSED_PAD src0_sel:DWORD src1_sel:WORD_0
	v_add_co_u32_e32 v4, vcc, s4, v2
	v_lshl_add_u64 v[8:9], v[86:87], 0, v[160:161]
	s_waitcnt lgkmcnt(0)
	v_and_b32_e32 v10, 0xfff, v10
	v_addc_co_u32_e32 v5, vcc, 0, v3, vcc
	v_lshl_add_u64 v[8:9], s[2:3], 0, v[8:9]
	v_lshlrev_b32_sdwa v160, v191, v10 dst_sel:DWORD dst_unused:UNUSED_PAD src0_sel:DWORD src1_sel:WORD_0
	v_add_co_u32_e32 v8, vcc, s4, v8
	v_lshl_add_u64 v[10:11], v[86:87], 0, v[160:161]
	s_nop 0
	v_addc_co_u32_e32 v9, vcc, 0, v9, vcc
	v_lshl_add_u64 v[10:11], s[2:3], 0, v[10:11]
	v_add_co_u32_e32 v12, vcc, s4, v10
	global_load_dwordx4 v[0:3], v[0:1], off
	global_load_dwordx4 v[4:7], v[4:5], off
	v_addc_co_u32_e32 v13, vcc, 0, v11, vcc
	global_load_dwordx4 v[8:11], v[8:9], off
	global_load_dwordx4 v[12:15], v[12:13], off
	ds_read_b64_tr_b8 v[30:31], v126 offset:0
	ds_read_b64_tr_b8 v[74:75], v126 offset:16
	ds_read_b64_tr_b8 v[78:79], v126 offset:32
	ds_read_b64_tr_b8 v[94:95], v126 offset:48
	ds_read_b64_tr_b8 v[98:99], v126 offset:64
	ds_read_b64_tr_b8 v[102:103], v126 offset:80
	ds_read_b64_tr_b8 v[106:107], v126 offset:96
	ds_read_b64_tr_b8 v[110:111], v126 offset:112
	s_nop 0
	s_waitcnt lgkmcnt(0)
	s_nop 0
	v_mfma_f32_16x16x32_fp8_fp8 v[70:73], v[28:29], v[30:31], 0
	v_mfma_f32_16x16x32_fp8_fp8 v[74:77], v[28:29], v[74:75], 0
	v_mfma_f32_16x16x32_fp8_fp8 v[90:93], v[28:29], v[78:79], 0
	v_mfma_f32_16x16x32_fp8_fp8 v[94:97], v[28:29], v[94:95], 0
	v_mfma_f32_16x16x32_fp8_fp8 v[98:101], v[28:29], v[98:99], 0
	v_mfma_f32_16x16x32_fp8_fp8 v[102:105], v[28:29], v[102:103], 0
	v_mfma_f32_16x16x32_fp8_fp8 v[106:109], v[28:29], v[106:107], 0
	v_mfma_f32_16x16x32_fp8_fp8 v[28:31], v[28:29], v[110:111], 0
	s_waitcnt vmcnt(11)
	ds_write_b128 v135, v[38:41] offset:4096
	s_waitcnt vmcnt(10)
	ds_write_b128 v135, v[42:45] offset:5248
	s_waitcnt vmcnt(9)
	ds_write_b128 v135, v[46:49] offset:6400
	s_waitcnt vmcnt(8)
	ds_write_b128 v135, v[50:53] offset:7552
	ds_read_u16 v38, v127 offset:256
	ds_read_u16 v40, v127 offset:264
	ds_read_u16 v46, v127 offset:272
	ds_read_u16 v48, v127 offset:280
	s_waitcnt lgkmcnt(3)
	v_and_b32_e32 v38, 0xfff, v38
	v_lshlrev_b32_sdwa v160, v191, v38 dst_sel:DWORD dst_unused:UNUSED_PAD src0_sel:DWORD src1_sel:WORD_0
	v_lshl_add_u64 v[38:39], v[86:87], 0, v[160:161]
	s_waitcnt lgkmcnt(2)
	v_and_b32_e32 v40, 0xfff, v40
	v_lshl_add_u64 v[38:39], s[2:3], 0, v[38:39]
	v_lshlrev_b32_sdwa v160, v191, v40 dst_sel:DWORD dst_unused:UNUSED_PAD src0_sel:DWORD src1_sel:WORD_0
	v_add_co_u32_e32 v38, vcc, s4, v38
	v_lshl_add_u64 v[40:41], v[86:87], 0, v[160:161]
	s_waitcnt lgkmcnt(1)
	v_and_b32_e32 v46, 0xfff, v46
	v_addc_co_u32_e32 v39, vcc, 0, v39, vcc
	v_lshl_add_u64 v[40:41], s[2:3], 0, v[40:41]
	v_lshlrev_b32_sdwa v160, v191, v46 dst_sel:DWORD dst_unused:UNUSED_PAD src0_sel:DWORD src1_sel:WORD_0
	v_add_co_u32_e32 v42, vcc, s4, v40
	v_lshl_add_u64 v[46:47], v[86:87], 0, v[160:161]
	s_waitcnt lgkmcnt(0)
	v_and_b32_e32 v48, 0xfff, v48
	v_addc_co_u32_e32 v43, vcc, 0, v41, vcc
	v_lshl_add_u64 v[46:47], s[2:3], 0, v[46:47]
	v_lshlrev_b32_sdwa v160, v191, v48 dst_sel:DWORD dst_unused:UNUSED_PAD src0_sel:DWORD src1_sel:WORD_0
	v_add_co_u32_e32 v46, vcc, s4, v46
	v_lshl_add_u64 v[48:49], v[86:87], 0, v[160:161]
	s_nop 0
	v_addc_co_u32_e32 v47, vcc, 0, v47, vcc
	v_lshl_add_u64 v[48:49], s[2:3], 0, v[48:49]
	v_add_co_u32_e32 v50, vcc, s4, v48
	global_load_dwordx4 v[38:41], v[38:39], off
	global_load_dwordx4 v[42:45], v[42:43], off
	v_addc_co_u32_e32 v51, vcc, 0, v49, vcc
	global_load_dwordx4 v[46:49], v[46:47], off
	global_load_dwordx4 v[50:53], v[50:51], off
	ds_read_b64_tr_b8 v[78:79], v126 offset:0
	ds_read_b64_tr_b8 v[110:111], v126 offset:16
	ds_read_b64_tr_b8 v[112:113], v126 offset:32
	ds_read_b64_tr_b8 v[114:115], v126 offset:48
	ds_read_b64_tr_b8 v[116:117], v126 offset:64
	ds_read_b64_tr_b8 v[118:119], v126 offset:80
	ds_read_b64_tr_b8 v[120:121], v126 offset:96
	ds_read_b64_tr_b8 v[122:123], v126 offset:112
	s_nop 0
	s_waitcnt lgkmcnt(0)
	s_nop 0
	v_mfma_f32_16x16x32_fp8_fp8 v[70:73], v[26:27], v[78:79], v[70:73]
	v_mfma_f32_16x16x32_fp8_fp8 v[74:77], v[26:27], v[110:111], v[74:77]
	v_mfma_f32_16x16x32_fp8_fp8 v[90:93], v[26:27], v[112:113], v[90:93]
	v_mfma_f32_16x16x32_fp8_fp8 v[94:97], v[26:27], v[114:115], v[94:97]
	v_mfma_f32_16x16x32_fp8_fp8 v[98:101], v[26:27], v[116:117], v[98:101]
	v_mfma_f32_16x16x32_fp8_fp8 v[102:105], v[26:27], v[118:119], v[102:105]
	v_mfma_f32_16x16x32_fp8_fp8 v[106:109], v[26:27], v[120:121], v[106:109]
	v_mfma_f32_16x16x32_fp8_fp8 v[26:29], v[26:27], v[122:123], v[28:31]
	s_waitcnt vmcnt(11)
	ds_write_b128 v135, v[54:57] offset:4096
	s_waitcnt vmcnt(10)
	ds_write_b128 v135, v[58:61] offset:5248
	s_waitcnt vmcnt(9)
	ds_write_b128 v135, v[62:65] offset:6400
	s_waitcnt vmcnt(8)
	ds_write_b128 v135, v[66:69] offset:7552
	ds_read_u16 v30, v127 offset:320
	ds_read_u16 v54, v127 offset:328
	ds_read_u16 v62, v127 offset:336
	ds_read_u16 v63, v127 offset:344
	s_waitcnt lgkmcnt(3)
; #define PV_LOAD(set, st) do { _Pragma("unroll") for (int i = 0; i < 4; ++i) { const int row = widx[(st) * 32 + slot0 + 4 * i] & 4095; R[set][i] = *(const u32x4*)(vg + (size_t)row * 512); } __builtin_amdgcn_sched_barrier(0); } while (0)
; __device__ __forceinline__ void attn_phase(const int TID, const int BID, PP p, LAS unsigned char* lds) {
;     ...
;             PV_LOAD(0, 0); PV_LOAD(1, 1); PV_LOAD(2, 2);
;             PV_STEP(0, 0, true); PV_STEP(1, 1, true); PV_STEP(2, 2, true); PV_STEP(0, 3, true); PV_STEP(1, 4, true);
;             PV_STEP(2, 5, false); PV_STEP(0, 6, false); PV_STEP(1, 7, false);
	v_and_b32_e32 v30, 0xfff, v30
	v_lshlrev_b32_sdwa v160, v191, v30 dst_sel:DWORD dst_unused:UNUSED_PAD src0_sel:DWORD src1_sel:WORD_0
	v_lshl_add_u64 v[30:31], v[86:87], 0, v[160:161]
	s_waitcnt lgkmcnt(2)
	v_and_b32_e32 v54, 0xfff, v54
	v_lshl_add_u64 v[30:31], s[2:3], 0, v[30:31]
	v_lshlrev_b32_sdwa v160, v191, v54 dst_sel:DWORD dst_unused:UNUSED_PAD src0_sel:DWORD src1_sel:WORD_0
	v_add_co_u32_e32 v30, vcc, s4, v30
	v_lshl_add_u64 v[54:55], v[86:87], 0, v[160:161]
	s_nop 0
	v_addc_co_u32_e32 v31, vcc, 0, v31, vcc
	v_lshl_add_u64 v[54:55], s[2:3], 0, v[54:55]
	v_add_co_u32_e32 v58, vcc, s4, v54
	s_nop 1
	v_addc_co_u32_e32 v59, vcc, 0, v55, vcc
	global_load_dwordx4 v[54:57], v[30:31], off
	global_load_dwordx4 v[58:61], v[58:59], off
	s_waitcnt lgkmcnt(1)
	v_and_b32_e32 v30, 0xfff, v62
	v_lshlrev_b32_sdwa v160, v191, v30 dst_sel:DWORD dst_unused:UNUSED_PAD src0_sel:DWORD src1_sel:WORD_0
	v_lshl_add_u64 v[30:31], v[86:87], 0, v[160:161]
	s_waitcnt lgkmcnt(0)
	v_and_b32_e32 v62, 0xfff, v63
	v_lshl_add_u64 v[30:31], s[2:3], 0, v[30:31]
	v_lshlrev_b32_sdwa v160, v191, v62 dst_sel:DWORD dst_unused:UNUSED_PAD src0_sel:DWORD src1_sel:WORD_0
	v_add_co_u32_e32 v30, vcc, s4, v30
	v_lshl_add_u64 v[62:63], v[86:87], 0, v[160:161]
	s_nop 0
	v_addc_co_u32_e32 v31, vcc, 0, v31, vcc
	v_lshl_add_u64 v[62:63], s[2:3], 0, v[62:63]
	v_add_co_u32_e32 v66, vcc, s4, v62
	s_nop 1
	v_addc_co_u32_e32 v67, vcc, 0, v63, vcc
	global_load_dwordx4 v[62:65], v[30:31], off
	global_load_dwordx4 v[66:69], v[66:67], off
	ds_read_b64_tr_b8 v[30:31], v126 offset:0
	ds_read_b64_tr_b8 v[78:79], v126 offset:16
	ds_read_b64_tr_b8 v[110:111], v126 offset:32
	ds_read_b64_tr_b8 v[112:113], v126 offset:48
	ds_read_b64_tr_b8 v[114:115], v126 offset:64
	ds_read_b64_tr_b8 v[116:117], v126 offset:80
	ds_read_b64_tr_b8 v[118:119], v126 offset:96
	ds_read_b64_tr_b8 v[120:121], v126 offset:112
	s_nop 0
	s_waitcnt lgkmcnt(0)
	s_nop 0
	v_mfma_f32_16x16x32_fp8_fp8 v[70:73], v[24:25], v[30:31], v[70:73]
	v_mfma_f32_16x16x32_fp8_fp8 v[74:77], v[24:25], v[78:79], v[74:77]
	v_mfma_f32_16x16x32_fp8_fp8 v[90:93], v[24:25], v[110:111], v[90:93]
	v_mfma_f32_16x16x32_fp8_fp8 v[94:97], v[24:25], v[112:113], v[94:97]
	v_mfma_f32_16x16x32_fp8_fp8 v[98:101], v[24:25], v[114:115], v[98:101]
	v_mfma_f32_16x16x32_fp8_fp8 v[102:105], v[24:25], v[116:117], v[102:105]
	v_mfma_f32_16x16x32_fp8_fp8 v[106:109], v[24:25], v[118:119], v[106:109]
	v_mfma_f32_16x16x32_fp8_fp8 v[24:27], v[24:25], v[120:121], v[26:29]
	s_waitcnt vmcnt(11)
	ds_write_b128 v135, v[0:3] offset:4096
	s_waitcnt vmcnt(10)
	ds_write_b128 v135, v[4:7] offset:5248
	s_waitcnt vmcnt(9)
	ds_write_b128 v135, v[8:11] offset:6400
	s_waitcnt vmcnt(8)
	ds_write_b128 v135, v[12:15] offset:7552
	ds_read_u16 v0, v127 offset:384
	ds_read_u16 v2, v127 offset:392
	ds_read_u16 v8, v127 offset:400
	ds_read_u16 v10, v127 offset:408
	s_waitcnt lgkmcnt(3)
	v_and_b32_e32 v0, 0xfff, v0
	v_lshlrev_b32_sdwa v160, v191, v0 dst_sel:DWORD dst_unused:UNUSED_PAD src0_sel:DWORD src1_sel:WORD_0
	v_lshl_add_u64 v[0:1], v[86:87], 0, v[160:161]
	s_waitcnt lgkmcnt(2)
	v_and_b32_e32 v2, 0xfff, v2
	v_lshl_add_u64 v[0:1], s[2:3], 0, v[0:1]
	v_lshlrev_b32_sdwa v160, v191, v2 dst_sel:DWORD dst_unused:UNUSED_PAD src0_sel:DWORD src1_sel:WORD_0
	v_add_co_u32_e32 v0, vcc, s4, v0
	v_lshl_add_u64 v[2:3], v[86:87], 0, v[160:161]
	s_waitcnt lgkmcnt(1)
	v_and_b32_e32 v8, 0xfff, v8
	v_addc_co_u32_e32 v1, vcc, 0, v1, vcc
	v_lshl_add_u64 v[2:3], s[2:3], 0, v[2:3]
	v_lshlrev_b32_sdwa v160, v191, v8 dst_sel:DWORD dst_unused:UNUSED_PAD src0_sel:DWORD src1_sel:WORD_0
	v_add_co_u32_e32 v4, vcc, s4, v2
	v_lshl_add_u64 v[8:9], v[86:87], 0, v[160:161]
	s_waitcnt lgkmcnt(0)
	v_and_b32_e32 v10, 0xfff, v10
	v_addc_co_u32_e32 v5, vcc, 0, v3, vcc
	v_lshl_add_u64 v[8:9], s[2:3], 0, v[8:9]
	v_lshlrev_b32_sdwa v160, v191, v10 dst_sel:DWORD dst_unused:UNUSED_PAD src0_sel:DWORD src1_sel:WORD_0
	v_add_co_u32_e32 v8, vcc, s4, v8
	v_lshl_add_u64 v[10:11], v[86:87], 0, v[160:161]
	s_nop 0
	v_addc_co_u32_e32 v9, vcc, 0, v9, vcc
	v_lshl_add_u64 v[10:11], s[2:3], 0, v[10:11]
	v_add_co_u32_e32 v12, vcc, s4, v10
	global_load_dwordx4 v[0:3], v[0:1], off
	global_load_dwordx4 v[4:7], v[4:5], off
	v_addc_co_u32_e32 v13, vcc, 0, v11, vcc
	global_load_dwordx4 v[8:11], v[8:9], off
	global_load_dwordx4 v[12:15], v[12:13], off
	ds_read_b64_tr_b8 v[28:29], v126 offset:0
	ds_read_b64_tr_b8 v[78:79], v126 offset:16
	ds_read_b64_tr_b8 v[110:111], v126 offset:32
	ds_read_b64_tr_b8 v[112:113], v126 offset:48
	ds_read_b64_tr_b8 v[114:115], v126 offset:64
	ds_read_b64_tr_b8 v[116:117], v126 offset:80
	ds_read_b64_tr_b8 v[118:119], v126 offset:96
	ds_read_b64_tr_b8 v[120:121], v126 offset:112
	s_nop 0
	s_waitcnt lgkmcnt(0)
	s_nop 0
	v_mfma_f32_16x16x32_fp8_fp8 v[28:31], v[22:23], v[28:29], v[70:73]
	v_mfma_f32_16x16x32_fp8_fp8 v[70:73], v[22:23], v[78:79], v[74:77]
	v_mfma_f32_16x16x32_fp8_fp8 v[74:77], v[22:23], v[110:111], v[90:93]
	v_mfma_f32_16x16x32_fp8_fp8 v[90:93], v[22:23], v[112:113], v[94:97]
	v_mfma_f32_16x16x32_fp8_fp8 v[94:97], v[22:23], v[114:115], v[98:101]
	v_mfma_f32_16x16x32_fp8_fp8 v[98:101], v[22:23], v[116:117], v[102:105]
	v_mfma_f32_16x16x32_fp8_fp8 v[102:105], v[22:23], v[118:119], v[106:109]
	v_mfma_f32_16x16x32_fp8_fp8 v[22:25], v[22:23], v[120:121], v[24:27]
	s_waitcnt vmcnt(11)
	ds_write_b128 v135, v[38:41] offset:4096
	s_waitcnt vmcnt(10)
	ds_write_b128 v135, v[42:45] offset:5248
	s_waitcnt vmcnt(9)
	ds_write_b128 v135, v[46:49] offset:6400
	s_waitcnt vmcnt(8)
	ds_write_b128 v135, v[50:53] offset:7552
	ds_read_u16 v26, v127 offset:448
	ds_read_u16 v38, v127 offset:456
	ds_read_u16 v46, v127 offset:464
	ds_read_u16 v47, v127 offset:472
	s_waitcnt lgkmcnt(3)
; #define PV_LOAD(set, st) do { _Pragma("unroll") for (int i = 0; i < 4; ++i) { const int row = widx[(st) * 32 + slot0 + 4 * i] & 4095; R[set][i] = *(const u32x4*)(vg + (size_t)row * 512); } __builtin_amdgcn_sched_barrier(0); } while (0)
; __device__ __forceinline__ void attn_phase(const int TID, const int BID, PP p, LAS unsigned char* lds) {
;     ...
;             PV_LOAD(0, 0); PV_LOAD(1, 1); PV_LOAD(2, 2);
;             PV_STEP(0, 0, true); PV_STEP(1, 1, true); PV_STEP(2, 2, true); PV_STEP(0, 3, true); PV_STEP(1, 4, true);
;             PV_STEP(2, 5, false); PV_STEP(0, 6, false); PV_STEP(1, 7, false);
;     ...
; #pragma unroll
;             for (int nt = 0; nt < 8; ++nt)
;                 if ((nt >> 1) == fq) {
	v_and_b32_e32 v26, 0xfff, v26
	v_lshlrev_b32_sdwa v160, v191, v26 dst_sel:DWORD dst_unused:UNUSED_PAD src0_sel:DWORD src1_sel:WORD_0
	v_lshl_add_u64 v[26:27], v[86:87], 0, v[160:161]
	s_waitcnt lgkmcnt(2)
	v_and_b32_e32 v38, 0xfff, v38
	v_lshl_add_u64 v[26:27], s[2:3], 0, v[26:27]
	v_lshlrev_b32_sdwa v160, v191, v38 dst_sel:DWORD dst_unused:UNUSED_PAD src0_sel:DWORD src1_sel:WORD_0
	v_add_co_u32_e32 v26, vcc, s4, v26
	v_lshl_add_u64 v[38:39], v[86:87], 0, v[160:161]
	s_nop 0
	v_addc_co_u32_e32 v27, vcc, 0, v27, vcc
	v_lshl_add_u64 v[38:39], s[2:3], 0, v[38:39]
	v_add_co_u32_e32 v42, vcc, s4, v38
	s_nop 1
	v_addc_co_u32_e32 v43, vcc, 0, v39, vcc
	global_load_dwordx4 v[38:41], v[26:27], off
	global_load_dwordx4 v[42:45], v[42:43], off
	s_waitcnt lgkmcnt(1)
	v_and_b32_e32 v26, 0xfff, v46
	v_lshlrev_b32_sdwa v160, v191, v26 dst_sel:DWORD dst_unused:UNUSED_PAD src0_sel:DWORD src1_sel:WORD_0
	v_lshl_add_u64 v[26:27], v[86:87], 0, v[160:161]
	s_waitcnt lgkmcnt(0)
	v_and_b32_e32 v46, 0xfff, v47
	v_lshl_add_u64 v[26:27], s[2:3], 0, v[26:27]
	v_lshlrev_b32_sdwa v160, v191, v46 dst_sel:DWORD dst_unused:UNUSED_PAD src0_sel:DWORD src1_sel:WORD_0
	v_add_co_u32_e32 v26, vcc, s4, v26
	v_lshl_add_u64 v[46:47], v[86:87], 0, v[160:161]
	s_nop 0
	v_addc_co_u32_e32 v27, vcc, 0, v27, vcc
	v_lshl_add_u64 v[46:47], s[2:3], 0, v[46:47]
	v_add_co_u32_e32 v50, vcc, s4, v46
	s_nop 1
	v_addc_co_u32_e32 v51, vcc, 0, v47, vcc
	global_load_dwordx4 v[46:49], v[26:27], off
	global_load_dwordx4 v[50:53], v[50:51], off
	ds_read_b64_tr_b8 v[26:27], v126 offset:0
	ds_read_b64_tr_b8 v[78:79], v126 offset:16
	ds_read_b64_tr_b8 v[106:107], v126 offset:32
	ds_read_b64_tr_b8 v[108:109], v126 offset:48
	ds_read_b64_tr_b8 v[110:111], v126 offset:64
	ds_read_b64_tr_b8 v[112:113], v126 offset:80
	ds_read_b64_tr_b8 v[114:115], v126 offset:96
	ds_read_b64_tr_b8 v[116:117], v126 offset:112
	s_nop 0
	s_waitcnt lgkmcnt(0)
	s_nop 0
	v_mfma_f32_16x16x32_fp8_fp8 v[26:29], v[20:21], v[26:27], v[28:31]
	v_mfma_f32_16x16x32_fp8_fp8 v[70:73], v[20:21], v[78:79], v[70:73]
	v_mfma_f32_16x16x32_fp8_fp8 v[74:77], v[20:21], v[106:107], v[74:77]
	v_mfma_f32_16x16x32_fp8_fp8 v[90:93], v[20:21], v[108:109], v[90:93]
	v_mfma_f32_16x16x32_fp8_fp8 v[94:97], v[20:21], v[110:111], v[94:97]
	v_mfma_f32_16x16x32_fp8_fp8 v[98:101], v[20:21], v[112:113], v[98:101]
	v_mfma_f32_16x16x32_fp8_fp8 v[102:105], v[20:21], v[114:115], v[102:105]
	v_mfma_f32_16x16x32_fp8_fp8 v[20:23], v[20:21], v[116:117], v[22:25]
	s_waitcnt vmcnt(11)
	ds_write_b128 v135, v[54:57] offset:4096
	s_waitcnt vmcnt(10)
	ds_write_b128 v135, v[58:61] offset:5248
	s_waitcnt vmcnt(9)
	ds_write_b128 v135, v[62:65] offset:6400
	s_waitcnt vmcnt(8)
	ds_write_b128 v135, v[66:69] offset:7552
	ds_read_b64_tr_b8 v[24:25], v126 offset:0
	ds_read_b64_tr_b8 v[30:31], v126 offset:16
	ds_read_b64_tr_b8 v[54:55], v126 offset:32
	ds_read_b64_tr_b8 v[58:59], v126 offset:48
	ds_read_b64_tr_b8 v[62:63], v126 offset:64
	ds_read_b64_tr_b8 v[66:67], v126 offset:80
	ds_read_b64_tr_b8 v[78:79], v126 offset:96
	ds_read_b64_tr_b8 v[106:107], v126 offset:112
	s_nop 0
	s_waitcnt lgkmcnt(0)
	s_nop 0
	v_mfma_f32_16x16x32_fp8_fp8 v[24:27], v[18:19], v[24:25], v[26:29]
	v_mfma_f32_16x16x32_fp8_fp8 v[28:31], v[18:19], v[30:31], v[70:73]
	v_mfma_f32_16x16x32_fp8_fp8 v[54:57], v[18:19], v[54:55], v[74:77]
	v_mfma_f32_16x16x32_fp8_fp8 v[58:61], v[18:19], v[58:59], v[90:93]
	v_mfma_f32_16x16x32_fp8_fp8 v[62:65], v[18:19], v[62:63], v[94:97]
	v_mfma_f32_16x16x32_fp8_fp8 v[66:69], v[18:19], v[66:67], v[98:101]
	v_mfma_f32_16x16x32_fp8_fp8 v[70:73], v[18:19], v[78:79], v[102:105]
	v_mfma_f32_16x16x32_fp8_fp8 v[18:21], v[18:19], v[106:107], v[20:23]
	s_waitcnt vmcnt(7)
	ds_write_b128 v135, v[0:3] offset:4096
	s_waitcnt vmcnt(6)
	ds_write_b128 v135, v[4:7] offset:5248
	s_waitcnt vmcnt(5)
	ds_write_b128 v135, v[8:11] offset:6400
	s_waitcnt vmcnt(4)
	ds_write_b128 v135, v[12:15] offset:7552
	ds_read_b64_tr_b8 v[0:1], v126 offset:0
	ds_read_b64_tr_b8 v[4:5], v126 offset:16
	ds_read_b64_tr_b8 v[8:9], v126 offset:32
	ds_read_b64_tr_b8 v[12:13], v126 offset:48
	ds_read_b64_tr_b8 v[22:23], v126 offset:64
	ds_read_b64_tr_b8 v[74:75], v126 offset:80
	ds_read_b64_tr_b8 v[76:77], v126 offset:96
	ds_read_b64_tr_b8 v[78:79], v126 offset:112
	s_nop 0
	s_waitcnt lgkmcnt(0)
	s_nop 0
	v_mfma_f32_16x16x32_fp8_fp8 v[0:3], v[16:17], v[0:1], v[24:27]
	v_mfma_f32_16x16x32_fp8_fp8 v[4:7], v[16:17], v[4:5], v[28:31]
	v_mfma_f32_16x16x32_fp8_fp8 v[8:11], v[16:17], v[8:9], v[54:57]
	v_mfma_f32_16x16x32_fp8_fp8 v[12:15], v[16:17], v[12:13], v[58:61]
	v_mfma_f32_16x16x32_fp8_fp8 v[54:57], v[16:17], v[22:23], v[62:65]
	v_mfma_f32_16x16x32_fp8_fp8 v[58:61], v[16:17], v[74:75], v[66:69]
	v_mfma_f32_16x16x32_fp8_fp8 v[62:65], v[16:17], v[76:77], v[70:73]
	v_mfma_f32_16x16x32_fp8_fp8 v[66:69], v[16:17], v[78:79], v[18:21]
	s_waitcnt vmcnt(3)
	ds_write_b128 v135, v[38:41] offset:4096
	s_waitcnt vmcnt(2)
	ds_write_b128 v135, v[42:45] offset:5248
	s_waitcnt vmcnt(1)
	ds_write_b128 v135, v[46:49] offset:6400
	s_waitcnt vmcnt(0)
	ds_write_b128 v135, v[50:53] offset:7552
	ds_read_b64_tr_b8 v[16:17], v126 offset:0
	ds_read_b64_tr_b8 v[18:19], v126 offset:16
	ds_read_b64_tr_b8 v[20:21], v126 offset:32
	ds_read_b64_tr_b8 v[22:23], v126 offset:48
	ds_read_b64_tr_b8 v[38:39], v126 offset:64
	ds_read_b64_tr_b8 v[40:41], v126 offset:80
	ds_read_b64_tr_b8 v[42:43], v126 offset:96
	ds_read_b64_tr_b8 v[44:45], v126 offset:112
	s_nop 0
	s_waitcnt lgkmcnt(0)
	s_nop 0
	v_mfma_f32_16x16x32_fp8_fp8 v[28:31], v[32:33], v[16:17], v[0:3]
	v_mfma_f32_16x16x32_fp8_fp8 v[24:27], v[32:33], v[18:19], v[4:7]
	v_mfma_f32_16x16x32_fp8_fp8 v[16:19], v[32:33], v[20:21], v[8:11]
	v_mfma_f32_16x16x32_fp8_fp8 v[4:7], v[32:33], v[22:23], v[12:15]
	v_mfma_f32_16x16x32_fp8_fp8 v[12:15], v[32:33], v[38:39], v[54:57]
	v_mfma_f32_16x16x32_fp8_fp8 v[0:3], v[32:33], v[40:41], v[58:61]
	v_mfma_f32_16x16x32_fp8_fp8 v[20:23], v[32:33], v[42:43], v[62:65]
	v_mfma_f32_16x16x32_fp8_fp8 v[8:11], v[32:33], v[44:45], v[66:69]
	s_and_saveexec_b64 s[10:11], s[8:9]
	s_cbranch_execz .LBB0_707
; __device__ __forceinline__ unsigned cvt_pk_bf16(float lo, float hi) { unsigned r; asm volatile("v_cvt_pk_bf16_f32 %0, %1, %2" : "=v"(r) : "v"(lo), "v"(hi)); return r; }
; __device__ __forceinline__ void attn_phase(const int TID, const int BID, PP p, LAS unsigned char* lds) {
;     ...
; #pragma unroll
;             for (int nt = 0; nt < 8; ++nt)
;                 if ((nt >> 1) == fq) {
; #pragma unroll
;                     for (int i = 0; i < 4; ++i) O[(size_t)tok * 2048 + (g * 4 + i) * 128 + nt * 16 + fr] = (bf16_t)(cvt_pk_bf16(acc[nt][i] * invh[i], 0.f) & 0xffffu);
;                 }
	v_lshl_add_u64 v[32:33], v[80:81], 0, s[24:25]
	v_mul_f32_e32 v28, v28, v37
	v_or_b32_e32 v39, s13, v33
	v_or_b32_e32 v38, s12, v32
	v_cvt_pk_bf16_f32 v28, v28, v161
	v_lshl_add_u64 v[38:39], v[38:39], 1, s[80:81]
	global_store_short v[38:39], v28, off
	v_mul_f32_e32 v28, v29, v36
	v_cvt_pk_bf16_f32 v38, v28, v161
	v_lshl_add_u64 v[28:29], v[32:33], 0, s[90:91]
	v_or_b32_e32 v29, s13, v29
	v_or_b32_e32 v28, s12, v28
	v_lshl_add_u64 v[28:29], v[28:29], 1, s[80:81]
	global_store_short v[28:29], v38, off
	v_mul_f32_e32 v28, v30, v35
	s_mov_b64 s[0:1], 0x100
	v_cvt_pk_bf16_f32 v30, v28, v161
	v_lshl_add_u64 v[28:29], v[32:33], 0, s[0:1]
	v_or_b32_e32 v29, s13, v29
	v_or_b32_e32 v28, s12, v28
	v_lshl_add_u64 v[28:29], v[28:29], 1, s[80:81]
	global_store_short v[28:29], v30, off
	v_mul_f32_e32 v28, v31, v34
	s_mov_b64 s[0:1], 0x180
	v_cvt_pk_bf16_f32 v30, v28, v161
	v_lshl_add_u64 v[28:29], v[32:33], 0, s[0:1]
	v_or_b32_e32 v29, s13, v29
	v_or_b32_e32 v28, s12, v28
	v_lshl_add_u64 v[28:29], v[28:29], 1, s[80:81]
	global_store_short v[28:29], v30, off
	v_lshl_add_u64 v[28:29], v[32:33], 0, 16
	v_mul_f32_e32 v24, v24, v37
	v_or_b32_e32 v29, s13, v29
	v_or_b32_e32 v28, s12, v28
	v_cvt_pk_bf16_f32 v24, v24, v161
	v_lshl_add_u64 v[28:29], v[28:29], 1, s[80:81]
	global_store_short v[28:29], v24, off
	v_mul_f32_e32 v24, v25, v36
	s_mov_b64 s[0:1], 0x90
	v_cvt_pk_bf16_f32 v28, v24, v161
	v_lshl_add_u64 v[24:25], v[32:33], 0, s[0:1]
	v_or_b32_e32 v25, s13, v25
	v_or_b32_e32 v24, s12, v24
	v_lshl_add_u64 v[24:25], v[24:25], 1, s[80:81]
	global_store_short v[24:25], v28, off
	v_mul_f32_e32 v24, v26, v35
	s_mov_b64 s[0:1], 0x110
	v_cvt_pk_bf16_f32 v26, v24, v161
	v_lshl_add_u64 v[24:25], v[32:33], 0, s[0:1]
	v_or_b32_e32 v25, s13, v25
	v_or_b32_e32 v24, s12, v24
	v_lshl_add_u64 v[24:25], v[24:25], 1, s[80:81]
	global_store_short v[24:25], v26, off
	v_mul_f32_e32 v24, v27, v34
	s_mov_b64 s[0:1], 0x190
	v_cvt_pk_bf16_f32 v26, v24, v161
	v_lshl_add_u64 v[24:25], v[32:33], 0, s[0:1]
	v_or_b32_e32 v25, s13, v25
	v_or_b32_e32 v24, s12, v24
	v_lshl_add_u64 v[24:25], v[24:25], 1, s[80:81]
	global_store_short v[24:25], v26, off

; #define LAS __attribute__((address_space(3)))
; __device__ __forceinline__ void idx_phase(const int TID, const int BID, PP p, LAS unsigned char* lds) {
;     ...
;     for (int item = BID; item < 1088; item += gridDim.x) {
;         const int b = item / 544; int rem = item % 544;
;         int a = 0; while (rem >= 4 * (a + 1)) { rem -= 4 * (a + 1); ++a; }
;         const int c = 4 * a + rem / (a + 1), kb = rem % (a + 1);
;         const int key0 = kb * 256, Nk = (c + 1) * 64, nkeys = min(256, Nk - key0);
;         bf16x8 Aq[4][4]; float wqa[4][16];
; #pragma unroll
;         for (int pr = 0; pr < 4; ++pr) {
;             const int tokq = b * SEQ + c * 64 + wv * 8 + 2 * pr;
;             const bf16_t* src = QIb + (size_t)(tokq + (rr >> 4)) * 1024 + (rr & 15) * 64 + g2 * 32;
; #pragma unroll
;             for (int ks = 0; ks < 4; ++ks) Aq[pr][ks] = *(const bf16x8*)(src + ks * 8);
; #pragma unroll
;             for (int i = 0; i < 16; ++i) wqa[pr][i] = WI[(size_t)(tokq + (i >> 3)) * 16 + 8 * ((i >> 2) & 1) + 4 * g2 + (i & 3)];
;         }
;         __syncthreads();
;         { const int key = t >> 1, half = t & 1;
;           if (key < nkeys) { const bf16_t* src = KIb + (size_t)(b * SEQ + key0 + key) * 64 + half * 32;
; #pragma unroll
;               for (int j = 0; j < 4; ++j) *(LAS u32x4*)(lds + key * 144 + half * 64 + j * 16) = *(const u32x4*)(src + j * 8); } }
.LBB0_731:
	v_mov_b32_e32 v0, v1
	v_mov_b32_e32 v199, v2
	v_mov_b32_e32 v198, v3
	v_mov_b32_e32 v197, v4
	s_mov_b32 s8, s4
	s_sub_i32 s4, s4, s10
	s_add_i32 s9, s9, 1
	s_add_i32 s11, s10, 4
	s_cmp_ge_i32 s8, s10
	v_add_u32_e32 v1, 0x100, v0
	v_add_u32_e32 v2, 0x100, v199
	v_add_u32_e32 v3, 0x100, v198
	v_add_u32_e32 v4, 0x100, v197
	s_mov_b32 s10, s11
	s_cbranch_scc1 .LBB0_731
	s_add_i32 s10, s9, 1
	v_cvt_f32_u32_e32 v1, s10
	s_not_b32 s12, s9
	s_abs_i32 s11, s8
	s_ashr_i32 s4, s8, 31
	v_rcp_iflag_f32_e32 v1, v1
	s_nop 0
	v_mul_f32_e32 v1, 0x4f7ffffe, v1
	v_cvt_u32_f32_e32 v1, v1
	s_nop 0
	v_readfirstlane_b32 s13, v1
	s_mul_i32 s12, s12, s13
	s_mul_hi_u32 s12, s13, s12
	s_add_i32 s13, s13, s12
	s_mul_hi_u32 s12, s11, s13
	s_mul_i32 s13, s12, s10
	s_sub_i32 s11, s11, s13
	s_add_i32 s14, s12, 1
	s_sub_i32 s13, s11, s10
	s_cmp_ge_u32 s11, s10
	s_cselect_b32 s12, s14, s12
	s_cselect_b32 s11, s13, s11
	s_add_i32 s13, s12, 1
	s_cmp_ge_u32 s11, s10
	s_cselect_b32 s11, s13, s12
	s_xor_b32 s14, s11, s4
	s_sub_i32 s11, s14, s4
	s_lshl_b32 s9, s9, 8
	s_lshl_b32 s12, s11, 6
	s_add_i32 s9, s12, s9
	s_add_i32 s12, s9, s1
	v_add_u32_e32 v2, s12, v178
	v_or_b32_e32 v4, v2, v179
	v_ashrrev_i32_e32 v5, 31, v4
	v_lshlrev_b64 v[4:5], 11, v[4:5]
	v_lshl_add_u64 v[4:5], v[166:167], 0, v[4:5]
	v_ashrrev_i32_e32 v3, 31, v2
	global_load_dwordx4 v[128:131], v[4:5], off
	global_load_dwordx4 v[132:135], v[4:5], off offset:16
	global_load_dwordx4 v[136:139], v[4:5], off offset:32
	global_load_dwordx4 v[140:143], v[4:5], off offset:48
	v_lshlrev_b64 v[4:5], 6, v[2:3]
	v_lshl_add_u64 v[4:5], v[170:171], 0, v[4:5]
	global_load_dwordx4 v[144:147], v[4:5], off
	global_load_dwordx4 v[148:151], v[4:5], off offset:32
	v_or_b32_e32 v4, 1, v2
	v_ashrrev_i32_e32 v5, 31, v4
	v_lshlrev_b64 v[4:5], 6, v[4:5]
	v_lshl_add_u64 v[4:5], v[170:171], 0, v[4:5]
	global_load_dwordx4 v[152:155], v[4:5], off
	global_load_dwordx4 v[156:159], v[4:5], off offset:32
	v_or_b32_e32 v4, 2, v2
	v_or_b32_e32 v6, v4, v179
	v_ashrrev_i32_e32 v7, 31, v6
	v_ashrrev_i32_e32 v5, 31, v4
	v_lshlrev_b64 v[6:7], 11, v[6:7]
	v_lshlrev_b64 v[4:5], 6, v[4:5]
	v_lshl_add_u64 v[6:7], v[166:167], 0, v[6:7]
	v_lshl_add_u64 v[4:5], v[170:171], 0, v[4:5]
	global_load_dwordx4 v[96:99], v[6:7], off
	global_load_dwordx4 v[100:103], v[6:7], off offset:16
	global_load_dwordx4 v[104:107], v[6:7], off offset:32
	global_load_dwordx4 v[108:111], v[6:7], off offset:48
	global_load_dwordx4 v[112:115], v[4:5], off
	global_load_dwordx4 v[116:119], v[4:5], off offset:32
	v_or_b32_e32 v4, 3, v2
	v_ashrrev_i32_e32 v5, 31, v4
	v_lshlrev_b64 v[4:5], 6, v[4:5]
	v_lshl_add_u64 v[4:5], v[170:171], 0, v[4:5]
	global_load_dwordx4 v[120:123], v[4:5], off
	global_load_dwordx4 v[124:127], v[4:5], off offset:32
	v_or_b32_e32 v4, 4, v2
	v_or_b32_e32 v6, v4, v179
	v_ashrrev_i32_e32 v7, 31, v6
	v_ashrrev_i32_e32 v5, 31, v4
	v_lshlrev_b64 v[6:7], 11, v[6:7]
	v_lshlrev_b64 v[4:5], 6, v[4:5]
	v_lshl_add_u64 v[6:7], v[166:167], 0, v[6:7]
	v_lshl_add_u64 v[4:5], v[170:171], 0, v[4:5]
	global_load_dwordx4 v[64:67], v[6:7], off
	global_load_dwordx4 v[68:71], v[6:7], off offset:16
	global_load_dwordx4 v[72:75], v[6:7], off offset:32
	global_load_dwordx4 v[76:79], v[6:7], off offset:48
	global_load_dwordx4 v[80:83], v[4:5], off
	global_load_dwordx4 v[84:87], v[4:5], off offset:32
	v_or_b32_e32 v4, 5, v2
	v_ashrrev_i32_e32 v5, 31, v4
	v_lshlrev_b64 v[4:5], 6, v[4:5]
	v_lshl_add_u64 v[4:5], v[170:171], 0, v[4:5]
	global_load_dwordx4 v[88:91], v[4:5], off
	global_load_dwordx4 v[92:95], v[4:5], off offset:32
	v_or_b32_e32 v4, 6, v2
	v_or_b32_e32 v6, v4, v179
	v_ashrrev_i32_e32 v7, 31, v6
	v_lshlrev_b64 v[6:7], 11, v[6:7]
	v_or_b32_e32 v2, 7, v2
	v_lshl_add_u64 v[6:7], v[166:167], 0, v[6:7]
	v_ashrrev_i32_e32 v5, 31, v4
	v_ashrrev_i32_e32 v3, 31, v2
	global_load_dwordx4 v[32:35], v[6:7], off
	global_load_dwordx4 v[36:39], v[6:7], off offset:16
	global_load_dwordx4 v[40:43], v[6:7], off offset:32
	global_load_dwordx4 v[44:47], v[6:7], off offset:48
	v_lshlrev_b64 v[4:5], 6, v[4:5]
	v_lshlrev_b64 v[2:3], 6, v[2:3]
	v_lshl_add_u64 v[4:5], v[170:171], 0, v[4:5]
	v_lshl_add_u64 v[2:3], v[170:171], 0, v[2:3]
	global_load_dwordx4 v[48:51], v[4:5], off
	global_load_dwordx4 v[52:55], v[4:5], off offset:32
	global_load_dwordx4 v[56:59], v[2:3], off
	global_load_dwordx4 v[60:63], v[2:3], off offset:32
	s_mul_i32 s11, s11, s10
	s_sub_i32 s8, s8, s11
	s_lshl_b32 s10, s8, 8
	s_sub_i32 s8, s9, s10
	s_add_i32 s8, s8, 64
	s_min_i32 s11, s8, 0x100
	v_cmp_gt_i32_e64 s[8:9], s11, v180
	s_and_saveexec_b64 s[12:13], s[8:9]
	s_add_i32 s1, s10, s1
	v_add_u32_e32 v2, s1, v180
	v_ashrrev_i32_e32 v3, 31, v2
	v_lshlrev_b64 v[2:3], 7, v[2:3]
	v_lshl_add_u64 v[14:15], v[168:169], 0, v[2:3]
	global_load_dwordx4 v[2:5], v[14:15], off
	global_load_dwordx4 v[6:9], v[14:15], off offset:16
	global_load_dwordx4 v[10:13], v[14:15], off offset:32
	global_load_dwordx4 v[14:17], v[14:15], off offset:48
	s_or_b64 exec, exec, s[12:13]
	s_barrier
	s_and_saveexec_b64 s[12:13], s[8:9]
	s_cbranch_execz .LBB0_734
	s_waitcnt vmcnt(3)
	ds_write_b128 v185, v[2:5]
	s_waitcnt vmcnt(2)
	ds_write_b128 v185, v[6:9] offset:16
	s_waitcnt vmcnt(1)
	ds_write_b128 v185, v[10:13] offset:32
	s_waitcnt vmcnt(0)
	ds_write_b128 v185, v[14:17] offset:48

; #define PG8_STAGE(bufoff, gbase, voff) do { _Pragma("unroll") for (int _i = 0; _i < 2; ++_i) \
;         __builtin_amdgcn_global_load_lds((const unsigned*)((const char*)(gbase) + (voff)[_i]), (LAS unsigned*)(lds + (bufoff) + ldsw + _i * 8192), 16, 0, 0); } while (0)
; #define PG8_LDA(dst, b, h) do { _Pragma("unroll") for (int m = 0; m < 4; ++m) _Pragma("unroll") for (int k = 0; k < 2; ++k) dst[m][k] = *(const LAS bf16x8*)(lds + PG8_SA(b, h) + aoff + m * 2048 + k * 1024); } while (0)
; #define PG8_LDB(dst, b, h) do { _Pragma("unroll") for (int n = 0; n < 2; ++n) _Pragma("unroll") for (int k = 0; k < 2; ++k) dst[n][k] = *(const LAS bf16x8*)(lds + PG8_SB(b, h) + boff + n * 2048 + k * 1024); } while (0)
; #define PG8_MMA(ai, bj, At, Bt) do { __builtin_amdgcn_s_setprio(1); _Pragma("unroll") for (int m = 0; m < 4; ++m) _Pragma("unroll") for (int n = 0; n < 2; ++n) _Pragma("unroll") for (int k = 0; k < 2; ++k) \
;         acc[ai][bj][m][n] = __builtin_amdgcn_mfma_f32_16x16x32_bf16(Bt[n][k], At[m][k], acc[ai][bj][m][n], 0, 0, 0); __builtin_amdgcn_s_setprio(0); } while (0)
; #define PG8_WAIT_V(n) asm volatile("s_waitcnt vmcnt(" #n ")" ::: "memory")
; #define PG8_WAIT_L(n) asm volatile("s_waitcnt lgkmcnt(" #n ")" ::: "memory")
; template <class Epi>
; __device__ __forceinline__ void gemm_phase(const int TID, const int BID, LAS unsigned char* lds, const Gemm g, const StaticOrder& S, const Epi& E) {
;     ...
;         for (int t = 0; t < nt; t += 2) {
;             const bool last = (t == nt - 2);
;             const char* a1 = cA + (size_t)(t + 1) * kstep;
;             const char* a2 = last ? nA : cA + (size_t)(t + 2) * kstep; const char* b2 = last ? nB : cB + (size_t)(t + 2) * kstep;
;             const char* a3 = a2 + kstep; const char* b3 = b2 + kstep;
;             PG8_LDB(B0, 0, 0); PG8_SCHED; PG8_LDA(At, 0, 0); PG8_STAGE(PG8_SA(1, 1), a1 + hstepA, voffA);
;             PG8_WAIT_L(8); PG8_BAR; PG8_WAIT_L(0); PG8_MMA(0, 0, At, B0); PG8_BAR; PG8_SCHED;
;             PG8_LDB(B1, 0, 1); PG8_STAGE(PG8_SB(0, 0), b2, voffB);
;             PG8_BAR; PG8_WAIT_L(0); PG8_MMA(0, 1, At, B1); PG8_BAR;
;             PG8_LDA(At, 0, 1); PG8_STAGE(PG8_SA(0, 0), a2, voffA);
;             PG8_BAR; PG8_WAIT_L(0); PG8_MMA(1, 0, At, B0); PG8_BAR; PG8_SCHED;
;             PG8_STAGE(PG8_SB(0, 1), b2 + hstepB, voffB);
;             PG8_WAIT_V(6); PG8_BAR; PG8_MMA(1, 1, At, B1); PG8_BAR;
.LBB0_864:
	v_add_u32_e32 v36, s43, v172
	ds_read_b128 v[8:11], v36
	ds_read_b128 v[12:15], v36 offset:1024
	ds_read_b128 v[32:35], v36 offset:2048
	ds_read_b128 v[36:39], v36 offset:3072
	s_add_u32 s36, s34, 0xfff80080
	s_addc_u32 s37, s35, -1
	s_cmp_eq_u32 s31, 28
	s_cselect_b32 s39, s0, s37
	s_cselect_b32 s38, s1, s36
	s_cselect_b32 s37, s4, s29
	s_cselect_b32 s36, s21, s23
	v_lshl_add_u64 v[158:159], s[34:35], 0, v[150:151]
	s_add_i32 m0, s46, 0xc000
	ds_read_b128 v[154:157], v174
	ds_read_b128 v[176:179], v174 offset:1024
	ds_read_b128 v[180:183], v174 offset:2048
	ds_read_b128 v[196:199], v174 offset:3072
	ds_read_b128 v[208:211], v174 offset:4096
	ds_read_b128 v[212:215], v174 offset:5120
	ds_read_b128 v[216:219], v174 offset:6144
	ds_read_b128 v[220:223], v174 offset:7168
	global_load_lds_dwordx4 v[158:159], off
	s_add_i32 m0, s46, 0xe000
	v_lshl_add_u64 v[158:159], s[34:35], 0, v[152:153]
	global_load_lds_dwordx4 v[158:159], off
	s_waitcnt lgkmcnt(8)
	s_barrier
	s_waitcnt lgkmcnt(0)
	s_setprio 1
	v_mfma_f32_16x16x32_bf16 v[140:143], v[8:11], v[154:157], v[140:143]
	v_mfma_f32_16x16x32_bf16 v[136:139], v[32:35], v[154:157], v[136:139]
	v_mfma_f32_16x16x32_bf16 v[124:127], v[8:11], v[180:183], v[124:127]
	v_mfma_f32_16x16x32_bf16 v[120:123], v[32:35], v[180:183], v[120:123]
	v_mfma_f32_16x16x32_bf16 v[108:111], v[8:11], v[208:211], v[108:111]
	v_mfma_f32_16x16x32_bf16 v[104:107], v[32:35], v[208:211], v[104:107]
	v_mfma_f32_16x16x32_bf16 v[92:95], v[8:11], v[216:219], v[92:95]
	v_mfma_f32_16x16x32_bf16 v[88:91], v[32:35], v[216:219], v[88:91]
	v_mfma_f32_16x16x32_bf16 v[140:143], v[12:15], v[176:179], v[140:143]
	v_mfma_f32_16x16x32_bf16 v[136:139], v[36:39], v[176:179], v[136:139]
	v_mfma_f32_16x16x32_bf16 v[124:127], v[12:15], v[196:199], v[124:127]
	v_mfma_f32_16x16x32_bf16 v[120:123], v[36:39], v[196:199], v[120:123]
	v_mfma_f32_16x16x32_bf16 v[108:111], v[12:15], v[212:215], v[108:111]
	v_mfma_f32_16x16x32_bf16 v[104:107], v[36:39], v[212:215], v[104:107]
	v_mfma_f32_16x16x32_bf16 v[92:95], v[12:15], v[220:223], v[92:95]
	v_mfma_f32_16x16x32_bf16 v[88:91], v[36:39], v[220:223], v[88:91]
	s_setprio 0
	s_barrier
	v_add_u32_e32 v158, s48, v172
	s_mov_b32 m0, s44
	ds_read_b128 v[224:227], v158
	ds_read_b128 v[228:231], v158 offset:1024
	ds_read_b128 v[232:235], v158 offset:2048
	ds_read_b128 v[236:239], v158 offset:3072
	v_lshl_add_u64 v[158:159], s[36:37], 0, v[160:161]
	global_load_lds_dwordx4 v[158:159], off
	s_mov_b32 m0, s45
	v_lshl_add_u64 v[166:167], s[36:37], 0, v[148:149]
	global_load_lds_dwordx4 v[166:167], off
	s_barrier
	s_waitcnt lgkmcnt(0)
	s_setprio 1
	v_mfma_f32_16x16x32_bf16 v[132:135], v[224:227], v[154:157], v[132:135]
	v_mfma_f32_16x16x32_bf16 v[128:131], v[232:235], v[154:157], v[128:131]
	v_mfma_f32_16x16x32_bf16 v[116:119], v[224:227], v[180:183], v[116:119]
	v_mfma_f32_16x16x32_bf16 v[112:115], v[232:235], v[180:183], v[112:115]
	v_mfma_f32_16x16x32_bf16 v[100:103], v[224:227], v[208:211], v[100:103]
	v_mfma_f32_16x16x32_bf16 v[96:99], v[232:235], v[208:211], v[96:99]
	v_mfma_f32_16x16x32_bf16 v[84:87], v[224:227], v[216:219], v[84:87]
	v_mfma_f32_16x16x32_bf16 v[80:83], v[232:235], v[216:219], v[80:83]
	v_mfma_f32_16x16x32_bf16 v[132:135], v[228:231], v[176:179], v[132:135]
	v_mfma_f32_16x16x32_bf16 v[128:131], v[236:239], v[176:179], v[128:131]
	v_mfma_f32_16x16x32_bf16 v[116:119], v[228:231], v[196:199], v[116:119]
	v_mfma_f32_16x16x32_bf16 v[112:115], v[236:239], v[196:199], v[112:115]
	v_mfma_f32_16x16x32_bf16 v[100:103], v[228:231], v[212:215], v[100:103]
	v_mfma_f32_16x16x32_bf16 v[96:99], v[236:239], v[212:215], v[96:99]
	v_mfma_f32_16x16x32_bf16 v[84:87], v[228:231], v[220:223], v[84:87]
	v_mfma_f32_16x16x32_bf16 v[80:83], v[236:239], v[220:223], v[80:83]
	s_setprio 0
	s_mov_b32 m0, s46
	v_lshl_add_u64 v[170:171], s[38:39], 0, v[144:145]
	s_barrier
	ds_read_b128 v[154:157], v174 offset:16384
	ds_read_b128 v[176:179], v174 offset:17408
	ds_read_b128 v[180:183], v174 offset:18432
	ds_read_b128 v[196:199], v174 offset:19456
	ds_read_b128 v[208:211], v174 offset:20480
	ds_read_b128 v[212:215], v174 offset:21504
	ds_read_b128 v[216:219], v174 offset:22528
	ds_read_b128 v[220:223], v174 offset:23552
	global_load_lds_dwordx4 v[170:171], off
	s_mov_b32 m0, s47
	v_lshl_add_u64 v[184:185], s[38:39], 0, v[146:147]
	global_load_lds_dwordx4 v[184:185], off
	s_barrier
	s_waitcnt lgkmcnt(0)
	s_setprio 1
	v_mfma_f32_16x16x32_bf16 v[76:79], v[8:11], v[154:157], v[76:79]
	v_mfma_f32_16x16x32_bf16 v[72:75], v[32:35], v[154:157], v[72:75]
	v_mfma_f32_16x16x32_bf16 v[60:63], v[8:11], v[180:183], v[60:63]
	v_mfma_f32_16x16x32_bf16 v[56:59], v[32:35], v[180:183], v[56:59]
	v_mfma_f32_16x16x32_bf16 v[44:47], v[8:11], v[208:211], v[44:47]
	v_mfma_f32_16x16x32_bf16 v[40:43], v[32:35], v[208:211], v[40:43]
	v_mfma_f32_16x16x32_bf16 v[8:11], v[8:11], v[216:219], v[20:23]
	v_mfma_f32_16x16x32_bf16 v[76:79], v[12:15], v[176:179], v[76:79]
	v_mfma_f32_16x16x32_bf16 v[72:75], v[36:39], v[176:179], v[72:75]
	v_mfma_f32_16x16x32_bf16 v[60:63], v[12:15], v[196:199], v[60:63]
	v_mfma_f32_16x16x32_bf16 v[56:59], v[36:39], v[196:199], v[56:59]
	v_mfma_f32_16x16x32_bf16 v[44:47], v[12:15], v[212:215], v[44:47]
	v_mfma_f32_16x16x32_bf16 v[40:43], v[36:39], v[212:215], v[40:43]
	v_mfma_f32_16x16x32_bf16 v[8:11], v[12:15], v[220:223], v[8:11]
	v_mfma_f32_16x16x32_bf16 v[12:15], v[32:35], v[216:219], v[16:19]
	v_mfma_f32_16x16x32_bf16 v[12:15], v[36:39], v[220:223], v[12:15]
	s_setprio 0
	s_barrier
; #define PG8_STAGE(bufoff, gbase, voff) do { _Pragma("unroll") for (int _i = 0; _i < 2; ++_i) \
;         __builtin_amdgcn_global_load_lds((const unsigned*)((const char*)(gbase) + (voff)[_i]), (LAS unsigned*)(lds + (bufoff) + ldsw + _i * 8192), 16, 0, 0); } while (0)
; #define PG8_LDA(dst, b, h) do { _Pragma("unroll") for (int m = 0; m < 4; ++m) _Pragma("unroll") for (int k = 0; k < 2; ++k) dst[m][k] = *(const LAS bf16x8*)(lds + PG8_SA(b, h) + aoff + m * 2048 + k * 1024); } while (0)
; #define PG8_LDB(dst, b, h) do { _Pragma("unroll") for (int n = 0; n < 2; ++n) _Pragma("unroll") for (int k = 0; k < 2; ++k) dst[n][k] = *(const LAS bf16x8*)(lds + PG8_SB(b, h) + boff + n * 2048 + k * 1024); } while (0)
; #define PG8_MMA(ai, bj, At, Bt) do { __builtin_amdgcn_s_setprio(1); _Pragma("unroll") for (int m = 0; m < 4; ++m) _Pragma("unroll") for (int n = 0; n < 2; ++n) _Pragma("unroll") for (int k = 0; k < 2; ++k) \
;         acc[ai][bj][m][n] = __builtin_amdgcn_mfma_f32_16x16x32_bf16(Bt[n][k], At[m][k], acc[ai][bj][m][n], 0, 0, 0); __builtin_amdgcn_s_setprio(0); } while (0)
; #define PG8_WAIT_V(n) asm volatile("s_waitcnt vmcnt(" #n ")" ::: "memory")
; #define PG8_WAIT_L(n) asm volatile("s_waitcnt lgkmcnt(" #n ")" ::: "memory")
; #define PG8_BAR __builtin_amdgcn_s_barrier()
; #define PG8_SCHED __builtin_amdgcn_sched_barrier(0)
; template <class Epi>
; __device__ __forceinline__ void gemm_phase(const int TID, const int BID, LAS unsigned char* lds, const Gemm g, const StaticOrder& S, const Epi& E) {
;     ...
;             PG8_STAGE(PG8_SB(0, 1), b2 + hstepB, voffB);
;             PG8_WAIT_V(6); PG8_BAR; PG8_MMA(1, 1, At, B1); PG8_BAR;
;             PG8_LDB(B0, 1, 0); PG8_SCHED; PG8_LDA(At, 1, 0); PG8_STAGE(PG8_SA(0, 1), a2 + hstepA, voffA);
;             PG8_WAIT_L(8); PG8_BAR; PG8_WAIT_L(0); PG8_MMA(0, 0, At, B0); PG8_BAR; PG8_SCHED;
;             PG8_LDB(B1, 1, 1); PG8_STAGE(PG8_SB(1, 0), b3, voffB);
;             PG8_BAR; PG8_WAIT_L(0); PG8_MMA(0, 1, At, B1); PG8_BAR;
;             PG8_LDA(At, 1, 1); PG8_STAGE(PG8_SA(1, 0), a3, voffA);
;             PG8_BAR; PG8_WAIT_L(0); PG8_MMA(1, 0, At, B0); PG8_BAR; PG8_SCHED;
;             PG8_STAGE(PG8_SB(1, 1), b3 + hstepB, voffB);
;             PG8_WAIT_V(6); PG8_BAR; PG8_MMA(1, 1, At, B1); PG8_BAR;
	s_add_u32 s66, s36, 0x80000
	s_addc_u32 s67, s37, 0
	s_mov_b32 m0, s49
	v_lshl_add_u64 v[16:17], s[66:67], 0, v[160:161]
	global_load_lds_dwordx4 v[16:17], off
	s_mov_b32 m0, s50
	v_lshl_add_u64 v[16:17], s[66:67], 0, v[148:149]
	global_load_lds_dwordx4 v[16:17], off
	s_waitcnt vmcnt(6)
	s_barrier
	s_setprio 1
	v_mfma_f32_16x16x32_bf16 v[16:19], v[224:227], v[154:157], v[68:71]
	v_mfma_f32_16x16x32_bf16 v[32:35], v[228:231], v[176:179], v[16:19]
	v_mfma_f32_16x16x32_bf16 v[16:19], v[232:235], v[154:157], v[64:67]
	v_mfma_f32_16x16x32_bf16 v[36:39], v[236:239], v[176:179], v[16:19]
	v_mfma_f32_16x16x32_bf16 v[16:19], v[224:227], v[180:183], v[52:55]
	v_mfma_f32_16x16x32_bf16 v[52:55], v[228:231], v[196:199], v[16:19]
	v_mfma_f32_16x16x32_bf16 v[16:19], v[232:235], v[180:183], v[48:51]
	v_mfma_f32_16x16x32_bf16 v[48:51], v[236:239], v[196:199], v[16:19]
	v_mfma_f32_16x16x32_bf16 v[16:19], v[224:227], v[208:211], v[28:31]
	v_mfma_f32_16x16x32_bf16 v[28:31], v[228:231], v[212:215], v[16:19]
	v_mfma_f32_16x16x32_bf16 v[16:19], v[232:235], v[208:211], v[24:27]
	v_mfma_f32_16x16x32_bf16 v[4:7], v[224:227], v[216:219], v[4:7]
	v_mfma_f32_16x16x32_bf16 v[0:3], v[232:235], v[216:219], v[0:3]
	v_mfma_f32_16x16x32_bf16 v[24:27], v[236:239], v[212:215], v[16:19]
	v_mfma_f32_16x16x32_bf16 v[4:7], v[228:231], v[220:223], v[4:7]
	v_mfma_f32_16x16x32_bf16 v[0:3], v[236:239], v[220:223], v[0:3]
	s_setprio 0
	v_add_u32_e32 v68, s53, v172
	s_barrier
	ds_read_b128 v[16:19], v68
	ds_read_b128 v[20:23], v68 offset:1024
	ds_read_b128 v[64:67], v68 offset:2048
	ds_read_b128 v[68:71], v68 offset:3072
	s_add_u32 s38, s38, 0x80000
	s_addc_u32 s39, s39, 0
	s_mov_b32 m0, s51
	v_lshl_add_u64 v[200:201], s[38:39], 0, v[144:145]
	ds_read_b128 v[154:157], v174 offset:32768
	ds_read_b128 v[176:179], v174 offset:33792
	ds_read_b128 v[180:183], v174 offset:34816
	ds_read_b128 v[196:199], v174 offset:35840
	ds_read_b128 v[208:211], v174 offset:36864
	ds_read_b128 v[212:215], v174 offset:37888
	ds_read_b128 v[216:219], v174 offset:38912
	ds_read_b128 v[220:223], v174 offset:39936
	global_load_lds_dwordx4 v[200:201], off
	s_mov_b32 m0, s52
	v_lshl_add_u64 v[200:201], s[38:39], 0, v[146:147]
	global_load_lds_dwordx4 v[200:201], off
	s_waitcnt lgkmcnt(8)
	s_barrier
	s_waitcnt lgkmcnt(0)
	s_setprio 1
	v_mfma_f32_16x16x32_bf16 v[140:143], v[16:19], v[154:157], v[140:143]
	v_mfma_f32_16x16x32_bf16 v[136:139], v[64:67], v[154:157], v[136:139]
	v_mfma_f32_16x16x32_bf16 v[124:127], v[16:19], v[180:183], v[124:127]
	v_mfma_f32_16x16x32_bf16 v[120:123], v[64:67], v[180:183], v[120:123]
	v_mfma_f32_16x16x32_bf16 v[108:111], v[16:19], v[208:211], v[108:111]
	v_mfma_f32_16x16x32_bf16 v[104:107], v[64:67], v[208:211], v[104:107]
	v_mfma_f32_16x16x32_bf16 v[92:95], v[16:19], v[216:219], v[92:95]
	v_mfma_f32_16x16x32_bf16 v[88:91], v[64:67], v[216:219], v[88:91]
	v_mfma_f32_16x16x32_bf16 v[140:143], v[20:23], v[176:179], v[140:143]
	v_mfma_f32_16x16x32_bf16 v[136:139], v[68:71], v[176:179], v[136:139]
	v_mfma_f32_16x16x32_bf16 v[124:127], v[20:23], v[196:199], v[124:127]
	v_mfma_f32_16x16x32_bf16 v[120:123], v[68:71], v[196:199], v[120:123]
	v_mfma_f32_16x16x32_bf16 v[108:111], v[20:23], v[212:215], v[108:111]
	v_mfma_f32_16x16x32_bf16 v[104:107], v[68:71], v[212:215], v[104:107]
	v_mfma_f32_16x16x32_bf16 v[92:95], v[20:23], v[220:223], v[92:95]
	v_mfma_f32_16x16x32_bf16 v[88:91], v[68:71], v[220:223], v[88:91]
	s_setprio 0
	s_barrier
	s_mov_b32 m0, s54
	v_add_u32_e32 v168, s58, v172
	v_lshl_add_u64 v[158:159], v[158:159], 0, s[90:91]
	ds_read_b128 v[224:227], v168
	ds_read_b128 v[228:231], v168 offset:1024
	ds_read_b128 v[232:235], v168 offset:2048
	ds_read_b128 v[236:239], v168 offset:3072
	global_load_lds_dwordx4 v[158:159], off
	s_mov_b32 m0, s55
	v_lshl_add_u64 v[158:159], v[166:167], 0, s[90:91]
	global_load_lds_dwordx4 v[158:159], off
	s_barrier
	s_waitcnt lgkmcnt(0)
	s_setprio 1
	v_mfma_f32_16x16x32_bf16 v[132:135], v[224:227], v[154:157], v[132:135]
	v_mfma_f32_16x16x32_bf16 v[128:131], v[232:235], v[154:157], v[128:131]
	v_mfma_f32_16x16x32_bf16 v[116:119], v[224:227], v[180:183], v[116:119]
	v_mfma_f32_16x16x32_bf16 v[112:115], v[232:235], v[180:183], v[112:115]
	v_mfma_f32_16x16x32_bf16 v[100:103], v[224:227], v[208:211], v[100:103]
	v_mfma_f32_16x16x32_bf16 v[96:99], v[232:235], v[208:211], v[96:99]
	v_mfma_f32_16x16x32_bf16 v[84:87], v[224:227], v[216:219], v[84:87]
	v_mfma_f32_16x16x32_bf16 v[80:83], v[232:235], v[216:219], v[80:83]
	v_mfma_f32_16x16x32_bf16 v[132:135], v[228:231], v[176:179], v[132:135]
	v_mfma_f32_16x16x32_bf16 v[128:131], v[236:239], v[176:179], v[128:131]
	v_mfma_f32_16x16x32_bf16 v[116:119], v[228:231], v[196:199], v[116:119]
	v_mfma_f32_16x16x32_bf16 v[112:115], v[236:239], v[196:199], v[112:115]
	v_mfma_f32_16x16x32_bf16 v[100:103], v[228:231], v[212:215], v[100:103]
	v_mfma_f32_16x16x32_bf16 v[96:99], v[236:239], v[212:215], v[96:99]
	v_mfma_f32_16x16x32_bf16 v[84:87], v[228:231], v[220:223], v[84:87]
	v_mfma_f32_16x16x32_bf16 v[80:83], v[236:239], v[220:223], v[80:83]
	s_setprio 0
	s_mov_b32 m0, s56
	v_lshl_add_u64 v[158:159], v[170:171], 0, s[90:91]
	s_barrier
	ds_read_b128 v[154:157], v174 offset:49152
	ds_read_b128 v[176:179], v174 offset:50176
	ds_read_b128 v[180:183], v174 offset:51200
	ds_read_b128 v[196:199], v174 offset:52224
	ds_read_b128 v[208:211], v174 offset:53248
	ds_read_b128 v[212:215], v174 offset:54272
	ds_read_b128 v[216:219], v174 offset:55296
	ds_read_b128 v[220:223], v174 offset:56320
	global_load_lds_dwordx4 v[158:159], off
	s_mov_b32 m0, s57
	v_lshl_add_u64 v[158:159], v[184:185], 0, s[90:91]
	global_load_lds_dwordx4 v[158:159], off
	s_barrier
; template <class Epi>
; __device__ __forceinline__ void gemm_phase(const int TID, const int BID, LAS unsigned char* lds, const Gemm g, const StaticOrder& S, const Epi& E) {
;     ...
;         for (int t = 0; t < nt; t += 2) {
;             const bool last = (t == nt - 2);
;             const char* a1 = cA + (size_t)(t + 1) * kstep;
;             const char* a2 = last ? nA : cA + (size_t)(t + 2) * kstep; const char* b2 = last ? nB : cB + (size_t)(t + 2) * kstep;
;             const char* a3 = a2 + kstep; const char* b3 = b2 + kstep;
;             PG8_LDB(B0, 0, 0); PG8_SCHED; PG8_LDA(At, 0, 0); PG8_STAGE(PG8_SA(1, 1), a1 + hstepA, voffA);
;             PG8_WAIT_L(8); PG8_BAR; PG8_WAIT_L(0); PG8_MMA(0, 0, At, B0); PG8_BAR; PG8_SCHED;
;             PG8_LDB(B1, 0, 1); PG8_STAGE(PG8_SB(0, 0), b2, voffB);
;             PG8_BAR; PG8_WAIT_L(0); PG8_MMA(0, 1, At, B1); PG8_BAR;
;             PG8_LDA(At, 0, 1); PG8_STAGE(PG8_SA(0, 0), a2, voffA);
;             PG8_BAR; PG8_WAIT_L(0); PG8_MMA(1, 0, At, B0); PG8_BAR; PG8_SCHED;
;             PG8_STAGE(PG8_SB(0, 1), b2 + hstepB, voffB);
;             PG8_WAIT_V(6); PG8_BAR; PG8_MMA(1, 1, At, B1); PG8_BAR;
;             PG8_LDB(B0, 1, 0); PG8_SCHED; PG8_LDA(At, 1, 0); PG8_STAGE(PG8_SA(0, 1), a2 + hstepA, voffA);
;             PG8_WAIT_L(8); PG8_BAR; PG8_WAIT_L(0); PG8_MMA(0, 0, At, B0); PG8_BAR; PG8_SCHED;
;             PG8_LDB(B1, 1, 1); PG8_STAGE(PG8_SB(1, 0), b3, voffB);
;             PG8_BAR; PG8_WAIT_L(0); PG8_MMA(0, 1, At, B1); PG8_BAR;
;             PG8_LDA(At, 1, 1); PG8_STAGE(PG8_SA(1, 0), a3, voffA);
;             PG8_BAR; PG8_WAIT_L(0); PG8_MMA(1, 0, At, B0); PG8_BAR; PG8_SCHED;
;             PG8_STAGE(PG8_SB(1, 1), b3 + hstepB, voffB);
;             PG8_WAIT_V(6); PG8_BAR; PG8_MMA(1, 1, At, B1); PG8_BAR;
;         }
;     __device__ __forceinline__ void operator()(const f32x4 (&acc)[2][2][4][2], const Unit& u, int wr, int wc, int fr, int fq) const {
;         const int row0 = u.pm * BM + wr * 64 + fr, col0 = u.pn * BM + wc * 32 + 8 * fq;
;         f32x4 bv[2][2];
; #pragma unroll
;         for (int bj = 0; bj < 2; ++bj)
; #pragma unroll
;             for (int n = 0; n < 2; ++n) bv[bj][n] = *(const f32x4*)(bias + col0 + bj * HALF + 4 * n);
;         const bool isv = u.pn >= 8;
; #pragma unroll
;         for (int ai = 0; ai < 2; ++ai)
; #pragma unroll
;             for (int m = 0; m < 4; ++m) {
	s_waitcnt lgkmcnt(0)
	s_setprio 1
	v_mfma_f32_16x16x32_bf16 v[76:79], v[16:19], v[154:157], v[76:79]
	v_mfma_f32_16x16x32_bf16 v[60:63], v[16:19], v[180:183], v[60:63]
	v_mfma_f32_16x16x32_bf16 v[44:47], v[16:19], v[208:211], v[44:47]
	v_mfma_f32_16x16x32_bf16 v[8:11], v[16:19], v[216:219], v[8:11]
	v_mfma_f32_16x16x32_bf16 v[76:79], v[20:23], v[176:179], v[76:79]
	v_mfma_f32_16x16x32_bf16 v[72:75], v[64:67], v[154:157], v[72:75]
	v_mfma_f32_16x16x32_bf16 v[60:63], v[20:23], v[196:199], v[60:63]
	v_mfma_f32_16x16x32_bf16 v[56:59], v[64:67], v[180:183], v[56:59]
	v_mfma_f32_16x16x32_bf16 v[44:47], v[20:23], v[212:215], v[44:47]
	v_mfma_f32_16x16x32_bf16 v[40:43], v[64:67], v[208:211], v[40:43]
	v_mfma_f32_16x16x32_bf16 v[20:23], v[20:23], v[220:223], v[8:11]
	v_mfma_f32_16x16x32_bf16 v[8:11], v[64:67], v[216:219], v[12:15]
	v_mfma_f32_16x16x32_bf16 v[72:75], v[68:71], v[176:179], v[72:75]
	v_mfma_f32_16x16x32_bf16 v[56:59], v[68:71], v[196:199], v[56:59]
	v_mfma_f32_16x16x32_bf16 v[40:43], v[68:71], v[212:215], v[40:43]
	v_mfma_f32_16x16x32_bf16 v[16:19], v[68:71], v[220:223], v[8:11]
	s_setprio 0
	s_barrier
	s_add_u32 s36, s36, 0x80080
	s_addc_u32 s37, s37, 0
	s_mov_b32 m0, s59
	v_lshl_add_u64 v[8:9], s[36:37], 0, v[160:161]
	global_load_lds_dwordx4 v[8:9], off
	s_mov_b32 m0, s60
	v_lshl_add_u64 v[8:9], s[36:37], 0, v[148:149]
	global_load_lds_dwordx4 v[8:9], off
	s_waitcnt vmcnt(6)
	s_barrier
	s_setprio 1
	v_mfma_f32_16x16x32_bf16 v[8:11], v[224:227], v[154:157], v[32:35]
	v_mfma_f32_16x16x32_bf16 v[68:71], v[228:231], v[176:179], v[8:11]
	v_mfma_f32_16x16x32_bf16 v[8:11], v[232:235], v[154:157], v[36:39]
	v_mfma_f32_16x16x32_bf16 v[64:67], v[236:239], v[176:179], v[8:11]
	v_mfma_f32_16x16x32_bf16 v[8:11], v[224:227], v[180:183], v[52:55]
	v_mfma_f32_16x16x32_bf16 v[52:55], v[228:231], v[196:199], v[8:11]
	v_mfma_f32_16x16x32_bf16 v[8:11], v[232:235], v[180:183], v[48:51]
	v_mfma_f32_16x16x32_bf16 v[48:51], v[236:239], v[196:199], v[8:11]
	v_mfma_f32_16x16x32_bf16 v[8:11], v[224:227], v[208:211], v[28:31]
	v_mfma_f32_16x16x32_bf16 v[28:31], v[228:231], v[212:215], v[8:11]
	v_mfma_f32_16x16x32_bf16 v[8:11], v[232:235], v[208:211], v[24:27]
	v_mfma_f32_16x16x32_bf16 v[4:7], v[224:227], v[216:219], v[4:7]
	v_mfma_f32_16x16x32_bf16 v[0:3], v[232:235], v[216:219], v[0:3]
	v_mfma_f32_16x16x32_bf16 v[24:27], v[236:239], v[212:215], v[8:11]
	v_mfma_f32_16x16x32_bf16 v[4:7], v[228:231], v[220:223], v[4:7]
	v_mfma_f32_16x16x32_bf16 v[0:3], v[236:239], v[220:223], v[0:3]
	s_setprio 0
	s_add_i32 s31, s31, 2
	s_add_u32 s34, s34, 0x100
	s_addc_u32 s35, s35, 0
	s_add_u32 s23, s23, 0x100
	s_addc_u32 s29, s29, 0
	s_cmp_gt_u32 s31, 29
	s_cbranch_scc0 .Lrot_864
	s_barrier
	v_readlane_b32 s0, v254, 32
	v_readlane_b32 s1, v254, 33
	s_load_dwordx2 s[0:1], s[0:1], 0x50
	v_lshl_or_b32 v154, s30, 8, v173
	v_lshl_add_u32 v156, s28, 8, v169
	v_ashrrev_i32_e32 v155, 31, v154
	v_ashrrev_i32_e32 v157, 31, v156
	s_waitcnt lgkmcnt(0)
	v_lshl_add_u64 v[12:13], v[154:155], 2, s[0:1]
	v_lshl_add_u64 v[158:159], v[156:157], 3, s[16:17]
	global_load_dwordx4 v[32:35], v[12:13], off offset:16
	global_load_dwordx4 v[36:39], v[12:13], off
	global_load_dwordx4 v[8:11], v[12:13], off offset:528
	global_load_dwordx4 v[12:15], v[12:13], off offset:512
	s_cmp_gt_i32 s30, 7
	global_load_dwordx2 v[166:167], v[158:159], off
	global_load_dwordx2 v[208:209], v[158:159], off offset:128
	global_load_dwordx2 v[210:211], v[158:159], off offset:256
	global_load_dwordx2 v[212:213], v[158:159], off offset:384
	global_load_dwordx2 v[214:215], v[158:159], off offset:1024
	global_load_dwordx2 v[216:217], v[158:159], off offset:1152
	global_load_dwordx2 v[218:219], v[158:159], off offset:1280
	global_load_dwordx2 v[220:221], v[158:159], off offset:1408
	s_mov_b32 s30, 0xbf38aa3b
	s_cselect_b64 s[0:1], -1, 0
	s_and_b64 s[28:29], s[8:9], s[0:1]
	s_mov_b32 s0, 0xbe11a98e
	s_mov_b32 s4, 0x3e027906
	s_waitcnt vmcnt(0)
	v_cvt_f64_u32_e32 v[170:171], v167
	v_ldexp_f64 v[170:171], v[170:171], 32
	v_cvt_f64_u32_e32 v[166:167], v166
	v_add_f64 v[166:167], v[170:171], v[166:167]
	v_ldexp_f64 v[166:167], v[166:167], s93
	v_cvt_f32_f64_e32 v166, v[166:167]
	v_fmamk_f32 v166, v166, 0x3a000000, v189
	v_cmp_gt_f32_e32 vcc, s78, v166
	v_mul_f32_e32 v167, 0x4b800000, v166
	s_nop 0
	v_cndmask_b32_e32 v166, v166, v167, vcc
	v_rsq_f32_e32 v166, v166
	s_nop 0
	v_mul_f32_e32 v167, 0x45800000, v166
	v_cndmask_b32_e32 v168, v166, v167, vcc
	v_pk_fma_f32 v[170:171], v[140:141], v[168:169], v[36:37] op_sel_hi:[1,0,1]
	v_pk_fma_f32 v[140:141], v[136:137], v[168:169], v[32:33] op_sel_hi:[1,0,1]
	v_and_b32_e32 v137, 0x7fffffff, v171
	v_and_b32_e32 v136, 0x7fffffff, v170
	v_pk_fma_f32 v[136:137], v[136:137], s[64:65], 1.0 op_sel_hi:[1,0,0]
	v_pk_mul_f32 v[180:181], v[170:171], v[170:171]
	v_rcp_f32_e32 v176, v136
	v_rcp_f32_e32 v177, v137
	v_mov_b64_e32 v[136:137], s[80:81]
	v_pk_mul_f32 v[180:181], v[180:181], s[30:31] op_sel_hi:[1,0]
	v_cmp_gt_f32_e32 vcc, 0, v170
	v_pk_fma_f32 v[178:179], v[176:177], s[74:75], v[136:137] op_sel_hi:[1,0,0]
	v_exp_f32_e32 v180, v180
	v_pk_fma_f32 v[178:179], v[176:177], v[178:179], s[86:87] op_sel_hi:[1,1,0]
	v_exp_f32_e32 v181, v181
	v_pk_fma_f32 v[178:179], v[176:177], v[178:179], s[0:1] op_sel_hi:[1,1,0]
	v_pk_fma_f32 v[142:143], v[142:143], v[168:169], v[38:39] op_sel_hi:[1,0,1]
	v_pk_fma_f32 v[178:179], v[176:177], v[178:179], s[4:5] op_sel_hi:[1,1,0]
	v_pk_fma_f32 v[138:139], v[138:139], v[168:169], v[34:35] op_sel_hi:[1,0,1]
	v_pk_mul_f32 v[176:177], v[176:177], v[178:179]
	v_pk_mul_f32 v[178:179], v[142:143], v[142:143]
	v_pk_mul_f32 v[176:177], v[180:181], v[176:177]
; __device__ __forceinline__ unsigned cvt_pk_bf16(float lo, float hi) { unsigned r; asm volatile("v_cvt_pk_bf16_f32 %0, %1, %2" : "=v"(r) : "v"(lo), "v"(hi)); return r; }
; __device__ __forceinline__ float rinv_st(stat_t s, float invn) { return rsqrtf((float)((double)s * (1.0 / 4294967296.0)) * invn + 1e-6f); }
; __device__ __forceinline__ f32x2 gelu_pk(f32x2 v) {
;     const f32x2 av = __builtin_elementwise_abs(v), d = av * 0.2316418882f + 1.0f;
;     f32x2 t; t.x = __builtin_amdgcn_rcpf(d.x); t.y = __builtin_amdgcn_rcpf(d.y);
;     f32x2 q = t * 0.5307027145f + (-0.7265760135f); q = q * t + 0.7107068705f; q = q * t + (-0.142248368f); q = q * t + 0.127414796f; q = q * t;
;     const f32x2 s = (v * v) * (-0.72134752044f);
;     f32x2 e; e.x = __builtin_amdgcn_exp2f(s.x); e.y = __builtin_amdgcn_exp2f(s.y);
;     const f32x2 m = v * (q * e), r = v - m;
;     f32x2 o; o.x = v.x < 0.f ? m.x : r.x; o.y = v.y < 0.f ? m.y : r.y; return o;
; }
;     __device__ __forceinline__ void operator()(const f32x4 (&acc)[2][2][4][2], const Unit& u, int wr, int wc, int fr, int fq) const {
;     ...
;                 const int row = row0 + ai * HALF + m * 16; const float r = rinv_st(stats[row], 1.0f / 2048.0f);
;                 bf16_t* rowp = uv + (size_t)row * 4096 + col0; float ss = 0.f;
; #pragma unroll
;                 for (int bj = 0; bj < 2; ++bj) {
;                     const f32x4 v0 = acc[ai][bj][m][0] * r + bv[bj][0], v1 = acc[ai][bj][m][1] * r + bv[bj][1];
;                     const f32x2 a = gelu_pk((f32x2){v0[0], v0[1]}), b = gelu_pk((f32x2){v0[2], v0[3]}), c = gelu_pk((f32x2){v1[0], v1[1]}), d = gelu_pk((f32x2){v1[2], v1[3]});
;                     ss += a.x * a.x + a.y * a.y + b.x * b.x + b.y * b.y + c.x * c.x + c.y * c.y + d.x * d.x + d.y * d.y;
;                     u32x4 w; w.x = cvt_pk_bf16(a.x, a.y); w.y = cvt_pk_bf16(b.x, b.y); w.z = cvt_pk_bf16(c.x, c.y); w.w = cvt_pk_bf16(d.x, d.y);
;                     *(u32x4*)(rowp + bj * HALF) = w;
	v_pk_mul_f32 v[178:179], v[178:179], s[30:31] op_sel_hi:[1,0]
	v_pk_mul_f32 v[180:181], v[170:171], v[176:177]
	v_pk_fma_f32 v[176:177], v[170:171], v[176:177], v[170:171] neg_lo:[1,0,0] neg_hi:[1,0,0]
	v_exp_f32_e32 v178, v178
	v_cndmask_b32_e32 v170, v176, v180, vcc
	v_cmp_gt_f32_e32 vcc, 0, v171
	v_and_b32_e32 v176, 0x7fffffff, v142
	v_exp_f32_e32 v179, v179
	v_cndmask_b32_e32 v171, v177, v181, vcc
	v_and_b32_e32 v177, 0x7fffffff, v143
	v_pk_fma_f32 v[176:177], v[176:177], s[64:65], 1.0 op_sel_hi:[1,0,0]
	v_cmp_gt_f32_e32 vcc, 0, v142
	v_rcp_f32_e32 v176, v176
	v_rcp_f32_e32 v177, v177
	v_lshlrev_b64 v[166:167], 13, v[156:157]
	v_lshl_add_u64 v[166:167], s[14:15], 0, v[166:167]
	v_lshl_add_u64 v[166:167], v[154:155], 1, v[166:167]
	v_pk_fma_f32 v[180:181], v[176:177], s[74:75], v[136:137] op_sel_hi:[1,0,0]
	v_pk_fma_f32 v[132:133], v[132:133], v[168:169], v[12:13] op_sel_hi:[1,0,1]
	v_pk_fma_f32 v[180:181], v[176:177], v[180:181], s[86:87] op_sel_hi:[1,1,0]
	v_pk_fma_f32 v[134:135], v[134:135], v[168:169], v[14:15] op_sel_hi:[1,0,1]
	v_pk_fma_f32 v[180:181], v[176:177], v[180:181], s[0:1] op_sel_hi:[1,1,0]
	v_pk_fma_f32 v[128:129], v[128:129], v[168:169], v[8:9] op_sel_hi:[1,0,1]
	v_pk_fma_f32 v[180:181], v[176:177], v[180:181], s[4:5] op_sel_hi:[1,1,0]
	v_pk_fma_f32 v[130:131], v[130:131], v[168:169], v[10:11] op_sel_hi:[1,0,1]
	v_pk_mul_f32 v[176:177], v[176:177], v[180:181]
	s_nop 0
	v_pk_mul_f32 v[176:177], v[178:179], v[176:177]
	s_nop 0
	v_pk_mul_f32 v[178:179], v[142:143], v[176:177]
	v_pk_fma_f32 v[176:177], v[142:143], v[176:177], v[142:143] neg_lo:[1,0,0] neg_hi:[1,0,0]
	v_and_b32_e32 v142, 0x7fffffff, v140
	v_cndmask_b32_e32 v175, v176, v178, vcc
	v_cmp_gt_f32_e32 vcc, 0, v143
	v_and_b32_e32 v143, 0x7fffffff, v141
	v_pk_fma_f32 v[142:143], v[142:143], s[64:65], 1.0 op_sel_hi:[1,0,0]
	v_cndmask_b32_e32 v180, v177, v179, vcc
	v_rcp_f32_e32 v142, v142
	v_rcp_f32_e32 v143, v143
	v_pk_mul_f32 v[178:179], v[140:141], v[140:141]
	v_cmp_gt_f32_e32 vcc, 0, v140
	v_pk_mul_f32 v[178:179], v[178:179], s[30:31] op_sel_hi:[1,0]
	v_pk_fma_f32 v[176:177], v[142:143], s[74:75], v[136:137] op_sel_hi:[1,0,0]
	v_exp_f32_e32 v178, v178
	v_pk_fma_f32 v[176:177], v[142:143], v[176:177], s[86:87] op_sel_hi:[1,1,0]
	v_exp_f32_e32 v179, v179
	v_pk_fma_f32 v[176:177], v[142:143], v[176:177], s[0:1] op_sel_hi:[1,1,0]
	s_nop 0
	v_pk_fma_f32 v[176:177], v[142:143], v[176:177], s[4:5] op_sel_hi:[1,1,0]
	s_nop 0
	v_pk_mul_f32 v[142:143], v[142:143], v[176:177]
	v_pk_mul_f32 v[176:177], v[138:139], v[138:139]
	v_pk_mul_f32 v[142:143], v[178:179], v[142:143]
	s_nop 0
	v_pk_mul_f32 v[178:179], v[140:141], v[142:143]
	v_pk_fma_f32 v[142:143], v[140:141], v[142:143], v[140:141] neg_lo:[1,0,0] neg_hi:[1,0,0]
	v_and_b32_e32 v140, 0x7fffffff, v138
	v_cndmask_b32_e32 v178, v142, v178, vcc
	v_cmp_gt_f32_e32 vcc, 0, v141
	v_and_b32_e32 v141, 0x7fffffff, v139
	v_pk_fma_f32 v[140:141], v[140:141], s[64:65], 1.0 op_sel_hi:[1,0,0]
	v_cndmask_b32_e32 v179, v143, v179, vcc
	v_rcp_f32_e32 v140, v140
	v_rcp_f32_e32 v141, v141
	v_cmp_gt_f32_e32 vcc, 0, v138
	v_pk_fma_f32 v[142:143], v[140:141], s[74:75], v[136:137] op_sel_hi:[1,0,0]
	s_nop 0
	v_pk_fma_f32 v[142:143], v[140:141], v[142:143], s[86:87] op_sel_hi:[1,1,0]
	s_nop 0
	v_pk_fma_f32 v[142:143], v[140:141], v[142:143], s[0:1] op_sel_hi:[1,1,0]
	s_nop 0
	v_pk_fma_f32 v[142:143], v[140:141], v[142:143], s[4:5] op_sel_hi:[1,1,0]
	s_nop 0
	v_pk_mul_f32 v[140:141], v[140:141], v[142:143]
	v_pk_mul_f32 v[142:143], v[176:177], s[30:31] op_sel_hi:[1,0]
	v_mul_f32_e32 v176, v171, v171
	v_exp_f32_e32 v142, v142
	v_exp_f32_e32 v143, v143
	v_fmac_f32_e32 v176, v170, v170
	v_fmac_f32_e32 v176, v175, v175
	v_fmac_f32_e32 v176, v180, v180
	v_pk_mul_f32 v[140:141], v[142:143], v[140:141]
	v_fmac_f32_e32 v176, v178, v178
	v_pk_mul_f32 v[142:143], v[138:139], v[140:141]
	v_pk_fma_f32 v[140:141], v[138:139], v[140:141], v[138:139] neg_lo:[1,0,0] neg_hi:[1,0,0]
	v_fmac_f32_e32 v176, v179, v179
	v_cndmask_b32_e32 v142, v140, v142, vcc
	v_cmp_gt_f32_e32 vcc, 0, v139
	v_fmac_f32_e32 v176, v142, v142
	v_cvt_pk_bf16_f32 v138, v170, v171
	v_cvt_pk_bf16_f32 v139, v175, v180
	v_cvt_pk_bf16_f32 v140, v178, v179
	s_nop 0
	v_cndmask_b32_e32 v141, v141, v143, vcc
	v_fmac_f32_e32 v176, v141, v141
	v_cvt_pk_bf16_f32 v141, v142, v141
	global_store_dwordx4 v[166:167], v[138:141], off
	v_pk_mul_f32 v[142:143], v[132:133], v[132:133]
	v_cmp_gt_f32_e32 vcc, 0, v132
	v_and_b32_e32 v139, 0x7fffffff, v133
	v_and_b32_e32 v138, 0x7fffffff, v132
	v_pk_fma_f32 v[138:139], v[138:139], s[64:65], 1.0 op_sel_hi:[1,0,0]
	v_pk_mul_f32 v[142:143], v[142:143], s[30:31] op_sel_hi:[1,0]
	v_rcp_f32_e32 v138, v138
	v_rcp_f32_e32 v139, v139
	v_exp_f32_e32 v142, v142
	v_exp_f32_e32 v143, v143
	v_pk_fma_f32 v[140:141], v[138:139], s[74:75], v[136:137] op_sel_hi:[1,0,0]
	s_nop 0
	v_pk_fma_f32 v[140:141], v[138:139], v[140:141], s[86:87] op_sel_hi:[1,1,0]
	s_nop 0
	v_pk_fma_f32 v[140:141], v[138:139], v[140:141], s[0:1] op_sel_hi:[1,1,0]
	s_nop 0
	v_pk_fma_f32 v[140:141], v[138:139], v[140:141], s[4:5] op_sel_hi:[1,1,0]
	s_nop 0
	v_pk_mul_f32 v[138:139], v[138:139], v[140:141]
; __device__ __forceinline__ unsigned cvt_pk_bf16(float lo, float hi) { unsigned r; asm volatile("v_cvt_pk_bf16_f32 %0, %1, %2" : "=v"(r) : "v"(lo), "v"(hi)); return r; }
; __device__ __forceinline__ void stat_add(stat_t* p, float ss) { __hip_atomic_fetch_add(p, (stat_t)((double)ss * 4294967296.0), __ATOMIC_RELAXED, __HIP_MEMORY_SCOPE_AGENT); }
;     __device__ __forceinline__ void operator()(const f32x4 (&acc)[2][2][4][2], const Unit& u, int wr, int wc, int fr, int fq) const {
;     ...
;                     const f32x4 v0 = acc[ai][bj][m][0] * r + bv[bj][0], v1 = acc[ai][bj][m][1] * r + bv[bj][1];
;                     const f32x2 a = gelu_pk((f32x2){v0[0], v0[1]}), b = gelu_pk((f32x2){v0[2], v0[3]}), c = gelu_pk((f32x2){v1[0], v1[1]}), d = gelu_pk((f32x2){v1[2], v1[3]});
;                     ss += a.x * a.x + a.y * a.y + b.x * b.x + b.y * b.y + c.x * c.x + c.y * c.y + d.x * d.x + d.y * d.y;
;                     u32x4 w; w.x = cvt_pk_bf16(a.x, a.y); w.y = cvt_pk_bf16(b.x, b.y); w.z = cvt_pk_bf16(c.x, c.y); w.w = cvt_pk_bf16(d.x, d.y);
;                     *(u32x4*)(rowp + bj * HALF) = w;
;                 }
;                 ss += __shfl_xor(ss, 16); ss += __shfl_xor(ss, 32);
;                 if (isv && fq == 0) stat_add(stats_v + row, ss);
	v_pk_mul_f32 v[140:141], v[134:135], v[134:135]
	v_pk_mul_f32 v[138:139], v[142:143], v[138:139]
	s_nop 0
	v_pk_mul_f32 v[142:143], v[132:133], v[138:139]
	v_pk_fma_f32 v[138:139], v[132:133], v[138:139], v[132:133] neg_lo:[1,0,0] neg_hi:[1,0,0]
	v_and_b32_e32 v132, 0x7fffffff, v134
	v_cndmask_b32_e32 v142, v138, v142, vcc
	v_cmp_gt_f32_e32 vcc, 0, v133
	v_and_b32_e32 v133, 0x7fffffff, v135
	v_pk_fma_f32 v[132:133], v[132:133], s[64:65], 1.0 op_sel_hi:[1,0,0]
	v_cndmask_b32_e32 v143, v139, v143, vcc
	v_rcp_f32_e32 v132, v132
	v_rcp_f32_e32 v133, v133
	v_cmp_gt_f32_e32 vcc, 0, v134
	v_pk_fma_f32 v[138:139], v[132:133], s[74:75], v[136:137] op_sel_hi:[1,0,0]
	s_nop 0
	v_pk_fma_f32 v[138:139], v[132:133], v[138:139], s[86:87] op_sel_hi:[1,1,0]
	s_nop 0
	v_pk_fma_f32 v[138:139], v[132:133], v[138:139], s[0:1] op_sel_hi:[1,1,0]
	s_nop 0
	v_pk_fma_f32 v[138:139], v[132:133], v[138:139], s[4:5] op_sel_hi:[1,1,0]
	s_nop 0
	v_pk_mul_f32 v[132:133], v[132:133], v[138:139]
	v_pk_mul_f32 v[138:139], v[140:141], s[30:31] op_sel_hi:[1,0]
	s_nop 0
	v_exp_f32_e32 v138, v138
	v_exp_f32_e32 v139, v139
	s_nop 0
	v_pk_mul_f32 v[132:133], v[138:139], v[132:133]
	s_nop 0
	v_pk_mul_f32 v[138:139], v[134:135], v[132:133]
	v_pk_fma_f32 v[132:133], v[134:135], v[132:133], v[134:135] neg_lo:[1,0,0] neg_hi:[1,0,0]
	s_nop 0
	v_cndmask_b32_e32 v140, v132, v138, vcc
	v_cmp_gt_f32_e32 vcc, 0, v135
	v_and_b32_e32 v132, 0x7fffffff, v128
	s_nop 0
	v_cndmask_b32_e32 v141, v133, v139, vcc
	v_and_b32_e32 v133, 0x7fffffff, v129
	v_pk_fma_f32 v[132:133], v[132:133], s[64:65], 1.0 op_sel_hi:[1,0,0]
	v_pk_mul_f32 v[138:139], v[128:129], v[128:129]
	v_rcp_f32_e32 v132, v132
	v_rcp_f32_e32 v133, v133
	v_pk_mul_f32 v[138:139], v[138:139], s[30:31] op_sel_hi:[1,0]
	v_cmp_gt_f32_e32 vcc, 0, v128
	v_exp_f32_e32 v138, v138
	v_pk_fma_f32 v[134:135], v[132:133], s[74:75], v[136:137] op_sel_hi:[1,0,0]
	v_exp_f32_e32 v139, v139
	v_pk_fma_f32 v[134:135], v[132:133], v[134:135], s[86:87] op_sel_hi:[1,1,0]
	s_nop 0
	v_pk_fma_f32 v[134:135], v[132:133], v[134:135], s[0:1] op_sel_hi:[1,1,0]
	s_nop 0
	v_pk_fma_f32 v[134:135], v[132:133], v[134:135], s[4:5] op_sel_hi:[1,1,0]
	s_nop 0
	v_pk_mul_f32 v[132:133], v[132:133], v[134:135]
	v_pk_mul_f32 v[134:135], v[130:131], v[130:131]
	v_pk_mul_f32 v[132:133], v[138:139], v[132:133]
	s_nop 0
	v_pk_mul_f32 v[138:139], v[128:129], v[132:133]
	v_pk_fma_f32 v[132:133], v[128:129], v[132:133], v[128:129] neg_lo:[1,0,0] neg_hi:[1,0,0]
	v_and_b32_e32 v128, 0x7fffffff, v130
	v_cndmask_b32_e32 v138, v132, v138, vcc
	v_cmp_gt_f32_e32 vcc, 0, v129
	v_and_b32_e32 v129, 0x7fffffff, v131
	v_pk_fma_f32 v[128:129], v[128:129], s[64:65], 1.0 op_sel_hi:[1,0,0]
	v_cndmask_b32_e32 v139, v133, v139, vcc
	v_rcp_f32_e32 v128, v128
	v_rcp_f32_e32 v129, v129
	v_cmp_gt_f32_e32 vcc, 0, v130
	v_pk_fma_f32 v[132:133], v[128:129], s[74:75], v[136:137] op_sel_hi:[1,0,0]
	s_nop 0
	v_pk_fma_f32 v[132:133], v[128:129], v[132:133], s[86:87] op_sel_hi:[1,1,0]
	s_nop 0
	v_pk_fma_f32 v[132:133], v[128:129], v[132:133], s[0:1] op_sel_hi:[1,1,0]
	s_nop 0
	v_pk_fma_f32 v[132:133], v[128:129], v[132:133], s[4:5] op_sel_hi:[1,1,0]
	s_nop 0
	v_pk_mul_f32 v[128:129], v[128:129], v[132:133]
	v_pk_mul_f32 v[132:133], v[134:135], s[30:31] op_sel_hi:[1,0]
	s_nop 0
	v_exp_f32_e32 v132, v132
	v_exp_f32_e32 v133, v133
	s_nop 0
	v_pk_mul_f32 v[128:129], v[132:133], v[128:129]
	s_nop 0
	v_pk_mul_f32 v[132:133], v[130:131], v[128:129]
	v_pk_fma_f32 v[128:129], v[130:131], v[128:129], v[130:131] neg_lo:[1,0,0] neg_hi:[1,0,0]
	s_nop 0
	v_cndmask_b32_e32 v132, v128, v132, vcc
	v_mul_f32_e32 v128, v143, v143
	v_fmac_f32_e32 v128, v142, v142
	v_fmac_f32_e32 v128, v140, v140
	v_fmac_f32_e32 v128, v141, v141
	v_fmac_f32_e32 v128, v138, v138
	v_cmp_gt_f32_e32 vcc, 0, v131
	v_fmac_f32_e32 v128, v139, v139
	v_fmac_f32_e32 v128, v132, v132
	v_cndmask_b32_e32 v131, v129, v133, vcc
	v_fmac_f32_e32 v128, v131, v131
	v_add_f32_e32 v134, v176, v128
	v_cvt_pk_bf16_f32 v128, v142, v143
	v_cvt_pk_bf16_f32 v129, v140, v141
	v_cvt_pk_bf16_f32 v130, v138, v139
	v_cvt_pk_bf16_f32 v131, v132, v131
	global_store_dwordx4 v[166:167], v[128:131], off offset:256
	s_nop 1
	v_and_b32_e32 v129, 64, v190
	v_xor_b32_e32 v128, 16, v190
	v_add_u32_e32 v129, 64, v129
	v_cmp_lt_i32_e32 vcc, v128, v129
	v_xor_b32_e32 v130, 32, v190
	s_nop 0
	v_cndmask_b32_e32 v128, v190, v128, vcc
	v_lshlrev_b32_e32 v133, 2, v128
	ds_bpermute_b32 v128, v133, v134
	v_cmp_lt_i32_e32 vcc, v130, v129
	s_waitcnt lgkmcnt(0)
	v_add_f32_e32 v128, v134, v128
	v_cndmask_b32_e32 v129, v190, v130, vcc
	v_lshlrev_b32_e32 v134, 2, v129
	ds_bpermute_b32 v129, v134, v128
	s_and_saveexec_b64 s[30:31], s[28:29]
	s_cbranch_execz .LBB0_867
	s_waitcnt lgkmcnt(0)
	v_add_f32_e32 v128, v128, v129
	v_cvt_f64_f32_e32 v[128:129], v128
	v_ldexp_f64 v[128:129], v[128:129], 32
	v_trunc_f64_e32 v[128:129], v[128:129]
	v_ldexp_f64 v[136:137], v[128:129], s93
	v_floor_f64_e32 v[136:137], v[136:137]
	v_fmac_f64_e32 v[128:129], 0xc1f00000, v[136:137]
	v_lshl_add_u64 v[130:131], v[156:157], 3, s[18:19]
	v_cvt_u32_f64_e32 v128, v[128:129]
	v_cvt_u32_f64_e32 v129, v[136:137]
	global_atomic_add_x2 v[130:131], v[128:129], off

; #define LAS __attribute__((address_space(3)))
; __device__ __forceinline__ unsigned cvt_pk_bf16(float lo, float hi) { unsigned r; asm volatile("v_cvt_pk_bf16_f32 %0, %1, %2" : "=v"(r) : "v"(lo), "v"(hi)); return r; }
; __device__ __forceinline__ float bf_lo(unsigned v) { return __uint_as_float(v << 16); }
; __device__ __forceinline__ float bf_hi(unsigned v) { return __uint_as_float(v & 0xffff0000u); }
; template <bool BF> __device__ __forceinline__ f32x4 ld4(const void* base, size_t idx) {
;     if (BF) { const u32x2 w = *(const u32x2*)((const bf16_t*)base + idx); return (f32x4){bf_lo(w.x), bf_hi(w.x), bf_lo(w.y), bf_hi(w.y)}; }
; template <bool BF, int W> __device__ __forceinline__ void poolp_chunk(const void* xsrc, size_t xb0, int s_base, int s0, int c, f32x4 g4, const LAS float* rinv, bf16_t* Pout) {
;     f32x4 h[W + 8];
; #pragma unroll
;     for (int r = 0; r < W + 8; ++r) {
;         const int s = s_base - W + r;
;         if (s >= 0) h[r] = ld4<BF>(xsrc, xb0 + (size_t)s * D + c) * (g4 * rinv[s - s0 + 16]);
;         else h[r] = (f32x4){0.f, 0.f, 0.f, 0.f};
;     }
;     f32x4 S = (f32x4){0.f, 0.f, 0.f, 0.f};
; #pragma unroll
;     for (int i = 0; i < W; ++i) S += h[i];
; #pragma unroll
;     for (int tt = 0; tt < 8; ++tt) {
;         const int s = s_base + tt;
;         S += h[W + tt] - h[tt];
;         const float inv = 1.0f / (float)min(s + 1, W);
;         const f32x4 pv = S * inv - h[W + tt];
;         u32x2 o; o.x = cvt_pk_bf16(pv[0], pv[1]); o.y = cvt_pk_bf16(pv[2], pv[3]);
;         *(u32x2*)(Pout + (size_t)tt * D) = o;
;     }
; }
.LBB0_1171:
	v_add_co_u32_e32 v34, vcc, s34, v14
	v_mov_b32_e32 v48, s28
	s_nop 0
	v_addc_co_u32_e32 v35, vcc, -1, v15, vcc
	v_add_co_u32_e32 v36, vcc, s35, v14
	global_load_dwordx2 v[40:41], v[34:35], off offset:-4096
	global_load_dwordx2 v[34:35], v[34:35], off
	v_addc_co_u32_e32 v37, vcc, -1, v15, vcc
	global_load_dwordx2 v[42:43], v[36:37], off offset:-4096
	global_load_dwordx2 v[44:45], v[36:37], off
	v_add_co_u32_e32 v36, vcc, s94, v14
	global_load_dwordx2 v[52:53], v[14:15], off offset:-4096
	s_nop 0
	v_addc_co_u32_e32 v37, vcc, -1, v15, vcc
	global_load_dwordx2 v[46:47], v[36:37], off
	v_add_co_u32_e32 v36, vcc, 0xffff9000, v14
	s_min_i32 s4, s29, 3
	s_nop 0
	v_addc_co_u32_e32 v37, vcc, -1, v15, vcc
	global_load_dwordx2 v[60:61], v[36:37], off
	global_load_dwordx2 v[98:99], v[14:15], off
	ds_read2_b32 v[36:37], v48 offset0:16 offset1:17
	v_pk_add_f32 v[132:133], v[26:27], 0 op_sel_hi:[1,0]
	v_xor_b32_e32 v27, 0x80000000, v27
	v_xor_b32_e32 v26, 0x80000000, v26
	s_add_i32 s4, s4, 1
	s_waitcnt vmcnt(8) lgkmcnt(0)
	v_pk_mul_f32 v[102:103], v[2:3], v[36:37] op_sel_hi:[1,0]
	v_pk_mul_f32 v[104:105], v[0:1], v[36:37] op_sel_hi:[1,0]
	v_pk_add_f32 v[130:131], v[22:23], 0 op_sel_hi:[1,0]
	v_xor_b32_e32 v23, 0x80000000, v23
	v_xor_b32_e32 v22, 0x80000000, v22
	v_pk_add_f32 v[132:133], v[132:133], v[30:31]
	v_pk_add_f32 v[130:131], v[130:131], v[18:19]
	v_pk_add_f32 v[132:133], v[132:133], v[28:29]
	v_pk_add_f32 v[130:131], v[130:131], v[24:25]
	v_pk_add_f32 v[132:133], v[132:133], v[32:33]
	v_pk_add_f32 v[130:131], v[130:131], v[20:21]
	s_add_i32 s1, s29, 1
	s_min_i32 s1, s1, 3
	ds_read2_b32 v[38:39], v48 offset0:18 offset1:19
	ds_read2_b32 v[54:55], v48 offset0:20 offset1:21
	ds_read2_b32 v[100:101], v48 offset0:22 offset1:23
	s_add_i32 s1, s1, 1
	v_pk_mul_f32 v[106:107], v[2:3], v[36:37] op_sel:[0,1]
	v_pk_mul_f32 v[108:109], v[0:1], v[36:37] op_sel:[0,1]
	v_xor_b32_e32 v31, 0x80000000, v31
	v_xor_b32_e32 v30, 0x80000000, v30
	v_xor_b32_e32 v19, 0x80000000, v19
	v_xor_b32_e32 v18, 0x80000000, v18
	s_add_i32 s0, s29, 2
	s_min_i32 s0, s0, 3
	s_add_i32 s0, s0, 1
	s_waitcnt lgkmcnt(2)
	v_pk_mul_f32 v[92:93], v[2:3], v[38:39] op_sel_hi:[1,0]
	v_pk_mul_f32 v[88:89], v[0:1], v[38:39] op_sel_hi:[1,0]
	v_xor_b32_e32 v25, 0x80000000, v25
	v_xor_b32_e32 v24, 0x80000000, v24
	v_pk_mul_f32 v[70:71], v[2:3], v[38:39] op_sel:[0,1]
	v_pk_mul_f32 v[64:65], v[0:1], v[38:39] op_sel:[0,1]
	s_waitcnt lgkmcnt(1)
	v_pk_mul_f32 v[48:49], v[2:3], v[54:55] op_sel_hi:[1,0]
	v_pk_mul_f32 v[50:51], v[0:1], v[54:55] op_sel_hi:[1,0]
	v_pk_mul_f32 v[36:37], v[2:3], v[54:55] op_sel:[0,1]
	v_pk_mul_f32 v[38:39], v[0:1], v[54:55] op_sel:[0,1]
	v_xor_b32_e32 v21, 0x80000000, v21
	v_xor_b32_e32 v20, 0x80000000, v20
	s_waitcnt lgkmcnt(0)
	v_pk_mul_f32 v[86:87], v[2:3], v[100:101] op_sel_hi:[1,0]
	v_pk_mul_f32 v[118:119], v[0:1], v[100:101] op_sel_hi:[1,0]
	v_pk_mul_f32 v[124:125], v[2:3], v[100:101] op_sel:[0,1]
	v_pk_mul_f32 v[100:101], v[0:1], v[100:101] op_sel:[0,1]
	s_waitcnt vmcnt(7)
	v_lshlrev_b32_e32 v110, 16, v40
	v_and_b32_e32 v111, 0xffff0000, v40
	v_lshlrev_b32_e32 v112, 16, v41
	v_and_b32_e32 v113, 0xffff0000, v41
	v_pk_fma_f32 v[30:31], v[106:107], v[112:113], v[30:31]
	v_pk_fma_f32 v[18:19], v[108:109], v[110:111], v[18:19]
	v_pk_mul_f32 v[62:63], v[106:107], v[112:113]
	s_waitcnt vmcnt(6)
	v_lshlrev_b32_e32 v96, 16, v35
	v_and_b32_e32 v97, 0xffff0000, v35
	s_waitcnt vmcnt(5)
	v_lshlrev_b32_e32 v74, 16, v42
	v_and_b32_e32 v75, 0xffff0000, v42
	v_lshlrev_b32_e32 v80, 16, v43
	v_and_b32_e32 v81, 0xffff0000, v43
	s_waitcnt vmcnt(4)
	v_lshlrev_b32_e32 v58, 16, v44
	v_and_b32_e32 v59, 0xffff0000, v44
	s_waitcnt vmcnt(1)
	v_lshlrev_b32_e32 v116, 16, v61
	v_and_b32_e32 v117, 0xffff0000, v61
	v_pk_mul_f32 v[84:85], v[102:103], v[116:117]
	v_pk_fma_f32 v[26:27], v[102:103], v[116:117], v[26:27]
	v_cvt_f32_u32_e32 v102, s4
	v_lshlrev_b32_e32 v114, 16, v60
	v_and_b32_e32 v115, 0xffff0000, v60
	v_pk_mul_f32 v[82:83], v[104:105], v[114:115]
	v_div_scale_f32 v103, s[10:11], v102, v102, 1.0
	v_rcp_f32_e32 v116, v103
	v_pk_fma_f32 v[22:23], v[104:105], v[114:115], v[22:23]
	v_pk_add_f32 v[26:27], v[132:133], v[26:27]
	v_pk_add_f32 v[22:23], v[130:131], v[22:23]
	v_fma_f32 v104, -v103, v116, 1.0
	v_fmac_f32_e32 v116, v104, v116
	v_div_scale_f32 v104, vcc, 1.0, v102, 1.0
	v_mul_f32_e32 v105, v104, v116
	v_fma_f32 v114, -v103, v105, v104
	v_fmac_f32_e32 v105, v114, v116
	v_fma_f32 v103, -v103, v105, v104
	v_div_fmas_f32 v103, v103, v116, v105
	v_div_fixup_f32 v102, v103, v102, 1.0
	v_pk_fma_f32 v[104:105], v[102:103], v[26:27], v[84:85] op_sel_hi:[0,1,1] neg_lo:[0,0,1] neg_hi:[0,0,1]
	v_pk_fma_f32 v[102:103], v[102:103], v[22:23], v[82:83] op_sel_hi:[0,1,1] neg_lo:[0,0,1] neg_hi:[0,0,1]
	v_cvt_pk_bf16_f32 v102, v102, v103
	v_cvt_pk_bf16_f32 v103, v104, v105
	global_store_dwordx2 v[16:17], v[102:103], off
	v_cvt_f32_u32_e32 v102, s1
	v_pk_add_f32 v[18:19], v[22:23], v[18:19]
	v_pk_add_f32 v[22:23], v[26:27], v[30:31]
	v_pk_mul_f32 v[60:61], v[108:109], v[110:111]
	v_div_scale_f32 v103, s[10:11], v102, v102, 1.0
	v_rcp_f32_e32 v104, v103
	v_lshlrev_b32_e32 v66, 16, v45
	v_and_b32_e32 v67, 0xffff0000, v45
	v_lshlrev_b32_e32 v42, 16, v52
	v_fma_f32 v26, -v103, v104, 1.0
	v_fmac_f32_e32 v104, v26, v104
	v_div_scale_f32 v26, vcc, 1.0, v102, 1.0
	v_mul_f32_e32 v27, v26, v104
	v_fma_f32 v30, -v103, v27, v26
	v_fmac_f32_e32 v27, v30, v104
	v_fma_f32 v26, -v103, v27, v26
; __device__ __forceinline__ unsigned cvt_pk_bf16(float lo, float hi) { unsigned r; asm volatile("v_cvt_pk_bf16_f32 %0, %1, %2" : "=v"(r) : "v"(lo), "v"(hi)); return r; }
; template <bool BF, int W> __device__ __forceinline__ void poolp_chunk(const void* xsrc, size_t xb0, int s_base, int s0, int c, f32x4 g4, const LAS float* rinv, bf16_t* Pout) {
;     ...
;     for (int tt = 0; tt < 8; ++tt) {
;         const int s = s_base + tt;
;         S += h[W + tt] - h[tt];
;         const float inv = 1.0f / (float)min(s + 1, W);
;         const f32x4 pv = S * inv - h[W + tt];
;         u32x2 o; o.x = cvt_pk_bf16(pv[0], pv[1]); o.y = cvt_pk_bf16(pv[2], pv[3]);
;         *(u32x2*)(Pout + (size_t)tt * D) = o;
;     }
	v_div_fmas_f32 v26, v26, v104, v27
	v_div_fixup_f32 v26, v26, v102, 1.0
	v_pk_fma_f32 v[30:31], v[26:27], v[22:23], v[62:63] op_sel_hi:[0,1,1] neg_lo:[0,0,1] neg_hi:[0,0,1]
	v_pk_fma_f32 v[26:27], v[26:27], v[18:19], v[60:61] op_sel_hi:[0,1,1] neg_lo:[0,0,1] neg_hi:[0,0,1]
	v_cvt_pk_bf16_f32 v26, v26, v27
	v_cvt_pk_bf16_f32 v27, v30, v31
	v_add_co_u32_e32 v30, vcc, s5, v16
	v_and_b32_e32 v43, 0xffff0000, v52
	s_nop 0
	v_addc_co_u32_e32 v31, vcc, 0, v17, vcc
	global_store_dwordx2 v[30:31], v[26:27], off offset:-4096
	v_xor_b32_e32 v26, 0x80000000, v28
	v_cvt_f32_u32_e32 v28, s0
	v_xor_b32_e32 v27, 0x80000000, v29
	v_lshlrev_b32_e32 v44, 16, v53
	v_and_b32_e32 v45, 0xffff0000, v53
	v_div_scale_f32 v29, s[0:1], v28, v28, 1.0
	v_pk_mul_f32 v[52:53], v[92:93], v[96:97]
	v_pk_fma_f32 v[26:27], v[92:93], v[96:97], v[26:27]
	v_rcp_f32_e32 v92, v29
	v_lshlrev_b32_e32 v90, 16, v34
	v_and_b32_e32 v91, 0xffff0000, v34
	v_pk_fma_f32 v[24:25], v[88:89], v[90:91], v[24:25]
	v_pk_add_f32 v[22:23], v[22:23], v[26:27]
	v_pk_add_f32 v[18:19], v[18:19], v[24:25]
	v_fma_f32 v24, -v29, v92, 1.0
	v_fmac_f32_e32 v92, v24, v92
	v_div_scale_f32 v24, vcc, 1.0, v28, 1.0
	v_mul_f32_e32 v25, v24, v92
	v_fma_f32 v26, -v29, v25, v24
	v_fmac_f32_e32 v25, v26, v92
	v_fma_f32 v24, -v29, v25, v24
	v_div_fmas_f32 v24, v24, v92, v25
	v_lshlrev_b32_e32 v54, 16, v46
	v_and_b32_e32 v55, 0xffff0000, v46
	v_lshlrev_b32_e32 v56, 16, v47
	v_and_b32_e32 v57, 0xffff0000, v47
	v_pk_mul_f32 v[46:47], v[88:89], v[90:91]
	v_div_fixup_f32 v24, v24, v28, 1.0
	v_pk_fma_f32 v[26:27], v[24:25], v[22:23], v[52:53] op_sel_hi:[0,1,1] neg_lo:[0,0,1] neg_hi:[0,0,1]
	v_pk_fma_f32 v[24:25], v[24:25], v[18:19], v[46:47] op_sel_hi:[0,1,1] neg_lo:[0,0,1] neg_hi:[0,0,1]
	v_cvt_pk_bf16_f32 v24, v24, v25
	v_cvt_pk_bf16_f32 v25, v26, v27
	global_store_dwordx2 v[30:31], v[24:25], off
	v_xor_b32_e32 v25, 0x80000000, v33
	v_xor_b32_e32 v24, 0x80000000, v32
	v_pk_fma_f32 v[24:25], v[70:71], v[80:81], v[24:25]
	v_pk_fma_f32 v[20:21], v[64:65], v[74:75], v[20:21]
	v_pk_mul_f32 v[34:35], v[64:65], v[74:75]
	v_pk_mul_f32 v[40:41], v[70:71], v[80:81]
	v_pk_add_f32 v[18:19], v[18:19], v[20:21]
	v_pk_add_f32 v[20:21], v[22:23], v[24:25]
	v_pk_fma_f32 v[24:25], v[18:19], s[6:7], v[34:35] op_sel_hi:[1,0,1] neg_lo:[0,0,1] neg_hi:[0,0,1]
	v_pk_fma_f32 v[22:23], v[20:21], s[6:7], v[40:41] op_sel_hi:[1,0,1] neg_lo:[0,0,1] neg_hi:[0,0,1]
	v_cvt_pk_bf16_f32 v24, v24, v25
	v_pk_fma_f32 v[26:27], v[50:51], v[58:59], v[82:83] neg_lo:[0,0,1] neg_hi:[0,0,1]
	v_cvt_pk_bf16_f32 v25, v22, v23
	v_add_co_u32_e32 v22, vcc, s7, v16
	v_pk_mul_f32 v[76:77], v[50:51], v[58:59]
	s_nop 0
	v_addc_co_u32_e32 v23, vcc, 0, v17, vcc
	global_store_dwordx2 v[22:23], v[24:25], off offset:-4096
	v_pk_fma_f32 v[24:25], v[48:49], v[66:67], v[84:85] neg_lo:[0,0,1] neg_hi:[0,0,1]
	v_pk_mul_f32 v[78:79], v[48:49], v[66:67]
	v_pk_add_f32 v[18:19], v[18:19], v[26:27]
	v_pk_add_f32 v[20:21], v[20:21], v[24:25]
	v_pk_fma_f32 v[26:27], v[18:19], s[6:7], v[76:77] op_sel_hi:[1,0,1] neg_lo:[0,0,1] neg_hi:[0,0,1]
	v_pk_fma_f32 v[24:25], v[20:21], s[6:7], v[78:79] op_sel_hi:[1,0,1] neg_lo:[0,0,1] neg_hi:[0,0,1]
	v_cvt_pk_bf16_f32 v26, v26, v27
	v_pk_mul_f32 v[68:69], v[38:39], v[54:55]
	v_cvt_pk_bf16_f32 v27, v24, v25
	global_store_dwordx2 v[22:23], v[26:27], off
	v_pk_fma_f32 v[22:23], v[36:37], v[56:57], v[62:63] neg_lo:[0,0,1] neg_hi:[0,0,1]
	v_pk_fma_f32 v[24:25], v[38:39], v[54:55], v[60:61] neg_lo:[0,0,1] neg_hi:[0,0,1]
	v_pk_mul_f32 v[72:73], v[36:37], v[56:57]
	v_pk_add_f32 v[18:19], v[18:19], v[24:25]
	v_pk_add_f32 v[20:21], v[20:21], v[22:23]
	v_pk_fma_f32 v[24:25], v[18:19], s[6:7], v[68:69] op_sel_hi:[1,0,1] neg_lo:[0,0,1] neg_hi:[0,0,1]
	v_pk_fma_f32 v[22:23], v[20:21], s[6:7], v[72:73] op_sel_hi:[1,0,1] neg_lo:[0,0,1] neg_hi:[0,0,1]
	v_cvt_pk_bf16_f32 v24, v24, v25
	v_pk_fma_f32 v[26:27], v[118:119], v[42:43], v[46:47] neg_lo:[0,0,1] neg_hi:[0,0,1]
	v_cvt_pk_bf16_f32 v25, v22, v23
	v_add_co_u32_e32 v22, vcc, s77, v16
	v_pk_mul_f32 v[120:121], v[118:119], v[42:43]
	s_nop 0
	v_addc_co_u32_e32 v23, vcc, 0, v17, vcc
	global_store_dwordx2 v[22:23], v[24:25], off offset:-4096
	v_pk_fma_f32 v[24:25], v[86:87], v[44:45], v[52:53] neg_lo:[0,0,1] neg_hi:[0,0,1]
	v_pk_mul_f32 v[122:123], v[86:87], v[44:45]
	v_pk_add_f32 v[18:19], v[18:19], v[26:27]
	v_pk_add_f32 v[20:21], v[20:21], v[24:25]
	s_waitcnt vmcnt(6)
	v_lshlrev_b32_e32 v94, 16, v98
	v_and_b32_e32 v95, 0xffff0000, v98
	v_pk_fma_f32 v[24:25], v[20:21], s[6:7], v[122:123] op_sel_hi:[1,0,1] neg_lo:[0,0,1] neg_hi:[0,0,1]
	v_pk_fma_f32 v[26:27], v[18:19], s[6:7], v[120:121] op_sel_hi:[1,0,1] neg_lo:[0,0,1] neg_hi:[0,0,1]
	v_lshlrev_b32_e32 v98, 16, v99
	v_and_b32_e32 v99, 0xffff0000, v99
	v_cvt_pk_bf16_f32 v26, v26, v27
	v_cvt_pk_bf16_f32 v27, v24, v25
	v_pk_fma_f32 v[24:25], v[100:101], v[94:95], v[34:35] neg_lo:[0,0,1] neg_hi:[0,0,1]
	v_pk_mul_f32 v[126:127], v[100:101], v[94:95]
	global_store_dwordx2 v[22:23], v[26:27], off
	v_pk_fma_f32 v[22:23], v[124:125], v[98:99], v[40:41] neg_lo:[0,0,1] neg_hi:[0,0,1]
	v_pk_add_f32 v[18:19], v[18:19], v[24:25]
	v_pk_mul_f32 v[128:129], v[124:125], v[98:99]
	v_pk_add_f32 v[20:21], v[20:21], v[22:23]
	v_pk_fma_f32 v[18:19], v[18:19], s[6:7], v[126:127] op_sel_hi:[1,0,1] neg_lo:[0,0,1] neg_hi:[0,0,1]
	v_pk_fma_f32 v[20:21], v[20:21], s[6:7], v[128:129] op_sel_hi:[1,0,1] neg_lo:[0,0,1] neg_hi:[0,0,1]
	v_cvt_pk_bf16_f32 v18, v18, v19
	s_nop 0
	v_cvt_pk_bf16_f32 v19, v20, v21

; #define LAS __attribute__((address_space(3)))
; __device__ __forceinline__ unsigned cvt_pk_bf16(float lo, float hi) { unsigned r; asm volatile("v_cvt_pk_bf16_f32 %0, %1, %2" : "=v"(r) : "v"(lo), "v"(hi)); return r; }
; template <bool BF, int W> __device__ __forceinline__ void poolp_chunk(const void* xsrc, size_t xb0, int s_base, int s0, int c, f32x4 g4, const LAS float* rinv, bf16_t* Pout) {
;     f32x4 h[W + 8];
; #pragma unroll
;     for (int r = 0; r < W + 8; ++r) {
;         const int s = s_base - W + r;
;         if (s >= 0) h[r] = ld4<BF>(xsrc, xb0 + (size_t)s * D + c) * (g4 * rinv[s - s0 + 16]);
;         else h[r] = (f32x4){0.f, 0.f, 0.f, 0.f};
;     }
;     f32x4 S = (f32x4){0.f, 0.f, 0.f, 0.f};
; #pragma unroll
;     for (int i = 0; i < W; ++i) S += h[i];
; #pragma unroll
;     for (int tt = 0; tt < 8; ++tt) {
;         const int s = s_base + tt;
;         S += h[W + tt] - h[tt];
;         const float inv = 1.0f / (float)min(s + 1, W);
;         const f32x4 pv = S * inv - h[W + tt];
;         u32x2 o; o.x = cvt_pk_bf16(pv[0], pv[1]); o.y = cvt_pk_bf16(pv[2], pv[3]);
;         *(u32x2*)(Pout + (size_t)tt * D) = o;
;     }
.LBB0_1426:
	v_add_co_u32_e32 v4, vcc, 0xffff2000, v38
	s_min_i32 s2, s23, 1
	s_nop 0
	v_addc_co_u32_e32 v5, vcc, -1, v39, vcc
	global_load_dwordx4 v[24:27], v[4:5], off
	v_add_co_u32_e32 v4, vcc, s50, v38
	s_add_i32 s2, s2, 1
	s_nop 0
	v_addc_co_u32_e32 v5, vcc, -1, v39, vcc
	v_add_co_u32_e32 v6, vcc, s54, v38
	v_cvt_f32_u32_e32 v124, s2
	s_nop 0
	v_addc_co_u32_e32 v7, vcc, -1, v39, vcc
	global_load_dwordx4 v[20:23], v[4:5], off
	global_load_dwordx4 v[16:19], v[6:7], off
	v_add_co_u32_e32 v4, vcc, s49, v38
	v_div_scale_f32 v125, s[2:3], v124, v124, 1.0
	s_nop 0
	v_addc_co_u32_e32 v5, vcc, -1, v39, vcc
	v_add_co_u32_e32 v12, vcc, s94, v38
	global_load_dwordx4 v[8:11], v[4:5], off
	global_load_dwordx4 v[4:7], v[38:39], off
	v_addc_co_u32_e32 v13, vcc, -1, v39, vcc
	v_add_co_u32_e32 v42, vcc, s55, v38
	global_load_dwordx4 v[12:15], v[12:13], off
	s_nop 0
	v_addc_co_u32_e32 v43, vcc, -1, v39, vcc
	global_load_dwordx4 v[42:45], v[42:43], off
	v_add_co_u32_e32 v46, vcc, s48, v38
	v_mov_b32_e32 v60, s22
	s_nop 0
	v_addc_co_u32_e32 v47, vcc, -1, v39, vcc
	global_load_dwordx4 v[46:49], v[46:47], off
	v_rcp_f32_e32 v126, v125
	ds_read2_b32 v[54:55], v60 offset0:16 offset1:17
	ds_read2_b32 v[56:57], v60 offset0:18 offset1:19
	ds_read2_b32 v[58:59], v60 offset0:20 offset1:21
	ds_read2_b32 v[60:61], v60 offset0:22 offset1:23
	v_pk_add_f32 v[50:51], v[30:31], 0 op_sel_hi:[1,0]
	s_waitcnt vmcnt(8) lgkmcnt(3)
	v_pk_mul_f32 v[62:63], v[0:1], v[54:55] op_sel_hi:[1,0]
	v_xor_b32_e32 v31, 0x80000000, v31
	v_xor_b32_e32 v30, 0x80000000, v30
	v_pk_add_f32 v[50:51], v[50:51], v[28:29]
	v_pk_add_f32 v[52:53], v[34:35], 0 op_sel_hi:[1,0]
	v_xor_b32_e32 v35, 0x80000000, v35
	v_xor_b32_e32 v34, 0x80000000, v34
	v_pk_mul_f32 v[64:65], v[2:3], v[54:55] op_sel_hi:[1,0]
	v_pk_add_f32 v[52:53], v[52:53], v[32:33]
	v_pk_mul_f32 v[66:67], v[0:1], v[54:55] op_sel:[0,1]
	v_pk_mul_f32 v[54:55], v[2:3], v[54:55] op_sel:[0,1]
	v_xor_b32_e32 v29, 0x80000000, v29
	v_xor_b32_e32 v28, 0x80000000, v28
	s_waitcnt lgkmcnt(2)
	v_pk_mul_f32 v[68:69], v[0:1], v[56:57] op_sel_hi:[1,0]
	v_pk_mul_f32 v[70:71], v[2:3], v[56:57] op_sel_hi:[1,0]
	v_pk_mul_f32 v[72:73], v[0:1], v[56:57] op_sel:[0,1]
	v_pk_mul_f32 v[56:57], v[2:3], v[56:57] op_sel:[0,1]
	s_waitcnt lgkmcnt(1)
	v_pk_mul_f32 v[74:75], v[0:1], v[58:59] op_sel_hi:[1,0]
	v_pk_mul_f32 v[76:77], v[2:3], v[58:59] op_sel_hi:[1,0]
	v_pk_mul_f32 v[78:79], v[0:1], v[58:59] op_sel:[0,1]
	v_pk_mul_f32 v[58:59], v[2:3], v[58:59] op_sel:[0,1]
	s_waitcnt lgkmcnt(0)
	v_pk_mul_f32 v[80:81], v[0:1], v[60:61] op_sel_hi:[1,0]
	v_pk_mul_f32 v[82:83], v[2:3], v[60:61] op_sel_hi:[1,0]
	v_pk_mul_f32 v[84:85], v[0:1], v[60:61] op_sel:[0,1]
	v_pk_mul_f32 v[60:61], v[2:3], v[60:61] op_sel:[0,1]
	s_waitcnt vmcnt(7)
	v_pk_mul_f32 v[110:111], v[24:25], v[62:63]
	v_pk_fma_f32 v[24:25], v[24:25], v[62:63], v[30:31]
	v_fma_f32 v30, -v125, v126, 1.0
	v_fmac_f32_e32 v126, v30, v126
	v_div_scale_f32 v30, vcc, 1.0, v124, 1.0
	v_mul_f32_e32 v31, v30, v126
	v_pk_add_f32 v[24:25], v[50:51], v[24:25]
	v_fma_f32 v50, -v125, v31, v30
	v_fmac_f32_e32 v31, v50, v126
	v_fma_f32 v30, -v125, v31, v30
	v_pk_mul_f32 v[108:109], v[26:27], v[64:65]
	v_pk_fma_f32 v[26:27], v[26:27], v[64:65], v[34:35]
	v_div_fmas_f32 v30, v30, v126, v31
	v_pk_add_f32 v[26:27], v[52:53], v[26:27]
	v_div_fixup_f32 v30, v30, v124, 1.0
	v_pk_fma_f32 v[50:51], v[30:31], v[26:27], v[108:109] op_sel_hi:[0,1,1] neg_lo:[0,0,1] neg_hi:[0,0,1]
	v_pk_fma_f32 v[30:31], v[30:31], v[24:25], v[110:111] op_sel_hi:[0,1,1] neg_lo:[0,0,1] neg_hi:[0,0,1]
	v_cvt_pk_bf16_f32 v30, v30, v31
	v_cvt_pk_bf16_f32 v31, v50, v51
	global_store_dwordx2 v[40:41], v[30:31], off
	v_xor_b32_e32 v31, 0x80000000, v33
	v_xor_b32_e32 v30, 0x80000000, v32
	s_waitcnt vmcnt(7)
	v_pk_mul_f32 v[34:35], v[22:23], v[54:55]
	v_pk_mul_f32 v[64:65], v[20:21], v[66:67]
	v_pk_fma_f32 v[22:23], v[22:23], v[54:55], v[30:31]
	v_pk_fma_f32 v[20:21], v[20:21], v[66:67], v[28:29]
	v_pk_add_f32 v[22:23], v[26:27], v[22:23]
	v_pk_add_f32 v[20:21], v[24:25], v[20:21]
	s_waitcnt vmcnt(6)
; __device__ __forceinline__ unsigned cvt_pk_bf16(float lo, float hi) { unsigned r; asm volatile("v_cvt_pk_bf16_f32 %0, %1, %2" : "=v"(r) : "v"(lo), "v"(hi)); return r; }
; template <bool BF, int W> __device__ __forceinline__ void poolp_chunk(const void* xsrc, size_t xb0, int s_base, int s0, int c, f32x4 g4, const LAS float* rinv, bf16_t* Pout) {
;     ...
;     for (int tt = 0; tt < 8; ++tt) {
;         const int s = s_base + tt;
;         S += h[W + tt] - h[tt];
;         const float inv = 1.0f / (float)min(s + 1, W);
;         const f32x4 pv = S * inv - h[W + tt];
;         u32x2 o; o.x = cvt_pk_bf16(pv[0], pv[1]); o.y = cvt_pk_bf16(pv[2], pv[3]);
;         *(u32x2*)(Pout + (size_t)tt * D) = o;
;     }
	v_pk_mul_f32 v[114:115], v[16:17], v[68:69]
	v_pk_fma_f32 v[24:25], v[22:23], 0.5, v[34:35] op_sel_hi:[1,0,1] neg_lo:[0,0,1] neg_hi:[0,0,1]
	v_pk_fma_f32 v[26:27], v[20:21], 0.5, v[64:65] op_sel_hi:[1,0,1] neg_lo:[0,0,1] neg_hi:[0,0,1]
	v_pk_fma_f32 v[16:17], v[16:17], v[68:69], v[110:111] neg_lo:[0,0,1] neg_hi:[0,0,1]
	v_pk_mul_f32 v[112:113], v[18:19], v[70:71]
	v_cvt_pk_bf16_f32 v26, v26, v27
	v_cvt_pk_bf16_f32 v27, v24, v25
	v_add_co_u32_e32 v24, vcc, s5, v40
	v_pk_fma_f32 v[18:19], v[18:19], v[70:71], v[108:109] neg_lo:[0,0,1] neg_hi:[0,0,1]
	v_pk_add_f32 v[16:17], v[20:21], v[16:17]
	v_addc_co_u32_e32 v25, vcc, 0, v41, vcc
	v_pk_add_f32 v[18:19], v[22:23], v[18:19]
	v_pk_fma_f32 v[22:23], v[16:17], 0.5, v[114:115] op_sel_hi:[1,0,1] neg_lo:[0,0,1] neg_hi:[0,0,1]
	global_store_dwordx2 v[24:25], v[26:27], off offset:-4096
	v_pk_fma_f32 v[20:21], v[18:19], 0.5, v[112:113] op_sel_hi:[1,0,1] neg_lo:[0,0,1] neg_hi:[0,0,1]
	v_cvt_pk_bf16_f32 v22, v22, v23
	s_waitcnt vmcnt(3)
	v_pk_mul_f32 v[116:117], v[44:45], v[56:57]
	v_cvt_pk_bf16_f32 v23, v20, v21
	global_store_dwordx2 v[24:25], v[22:23], off
	v_pk_fma_f32 v[20:21], v[44:45], v[56:57], v[34:35] neg_lo:[0,0,1] neg_hi:[0,0,1]
	v_pk_fma_f32 v[22:23], v[42:43], v[72:73], v[64:65] neg_lo:[0,0,1] neg_hi:[0,0,1]
	v_pk_mul_f32 v[118:119], v[42:43], v[72:73]
	v_pk_add_f32 v[18:19], v[18:19], v[20:21]
	v_pk_add_f32 v[16:17], v[16:17], v[22:23]
	v_pk_fma_f32 v[20:21], v[18:19], 0.5, v[116:117] op_sel_hi:[1,0,1] neg_lo:[0,0,1] neg_hi:[0,0,1]
	v_pk_fma_f32 v[22:23], v[16:17], 0.5, v[118:119] op_sel_hi:[1,0,1] neg_lo:[0,0,1] neg_hi:[0,0,1]
	s_waitcnt vmcnt(3)
	v_pk_fma_f32 v[24:25], v[46:47], v[74:75], v[114:115] neg_lo:[0,0,1] neg_hi:[0,0,1]
	v_cvt_pk_bf16_f32 v22, v22, v23
	v_cvt_pk_bf16_f32 v23, v20, v21
	v_add_co_u32_e32 v20, vcc, s7, v40
	v_pk_mul_f32 v[90:91], v[10:11], v[58:59]
	s_nop 0
	v_addc_co_u32_e32 v21, vcc, 0, v41, vcc
	global_store_dwordx2 v[20:21], v[22:23], off offset:-4096
	v_pk_fma_f32 v[22:23], v[48:49], v[76:77], v[112:113] neg_lo:[0,0,1] neg_hi:[0,0,1]
	v_pk_mul_f32 v[92:93], v[8:9], v[78:79]
	v_pk_mul_f32 v[122:123], v[46:47], v[74:75]
	v_pk_add_f32 v[18:19], v[18:19], v[22:23]
	v_pk_add_f32 v[16:17], v[16:17], v[24:25]
	v_pk_fma_f32 v[10:11], v[10:11], v[58:59], v[116:117] neg_lo:[0,0,1] neg_hi:[0,0,1]
	v_pk_fma_f32 v[8:9], v[8:9], v[78:79], v[118:119] neg_lo:[0,0,1] neg_hi:[0,0,1]
	v_pk_mul_f32 v[106:107], v[12:13], v[80:81]
	v_pk_mul_f32 v[120:121], v[48:49], v[76:77]
	v_pk_add_f32 v[10:11], v[18:19], v[10:11]
	v_pk_add_f32 v[8:9], v[16:17], v[8:9]
	v_pk_fma_f32 v[12:13], v[12:13], v[80:81], v[122:123] neg_lo:[0,0,1] neg_hi:[0,0,1]
	v_pk_mul_f32 v[88:89], v[4:5], v[84:85]
	v_pk_mul_f32 v[94:95], v[14:15], v[82:83]
	v_pk_fma_f32 v[22:23], v[18:19], 0.5, v[120:121] op_sel_hi:[1,0,1] neg_lo:[0,0,1] neg_hi:[0,0,1]
	v_pk_fma_f32 v[24:25], v[16:17], 0.5, v[122:123] op_sel_hi:[1,0,1] neg_lo:[0,0,1] neg_hi:[0,0,1]
	v_pk_fma_f32 v[16:17], v[10:11], 0.5, v[90:91] op_sel_hi:[1,0,1] neg_lo:[0,0,1] neg_hi:[0,0,1]
	v_pk_fma_f32 v[18:19], v[8:9], 0.5, v[92:93] op_sel_hi:[1,0,1] neg_lo:[0,0,1] neg_hi:[0,0,1]
	v_pk_fma_f32 v[14:15], v[14:15], v[82:83], v[120:121] neg_lo:[0,0,1] neg_hi:[0,0,1]
	v_pk_add_f32 v[8:9], v[8:9], v[12:13]
	v_pk_fma_f32 v[4:5], v[4:5], v[84:85], v[92:93] neg_lo:[0,0,1] neg_hi:[0,0,1]
	v_pk_mul_f32 v[86:87], v[6:7], v[60:61]
	v_cvt_pk_bf16_f32 v24, v24, v25
	v_cvt_pk_bf16_f32 v25, v22, v23
	global_store_dwordx2 v[20:21], v[24:25], off
	v_cvt_pk_bf16_f32 v18, v18, v19
	v_cvt_pk_bf16_f32 v19, v16, v17
	v_add_co_u32_e32 v16, vcc, s77, v40
	v_pk_add_f32 v[10:11], v[10:11], v[14:15]
	v_pk_fma_f32 v[6:7], v[6:7], v[60:61], v[90:91] neg_lo:[0,0,1] neg_hi:[0,0,1]
	v_pk_add_f32 v[4:5], v[8:9], v[4:5]
	v_addc_co_u32_e32 v17, vcc, 0, v41, vcc
	v_pk_fma_f32 v[14:15], v[8:9], 0.5, v[106:107] op_sel_hi:[1,0,1] neg_lo:[0,0,1] neg_hi:[0,0,1]
	v_pk_add_f32 v[6:7], v[10:11], v[6:7]
	v_pk_fma_f32 v[4:5], v[4:5], 0.5, v[88:89] op_sel_hi:[1,0,1] neg_lo:[0,0,1] neg_hi:[0,0,1]
	global_store_dwordx2 v[16:17], v[18:19], off offset:-4096
	v_pk_fma_f32 v[12:13], v[10:11], 0.5, v[94:95] op_sel_hi:[1,0,1] neg_lo:[0,0,1] neg_hi:[0,0,1]
	v_cvt_pk_bf16_f32 v14, v14, v15
	v_pk_fma_f32 v[6:7], v[6:7], 0.5, v[86:87] op_sel_hi:[1,0,1] neg_lo:[0,0,1] neg_hi:[0,0,1]
	v_cvt_pk_bf16_f32 v15, v12, v13
	global_store_dwordx2 v[16:17], v[14:15], off
	v_cvt_pk_bf16_f32 v4, v4, v5
	v_cvt_pk_bf16_f32 v5, v6, v7

; #define LAS __attribute__((address_space(3)))
; __device__ __forceinline__ unsigned cvt_pk_bf16(float lo, float hi) { unsigned r; asm volatile("v_cvt_pk_bf16_f32 %0, %1, %2" : "=v"(r) : "v"(lo), "v"(hi)); return r; }
; template <bool BF, int W> __device__ __forceinline__ void poolp_chunk(const void* xsrc, size_t xb0, int s_base, int s0, int c, f32x4 g4, const LAS float* rinv, bf16_t* Pout) {
;     f32x4 h[W + 8];
; #pragma unroll
;     for (int r = 0; r < W + 8; ++r) {
;         const int s = s_base - W + r;
;         if (s >= 0) h[r] = ld4<BF>(xsrc, xb0 + (size_t)s * D + c) * (g4 * rinv[s - s0 + 16]);
;         else h[r] = (f32x4){0.f, 0.f, 0.f, 0.f};
;     }
;     f32x4 S = (f32x4){0.f, 0.f, 0.f, 0.f};
; #pragma unroll
;     for (int i = 0; i < W; ++i) S += h[i];
; #pragma unroll
;     for (int tt = 0; tt < 8; ++tt) {
;         const int s = s_base + tt;
;         S += h[W + tt] - h[tt];
;         const float inv = 1.0f / (float)min(s + 1, W);
;         const f32x4 pv = S * inv - h[W + tt];
;         u32x2 o; o.x = cvt_pk_bf16(pv[0], pv[1]); o.y = cvt_pk_bf16(pv[2], pv[3]);
;         *(u32x2*)(Pout + (size_t)tt * D) = o;
;     }
.LBB0_1450:
	v_add_co_u32_e32 v4, vcc, 0xffff2000, v38
	v_mov_b32_e32 v82, s22
	s_nop 0
	v_addc_co_u32_e32 v5, vcc, -1, v39, vcc
	global_load_dwordx4 v[32:35], v[4:5], off
	v_add_co_u32_e32 v4, vcc, s50, v38
	s_min_i32 s26, s23, 7
	s_nop 0
	v_addc_co_u32_e32 v5, vcc, -1, v39, vcc
	v_add_co_u32_e32 v6, vcc, s54, v38
	v_pk_add_f32 v[74:75], v[72:73], 0 op_sel_hi:[1,0]
	s_nop 0
	v_addc_co_u32_e32 v7, vcc, -1, v39, vcc
	global_load_dwordx4 v[28:31], v[4:5], off
	global_load_dwordx4 v[20:23], v[6:7], off
	v_add_co_u32_e32 v8, vcc, s49, v38
	global_load_dwordx4 v[4:7], v[38:39], off
	s_nop 0
	v_addc_co_u32_e32 v9, vcc, -1, v39, vcc
	v_add_co_u32_e32 v10, vcc, s94, v38
	v_xor_b32_e32 v73, 0x80000000, v73
	s_nop 0
	v_addc_co_u32_e32 v11, vcc, -1, v39, vcc
	v_add_co_u32_e32 v16, vcc, s55, v38
	global_load_dwordx4 v[12:15], v[8:9], off
	global_load_dwordx4 v[8:11], v[10:11], off
	v_addc_co_u32_e32 v17, vcc, -1, v39, vcc
	global_load_dwordx4 v[24:27], v[16:17], off
	v_add_co_u32_e32 v16, vcc, s48, v38
	v_xor_b32_e32 v72, 0x80000000, v72
	s_nop 0
	v_addc_co_u32_e32 v17, vcc, -1, v39, vcc
	global_load_dwordx4 v[16:19], v[16:17], off
	ds_read2_b32 v[76:77], v82 offset0:16 offset1:17
	ds_read2_b32 v[78:79], v82 offset0:18 offset1:19
	ds_read2_b32 v[80:81], v82 offset0:20 offset1:21
	ds_read2_b32 v[82:83], v82 offset0:22 offset1:23
	s_add_i32 s26, s26, 1
	s_waitcnt vmcnt(8) lgkmcnt(3)
	v_pk_mul_f32 v[130:131], v[2:3], v[76:77] op_sel_hi:[1,0]
	v_pk_add_f32 v[124:125], v[68:69], 0 op_sel_hi:[1,0]
	v_pk_mul_f32 v[128:129], v[0:1], v[76:77] op_sel_hi:[1,0]
	v_pk_add_f32 v[124:125], v[124:125], v[50:51]
	v_xor_b32_e32 v69, 0x80000000, v69
	v_pk_add_f32 v[124:125], v[124:125], v[62:63]
	v_xor_b32_e32 v68, 0x80000000, v68
	v_pk_add_f32 v[124:125], v[124:125], v[46:47]
	v_pk_add_f32 v[126:127], v[74:75], v[70:71]
	v_pk_add_f32 v[124:125], v[124:125], v[56:57]
	v_pk_add_f32 v[126:127], v[126:127], v[66:67]
	v_pk_add_f32 v[124:125], v[124:125], v[44:45]
	v_pk_add_f32 v[126:127], v[126:127], v[64:65]
	v_pk_add_f32 v[124:125], v[124:125], v[48:49]
	v_pk_add_f32 v[126:127], v[126:127], v[60:61]
	v_pk_add_f32 v[124:125], v[124:125], v[42:43]
	v_pk_add_f32 v[126:127], v[126:127], v[58:59]
	s_add_i32 s25, s23, 1
	v_pk_add_f32 v[126:127], v[126:127], v[54:55]
	s_min_i32 s25, s25, 7
	v_pk_add_f32 v[126:127], v[126:127], v[52:53]
	v_pk_mul_f32 v[134:135], v[2:3], v[76:77] op_sel:[0,1]
	s_add_i32 s25, s25, 1
	v_pk_mul_f32 v[132:133], v[0:1], v[76:77] op_sel:[0,1]
	v_xor_b32_e32 v51, 0x80000000, v51
	v_xor_b32_e32 v50, 0x80000000, v50
	s_add_i32 s24, s23, 2
	s_min_i32 s24, s24, 7
	s_add_i32 s24, s24, 1
	s_waitcnt lgkmcnt(2)
	v_pk_mul_f32 v[138:139], v[2:3], v[78:79] op_sel_hi:[1,0]
	v_pk_mul_f32 v[136:137], v[0:1], v[78:79] op_sel_hi:[1,0]
	s_add_i32 s19, s23, 3
	s_min_i32 s19, s19, 7
	s_add_i32 s19, s19, 1
	v_pk_mul_f32 v[122:123], v[2:3], v[78:79] op_sel:[0,1]
	v_pk_mul_f32 v[116:117], v[0:1], v[78:79] op_sel:[0,1]
	s_add_i32 s18, s23, 4
	s_min_i32 s18, s18, 7
	s_add_i32 s18, s18, 1
	s_waitcnt lgkmcnt(1)
	v_pk_mul_f32 v[114:115], v[2:3], v[80:81] op_sel_hi:[1,0]
	v_pk_mul_f32 v[108:109], v[0:1], v[80:81] op_sel_hi:[1,0]
	s_add_i32 s11, s23, 5
	s_min_i32 s11, s11, 7
	s_add_i32 s11, s11, 1
	s_waitcnt vmcnt(7)
	v_pk_mul_f32 v[140:141], v[34:35], v[130:131]
	v_pk_fma_f32 v[34:35], v[34:35], v[130:131], v[72:73]
	v_cvt_f32_u32_e32 v72, s26
	v_pk_mul_f32 v[142:143], v[32:33], v[128:129]
	v_pk_fma_f32 v[32:33], v[32:33], v[128:129], v[68:69]
	v_pk_add_f32 v[34:35], v[126:127], v[34:35]
	v_div_scale_f32 v73, s[26:27], v72, v72, 1.0
	v_rcp_f32_e32 v130, v73
	v_pk_add_f32 v[32:33], v[124:125], v[32:33]
	s_waitcnt vmcnt(6)
	v_pk_mul_f32 v[144:145], v[30:31], v[134:135]
	v_pk_mul_f32 v[146:147], v[28:29], v[132:133]
	v_fma_f32 v68, -v73, v130, 1.0
	v_fmac_f32_e32 v130, v68, v130
	v_div_scale_f32 v68, vcc, 1.0, v72, 1.0
	v_mul_f32_e32 v69, v68, v130
	v_fma_f32 v124, -v73, v69, v68
	v_fmac_f32_e32 v69, v124, v130
	v_fma_f32 v68, -v73, v69, v68
	v_div_fmas_f32 v68, v68, v130, v69
	v_div_fixup_f32 v68, v68, v72, 1.0
	v_pk_fma_f32 v[72:73], v[68:69], v[34:35], v[140:141] op_sel_hi:[0,1,1] neg_lo:[0,0,1] neg_hi:[0,0,1]
	v_pk_fma_f32 v[68:69], v[68:69], v[32:33], v[142:143] op_sel_hi:[0,1,1] neg_lo:[0,0,1] neg_hi:[0,0,1]
	v_cvt_pk_bf16_f32 v68, v68, v69
	v_cvt_pk_bf16_f32 v69, v72, v73
	global_store_dwordx2 v[40:41], v[68:69], off
	v_xor_b32_e32 v69, 0x80000000, v71
	v_xor_b32_e32 v68, 0x80000000, v70
	v_pk_fma_f32 v[30:31], v[30:31], v[134:135], v[68:69]
	v_cvt_f32_u32_e32 v68, s25
	v_pk_fma_f32 v[28:29], v[28:29], v[132:133], v[50:51]
	v_pk_add_f32 v[30:31], v[34:35], v[30:31]
	v_pk_add_f32 v[28:29], v[32:33], v[28:29]
	v_div_scale_f32 v69, s[26:27], v68, v68, 1.0
	v_rcp_f32_e32 v70, v69
	v_cvt_f32_u32_e32 v50, s24
	s_waitcnt vmcnt(6)
; __device__ __forceinline__ unsigned cvt_pk_bf16(float lo, float hi) { unsigned r; asm volatile("v_cvt_pk_bf16_f32 %0, %1, %2" : "=v"(r) : "v"(lo), "v"(hi)); return r; }
; template <bool BF, int W> __device__ __forceinline__ void poolp_chunk(const void* xsrc, size_t xb0, int s_base, int s0, int c, f32x4 g4, const LAS float* rinv, bf16_t* Pout) {
;     ...
;     for (int tt = 0; tt < 8; ++tt) {
;         const int s = s_base + tt;
;         S += h[W + tt] - h[tt];
;         const float inv = 1.0f / (float)min(s + 1, W);
;         const f32x4 pv = S * inv - h[W + tt];
;         u32x2 o; o.x = cvt_pk_bf16(pv[0], pv[1]); o.y = cvt_pk_bf16(pv[2], pv[3]);
;         *(u32x2*)(Pout + (size_t)tt * D) = o;
	v_pk_mul_f32 v[148:149], v[22:23], v[138:139]
	v_pk_mul_f32 v[150:151], v[20:21], v[136:137]
	v_fma_f32 v32, -v69, v70, 1.0
	v_fmac_f32_e32 v70, v32, v70
	v_div_scale_f32 v32, vcc, 1.0, v68, 1.0
	v_mul_f32_e32 v33, v32, v70
	v_fma_f32 v34, -v69, v33, v32
	v_fmac_f32_e32 v33, v34, v70
	v_fma_f32 v32, -v69, v33, v32
	v_div_fmas_f32 v32, v32, v70, v33
	v_div_fixup_f32 v32, v32, v68, 1.0
	v_pk_fma_f32 v[34:35], v[32:33], v[30:31], v[144:145] op_sel_hi:[0,1,1] neg_lo:[0,0,1] neg_hi:[0,0,1]
	v_pk_fma_f32 v[32:33], v[32:33], v[28:29], v[146:147] op_sel_hi:[0,1,1] neg_lo:[0,0,1] neg_hi:[0,0,1]
	v_cvt_pk_bf16_f32 v32, v32, v33
	v_cvt_pk_bf16_f32 v33, v34, v35
	v_add_co_u32_e32 v34, vcc, s5, v40
	v_div_scale_f32 v51, s[24:25], v50, v50, 1.0
	s_nop 0
	v_addc_co_u32_e32 v35, vcc, 0, v41, vcc
	global_store_dwordx2 v[34:35], v[32:33], off offset:-4096
	v_xor_b32_e32 v33, 0x80000000, v67
	v_xor_b32_e32 v32, 0x80000000, v66
	v_pk_fma_f32 v[22:23], v[22:23], v[138:139], v[32:33]
	v_xor_b32_e32 v32, 0x80000000, v62
	v_rcp_f32_e32 v62, v51
	v_xor_b32_e32 v33, 0x80000000, v63
	v_pk_fma_f32 v[20:21], v[20:21], v[136:137], v[32:33]
	v_pk_add_f32 v[22:23], v[30:31], v[22:23]
	v_pk_add_f32 v[20:21], v[28:29], v[20:21]
	v_fma_f32 v28, -v51, v62, 1.0
	v_fmac_f32_e32 v62, v28, v62
	v_div_scale_f32 v28, vcc, 1.0, v50, 1.0
	v_mul_f32_e32 v29, v28, v62
	v_fma_f32 v30, -v51, v29, v28
	v_fmac_f32_e32 v29, v30, v62
	v_fma_f32 v28, -v51, v29, v28
	v_div_fmas_f32 v28, v28, v62, v29
	v_div_fixup_f32 v28, v28, v50, 1.0
	v_pk_fma_f32 v[30:31], v[28:29], v[22:23], v[148:149] op_sel_hi:[0,1,1] neg_lo:[0,0,1] neg_hi:[0,0,1]
	v_pk_fma_f32 v[28:29], v[28:29], v[20:21], v[150:151] op_sel_hi:[0,1,1] neg_lo:[0,0,1] neg_hi:[0,0,1]
	v_cvt_pk_bf16_f32 v28, v28, v29
	v_cvt_pk_bf16_f32 v29, v30, v31
	v_cvt_f32_u32_e32 v30, s19
	global_store_dwordx2 v[34:35], v[28:29], off
	v_xor_b32_e32 v29, 0x80000000, v65
	v_xor_b32_e32 v28, 0x80000000, v64
	v_div_scale_f32 v31, s[24:25], v30, v30, 1.0
	v_rcp_f32_e32 v32, v31
	s_waitcnt vmcnt(4)
	v_pk_mul_f32 v[118:119], v[26:27], v[122:123]
	v_pk_fma_f32 v[26:27], v[26:27], v[122:123], v[28:29]
	v_xor_b32_e32 v29, 0x80000000, v47
	v_xor_b32_e32 v28, 0x80000000, v46
	v_pk_mul_f32 v[120:121], v[24:25], v[116:117]
	v_pk_fma_f32 v[24:25], v[24:25], v[116:117], v[28:29]
	v_pk_add_f32 v[22:23], v[22:23], v[26:27]
	v_pk_add_f32 v[20:21], v[20:21], v[24:25]
	v_fma_f32 v24, -v31, v32, 1.0
	v_fmac_f32_e32 v32, v24, v32
	v_div_scale_f32 v24, vcc, 1.0, v30, 1.0
	v_mul_f32_e32 v25, v24, v32
	v_fma_f32 v26, -v31, v25, v24
	v_fmac_f32_e32 v25, v26, v32
	v_fma_f32 v24, -v31, v25, v24
	v_cvt_f32_u32_e32 v28, s18
	v_div_fmas_f32 v24, v24, v32, v25
	v_div_fixup_f32 v24, v24, v30, 1.0
	v_pk_fma_f32 v[26:27], v[24:25], v[22:23], v[118:119] op_sel_hi:[0,1,1] neg_lo:[0,0,1] neg_hi:[0,0,1]
	v_pk_fma_f32 v[24:25], v[24:25], v[20:21], v[120:121] op_sel_hi:[0,1,1] neg_lo:[0,0,1] neg_hi:[0,0,1]
	v_cvt_pk_bf16_f32 v24, v24, v25
	v_cvt_pk_bf16_f32 v25, v26, v27
	v_add_co_u32_e32 v26, vcc, s7, v40
	v_div_scale_f32 v29, s[18:19], v28, v28, 1.0
	s_nop 0
	v_addc_co_u32_e32 v27, vcc, 0, v41, vcc
	v_rcp_f32_e32 v30, v29
	global_store_dwordx2 v[26:27], v[24:25], off offset:-4096
	v_xor_b32_e32 v25, 0x80000000, v61
	v_xor_b32_e32 v24, 0x80000000, v60
	s_waitcnt vmcnt(4)
; __device__ __forceinline__ unsigned cvt_pk_bf16(float lo, float hi) { unsigned r; asm volatile("v_cvt_pk_bf16_f32 %0, %1, %2" : "=v"(r) : "v"(lo), "v"(hi)); return r; }
; template <bool BF, int W> __device__ __forceinline__ void poolp_chunk(const void* xsrc, size_t xb0, int s_base, int s0, int c, f32x4 g4, const LAS float* rinv, bf16_t* Pout) {
;     ...
;     for (int tt = 0; tt < 8; ++tt) {
;         const int s = s_base + tt;
;         S += h[W + tt] - h[tt];
;         const float inv = 1.0f / (float)min(s + 1, W);
;         const f32x4 pv = S * inv - h[W + tt];
;         u32x2 o; o.x = cvt_pk_bf16(pv[0], pv[1]); o.y = cvt_pk_bf16(pv[2], pv[3]);
;         *(u32x2*)(Pout + (size_t)tt * D) = o;
	v_pk_mul_f32 v[110:111], v[18:19], v[114:115]
	v_pk_fma_f32 v[18:19], v[18:19], v[114:115], v[24:25]
	v_xor_b32_e32 v25, 0x80000000, v57
	v_xor_b32_e32 v24, 0x80000000, v56
	v_pk_mul_f32 v[112:113], v[16:17], v[108:109]
	v_pk_fma_f32 v[16:17], v[16:17], v[108:109], v[24:25]
	v_pk_add_f32 v[18:19], v[22:23], v[18:19]
	v_pk_add_f32 v[16:17], v[20:21], v[16:17]
	v_fma_f32 v20, -v29, v30, 1.0
	v_fmac_f32_e32 v30, v20, v30
	v_div_scale_f32 v20, vcc, 1.0, v28, 1.0
	v_mul_f32_e32 v21, v20, v30
	v_fma_f32 v22, -v29, v21, v20
	v_fmac_f32_e32 v21, v22, v30
	v_fma_f32 v20, -v29, v21, v20
	v_div_fmas_f32 v20, v20, v30, v21
	v_div_fixup_f32 v20, v20, v28, 1.0
	v_pk_fma_f32 v[22:23], v[20:21], v[18:19], v[110:111] op_sel_hi:[0,1,1] neg_lo:[0,0,1] neg_hi:[0,0,1]
	v_pk_fma_f32 v[20:21], v[20:21], v[16:17], v[112:113] op_sel_hi:[0,1,1] neg_lo:[0,0,1] neg_hi:[0,0,1]
	v_cvt_pk_bf16_f32 v20, v20, v21
	v_cvt_pk_bf16_f32 v21, v22, v23
	v_cvt_f32_u32_e32 v22, s11
	v_pk_mul_f32 v[106:107], v[2:3], v[80:81] op_sel:[0,1]
	global_store_dwordx2 v[26:27], v[20:21], off
	v_xor_b32_e32 v21, 0x80000000, v59
	v_div_scale_f32 v23, s[18:19], v22, v22, 1.0
	v_rcp_f32_e32 v24, v23
	v_xor_b32_e32 v20, 0x80000000, v58
	v_pk_mul_f32 v[94:95], v[0:1], v[80:81] op_sel:[0,1]
	v_pk_mul_f32 v[90:91], v[14:15], v[106:107]
	v_pk_fma_f32 v[14:15], v[14:15], v[106:107], v[20:21]
	v_xor_b32_e32 v21, 0x80000000, v45
	v_xor_b32_e32 v20, 0x80000000, v44
	v_pk_mul_f32 v[92:93], v[12:13], v[94:95]
	v_pk_fma_f32 v[12:13], v[12:13], v[94:95], v[20:21]
	s_add_i32 s10, s23, 6
	v_pk_add_f32 v[12:13], v[16:17], v[12:13]
	v_fma_f32 v16, -v23, v24, 1.0
	v_fmac_f32_e32 v24, v16, v24
	v_div_scale_f32 v16, vcc, 1.0, v22, 1.0
	v_mul_f32_e32 v17, v16, v24
	v_pk_add_f32 v[14:15], v[18:19], v[14:15]
	v_fma_f32 v18, -v23, v17, v16
	s_min_i32 s10, s10, 7
	v_fmac_f32_e32 v17, v18, v24
	s_add_i32 s10, s10, 1
	v_fma_f32 v16, -v23, v17, v16
	v_cvt_f32_u32_e32 v20, s10
	v_div_fmas_f32 v16, v16, v24, v17
	v_div_fixup_f32 v16, v16, v22, 1.0
	v_pk_fma_f32 v[18:19], v[16:17], v[14:15], v[90:91] op_sel_hi:[0,1,1] neg_lo:[0,0,1] neg_hi:[0,0,1]
	v_pk_fma_f32 v[16:17], v[16:17], v[12:13], v[92:93] op_sel_hi:[0,1,1] neg_lo:[0,0,1] neg_hi:[0,0,1]
	v_cvt_pk_bf16_f32 v16, v16, v17
	v_cvt_pk_bf16_f32 v17, v18, v19
	v_add_co_u32_e32 v18, vcc, s77, v40
	v_div_scale_f32 v21, s[10:11], v20, v20, 1.0
	s_nop 0
	v_addc_co_u32_e32 v19, vcc, 0, v41, vcc
	v_rcp_f32_e32 v22, v21
	s_waitcnt lgkmcnt(0)
	v_pk_mul_f32 v[88:89], v[2:3], v[82:83] op_sel_hi:[1,0]
	global_store_dwordx2 v[18:19], v[16:17], off offset:-4096
	v_xor_b32_e32 v17, 0x80000000, v55
	v_xor_b32_e32 v16, 0x80000000, v54
	v_pk_mul_f32 v[86:87], v[0:1], v[82:83] op_sel_hi:[1,0]
	v_pk_mul_f32 v[78:79], v[0:1], v[82:83] op_sel:[0,1]
	v_pk_mul_f32 v[80:81], v[2:3], v[82:83] op_sel:[0,1]
	v_pk_mul_f32 v[82:83], v[10:11], v[88:89]
	v_pk_fma_f32 v[10:11], v[10:11], v[88:89], v[16:17]
	v_xor_b32_e32 v17, 0x80000000, v49
	v_xor_b32_e32 v16, 0x80000000, v48
	v_pk_mul_f32 v[84:85], v[8:9], v[86:87]
	v_pk_fma_f32 v[8:9], v[8:9], v[86:87], v[16:17]
	v_pk_add_f32 v[10:11], v[14:15], v[10:11]
	v_pk_add_f32 v[8:9], v[12:13], v[8:9]
	v_fma_f32 v12, -v21, v22, 1.0
	v_fmac_f32_e32 v22, v12, v22
	v_div_scale_f32 v12, vcc, 1.0, v20, 1.0
	v_mul_f32_e32 v13, v12, v22
	v_fma_f32 v14, -v21, v13, v12
	v_fmac_f32_e32 v13, v14, v22
	v_fma_f32 v12, -v21, v13, v12
	v_div_fmas_f32 v12, v12, v22, v13
	v_div_fixup_f32 v12, v12, v20, 1.0
	v_pk_fma_f32 v[14:15], v[12:13], v[10:11], v[82:83] op_sel_hi:[0,1,1] neg_lo:[0,0,1] neg_hi:[0,0,1]
	v_pk_fma_f32 v[12:13], v[12:13], v[8:9], v[84:85] op_sel_hi:[0,1,1] neg_lo:[0,0,1] neg_hi:[0,0,1]
	v_cvt_pk_bf16_f32 v12, v12, v13
	v_cvt_pk_bf16_f32 v13, v14, v15
	global_store_dwordx2 v[18:19], v[12:13], off
	v_xor_b32_e32 v13, 0x80000000, v53
	v_xor_b32_e32 v12, 0x80000000, v52
	v_pk_mul_f32 v[74:75], v[6:7], v[80:81]
	v_pk_fma_f32 v[6:7], v[6:7], v[80:81], v[12:13]
	v_xor_b32_e32 v13, 0x80000000, v43
	v_xor_b32_e32 v12, 0x80000000, v42
	v_pk_mul_f32 v[76:77], v[4:5], v[78:79]
	v_pk_fma_f32 v[4:5], v[4:5], v[78:79], v[12:13]
	v_pk_add_f32 v[6:7], v[10:11], v[6:7]
	v_pk_add_f32 v[4:5], v[8:9], v[4:5]
	s_xor_b64 s[10:11], exec, -1
	v_pk_fma_f32 v[4:5], v[4:5], s[56:57], v[76:77] op_sel_hi:[1,0,1] neg_lo:[0,0,1] neg_hi:[0,0,1]
	v_pk_fma_f32 v[6:7], v[6:7], s[56:57], v[74:75] op_sel_hi:[1,0,1] neg_lo:[0,0,1] neg_hi:[0,0,1]
	v_cvt_pk_bf16_f32 v4, v4, v5
	s_nop 0
	v_cvt_pk_bf16_f32 v5, v6, v7

; #define LAS __attribute__((address_space(3)))
; __device__ __forceinline__ unsigned cvt_pk_bf16(float lo, float hi) { unsigned r; asm volatile("v_cvt_pk_bf16_f32 %0, %1, %2" : "=v"(r) : "v"(lo), "v"(hi)); return r; }
; template <bool BF, int W> __device__ __forceinline__ void poolp_chunk(const void* xsrc, size_t xb0, int s_base, int s0, int c, f32x4 g4, const LAS float* rinv, bf16_t* Pout) {
;     f32x4 h[W + 8];
; #pragma unroll
;     for (int r = 0; r < W + 8; ++r) {
;         const int s = s_base - W + r;
;         if (s >= 0) h[r] = ld4<BF>(xsrc, xb0 + (size_t)s * D + c) * (g4 * rinv[s - s0 + 16]);
;         else h[r] = (f32x4){0.f, 0.f, 0.f, 0.f};
;     }
;     f32x4 S = (f32x4){0.f, 0.f, 0.f, 0.f};
; #pragma unroll
;     for (int i = 0; i < W; ++i) S += h[i];
; #pragma unroll
;     for (int tt = 0; tt < 8; ++tt) {
;         const int s = s_base + tt;
;         S += h[W + tt] - h[tt];
;         const float inv = 1.0f / (float)min(s + 1, W);
;         const f32x4 pv = S * inv - h[W + tt];
;         u32x2 o; o.x = cvt_pk_bf16(pv[0], pv[1]); o.y = cvt_pk_bf16(pv[2], pv[3]);
;         *(u32x2*)(Pout + (size_t)tt * D) = o;
;     }
.LBB0_1461:
	v_add_co_u32_e32 v4, vcc, 0xffff2000, v38
	v_mov_b32_e32 v68, s22
	s_nop 0
	v_addc_co_u32_e32 v5, vcc, -1, v39, vcc
	global_load_dwordx4 v[32:35], v[4:5], off
	v_add_co_u32_e32 v4, vcc, s50, v38
	s_min_i32 s18, s23, 3
	s_nop 0
	v_addc_co_u32_e32 v5, vcc, -1, v39, vcc
	v_add_co_u32_e32 v6, vcc, s54, v38
	v_pk_add_f32 v[60:61], v[56:57], 0 op_sel_hi:[1,0]
	s_nop 0
	v_addc_co_u32_e32 v7, vcc, -1, v39, vcc
	global_load_dwordx4 v[28:31], v[4:5], off
	global_load_dwordx4 v[16:19], v[6:7], off
	v_add_co_u32_e32 v8, vcc, s49, v38
	global_load_dwordx4 v[4:7], v[38:39], off
	s_nop 0
	v_addc_co_u32_e32 v9, vcc, -1, v39, vcc
	v_add_co_u32_e32 v10, vcc, s94, v38
	v_xor_b32_e32 v57, 0x80000000, v57
	s_nop 0
	v_addc_co_u32_e32 v11, vcc, -1, v39, vcc
	v_add_co_u32_e32 v20, vcc, s55, v38
	global_load_dwordx4 v[12:15], v[8:9], off
	global_load_dwordx4 v[8:11], v[10:11], off
	v_addc_co_u32_e32 v21, vcc, -1, v39, vcc
	global_load_dwordx4 v[24:27], v[20:21], off
	v_add_co_u32_e32 v20, vcc, s48, v38
	v_xor_b32_e32 v56, 0x80000000, v56
	s_nop 0
	v_addc_co_u32_e32 v21, vcc, -1, v39, vcc
	global_load_dwordx4 v[20:23], v[20:21], off
	ds_read2_b32 v[62:63], v68 offset0:16 offset1:17
	ds_read2_b32 v[64:65], v68 offset0:18 offset1:19
	ds_read2_b32 v[66:67], v68 offset0:20 offset1:21
	ds_read2_b32 v[68:69], v68 offset0:22 offset1:23
	s_add_i32 s18, s18, 1
	s_waitcnt vmcnt(8) lgkmcnt(3)
	v_pk_mul_f32 v[114:115], v[2:3], v[62:63] op_sel_hi:[1,0]
	v_pk_add_f32 v[58:59], v[52:53], 0 op_sel_hi:[1,0]
	v_pk_mul_f32 v[112:113], v[0:1], v[62:63] op_sel_hi:[1,0]
	v_xor_b32_e32 v53, 0x80000000, v53
	v_xor_b32_e32 v52, 0x80000000, v52
	v_pk_add_f32 v[58:59], v[58:59], v[44:45]
	v_pk_add_f32 v[60:61], v[60:61], v[54:55]
	v_pk_add_f32 v[108:109], v[58:59], v[46:47]
	v_pk_add_f32 v[58:59], v[60:61], v[50:51]
	v_pk_add_f32 v[108:109], v[108:109], v[42:43]
	v_pk_add_f32 v[110:111], v[58:59], v[48:49]
	s_add_i32 s11, s23, 1
	s_min_i32 s11, s11, 3
	v_pk_mul_f32 v[118:119], v[2:3], v[62:63] op_sel:[0,1]
	s_add_i32 s11, s11, 1
	v_pk_mul_f32 v[116:117], v[0:1], v[62:63] op_sel:[0,1]
	v_xor_b32_e32 v45, 0x80000000, v45
	v_xor_b32_e32 v44, 0x80000000, v44
	s_add_i32 s10, s23, 2
	s_min_i32 s10, s10, 3
	s_add_i32 s10, s10, 1
	s_waitcnt lgkmcnt(2)
	v_pk_mul_f32 v[122:123], v[2:3], v[64:65] op_sel_hi:[1,0]
	v_pk_mul_f32 v[120:121], v[0:1], v[64:65] op_sel_hi:[1,0]
	v_pk_mul_f32 v[126:127], v[2:3], v[64:65] op_sel:[0,1]
	v_pk_mul_f32 v[124:125], v[0:1], v[64:65] op_sel:[0,1]
	s_waitcnt lgkmcnt(1)
	v_pk_mul_f32 v[90:91], v[0:1], v[66:67] op_sel_hi:[1,0]
	v_pk_mul_f32 v[106:107], v[2:3], v[66:67] op_sel_hi:[1,0]
	v_pk_mul_f32 v[82:83], v[0:1], v[66:67] op_sel:[0,1]
	v_pk_mul_f32 v[84:85], v[2:3], v[66:67] op_sel:[0,1]
	s_waitcnt lgkmcnt(0)
	v_pk_mul_f32 v[66:67], v[0:1], v[68:69] op_sel_hi:[1,0]
	v_pk_mul_f32 v[72:73], v[2:3], v[68:69] op_sel_hi:[1,0]
	v_pk_mul_f32 v[62:63], v[0:1], v[68:69] op_sel:[0,1]
	v_pk_mul_f32 v[64:65], v[2:3], v[68:69] op_sel:[0,1]
	s_waitcnt vmcnt(7)
	v_pk_mul_f32 v[128:129], v[34:35], v[114:115]
	v_pk_fma_f32 v[34:35], v[34:35], v[114:115], v[56:57]
	v_cvt_f32_u32_e32 v56, s18
	v_pk_mul_f32 v[130:131], v[32:33], v[112:113]
	v_pk_fma_f32 v[32:33], v[32:33], v[112:113], v[52:53]
	v_pk_add_f32 v[34:35], v[110:111], v[34:35]
	v_div_scale_f32 v57, s[18:19], v56, v56, 1.0
	v_rcp_f32_e32 v114, v57
	v_pk_add_f32 v[32:33], v[108:109], v[32:33]
	s_waitcnt vmcnt(6)
	v_pk_mul_f32 v[92:93], v[30:31], v[118:119]
	v_pk_mul_f32 v[94:95], v[28:29], v[116:117]
	v_fma_f32 v52, -v57, v114, 1.0
	v_fmac_f32_e32 v114, v52, v114
	v_div_scale_f32 v52, vcc, 1.0, v56, 1.0
	v_mul_f32_e32 v53, v52, v114
	v_fma_f32 v108, -v57, v53, v52
	v_fmac_f32_e32 v53, v108, v114
	v_fma_f32 v52, -v57, v53, v52
	v_div_fmas_f32 v52, v52, v114, v53
	v_div_fixup_f32 v52, v52, v56, 1.0
	v_pk_fma_f32 v[56:57], v[52:53], v[34:35], v[128:129] op_sel_hi:[0,1,1] neg_lo:[0,0,1] neg_hi:[0,0,1]
	v_pk_fma_f32 v[52:53], v[52:53], v[32:33], v[130:131] op_sel_hi:[0,1,1] neg_lo:[0,0,1] neg_hi:[0,0,1]
	v_cvt_pk_bf16_f32 v52, v52, v53
	v_cvt_pk_bf16_f32 v53, v56, v57
	global_store_dwordx2 v[40:41], v[52:53], off
	v_xor_b32_e32 v53, 0x80000000, v55
	v_xor_b32_e32 v52, 0x80000000, v54
	v_pk_fma_f32 v[30:31], v[30:31], v[118:119], v[52:53]
	v_cvt_f32_u32_e32 v52, s11
	v_pk_fma_f32 v[28:29], v[28:29], v[116:117], v[44:45]
	v_pk_add_f32 v[30:31], v[34:35], v[30:31]
	v_pk_add_f32 v[28:29], v[32:33], v[28:29]
	v_div_scale_f32 v53, s[18:19], v52, v52, 1.0
	v_rcp_f32_e32 v54, v53
	v_cvt_f32_u32_e32 v44, s10
	s_waitcnt vmcnt(6)
; __device__ __forceinline__ unsigned cvt_pk_bf16(float lo, float hi) { unsigned r; asm volatile("v_cvt_pk_bf16_f32 %0, %1, %2" : "=v"(r) : "v"(lo), "v"(hi)); return r; }
; template <bool BF, int W> __device__ __forceinline__ void poolp_chunk(const void* xsrc, size_t xb0, int s_base, int s0, int c, f32x4 g4, const LAS float* rinv, bf16_t* Pout) {
;     ...
;     for (int tt = 0; tt < 8; ++tt) {
;         const int s = s_base + tt;
;         S += h[W + tt] - h[tt];
;         const float inv = 1.0f / (float)min(s + 1, W);
;         const f32x4 pv = S * inv - h[W + tt];
;         u32x2 o; o.x = cvt_pk_bf16(pv[0], pv[1]); o.y = cvt_pk_bf16(pv[2], pv[3]);
;         *(u32x2*)(Pout + (size_t)tt * D) = o;
;     }
	v_pk_mul_f32 v[78:79], v[18:19], v[122:123]
	v_pk_mul_f32 v[80:81], v[16:17], v[120:121]
	v_fma_f32 v32, -v53, v54, 1.0
	v_fmac_f32_e32 v54, v32, v54
	v_div_scale_f32 v32, vcc, 1.0, v52, 1.0
	v_mul_f32_e32 v33, v32, v54
	v_fma_f32 v34, -v53, v33, v32
	v_fmac_f32_e32 v33, v34, v54
	v_fma_f32 v32, -v53, v33, v32
	v_div_fmas_f32 v32, v32, v54, v33
	v_div_fixup_f32 v32, v32, v52, 1.0
	v_pk_fma_f32 v[34:35], v[32:33], v[30:31], v[92:93] op_sel_hi:[0,1,1] neg_lo:[0,0,1] neg_hi:[0,0,1]
	v_pk_fma_f32 v[32:33], v[32:33], v[28:29], v[94:95] op_sel_hi:[0,1,1] neg_lo:[0,0,1] neg_hi:[0,0,1]
	v_cvt_pk_bf16_f32 v32, v32, v33
	v_cvt_pk_bf16_f32 v33, v34, v35
	v_add_co_u32_e32 v34, vcc, s5, v40
	v_div_scale_f32 v45, s[10:11], v44, v44, 1.0
	s_nop 0
	v_addc_co_u32_e32 v35, vcc, 0, v41, vcc
	global_store_dwordx2 v[34:35], v[32:33], off offset:-4096
	v_xor_b32_e32 v33, 0x80000000, v51
	v_xor_b32_e32 v32, 0x80000000, v50
	v_pk_fma_f32 v[18:19], v[18:19], v[122:123], v[32:33]
	v_xor_b32_e32 v32, 0x80000000, v46
	v_rcp_f32_e32 v46, v45
	v_xor_b32_e32 v33, 0x80000000, v47
	v_pk_fma_f32 v[16:17], v[16:17], v[120:121], v[32:33]
	v_pk_add_f32 v[18:19], v[30:31], v[18:19]
	v_pk_add_f32 v[16:17], v[28:29], v[16:17]
	v_fma_f32 v28, -v45, v46, 1.0
	v_fmac_f32_e32 v46, v28, v46
	v_div_scale_f32 v28, vcc, 1.0, v44, 1.0
	v_mul_f32_e32 v29, v28, v46
	v_fma_f32 v30, -v45, v29, v28
	v_fmac_f32_e32 v29, v30, v46
	v_fma_f32 v28, -v45, v29, v28
	v_div_fmas_f32 v28, v28, v46, v29
	v_div_fixup_f32 v28, v28, v44, 1.0
	v_pk_fma_f32 v[30:31], v[28:29], v[18:19], v[78:79] op_sel_hi:[0,1,1] neg_lo:[0,0,1] neg_hi:[0,0,1]
	v_pk_fma_f32 v[28:29], v[28:29], v[16:17], v[80:81] op_sel_hi:[0,1,1] neg_lo:[0,0,1] neg_hi:[0,0,1]
	v_cvt_pk_bf16_f32 v28, v28, v29
	v_cvt_pk_bf16_f32 v29, v30, v31
	global_store_dwordx2 v[34:35], v[28:29], off
	v_xor_b32_e32 v29, 0x80000000, v49
	v_xor_b32_e32 v28, 0x80000000, v48
	s_waitcnt vmcnt(4)
	v_pk_mul_f32 v[68:69], v[26:27], v[126:127]
	v_pk_fma_f32 v[26:27], v[26:27], v[126:127], v[28:29]
	v_xor_b32_e32 v29, 0x80000000, v43
	v_xor_b32_e32 v28, 0x80000000, v42
	v_pk_mul_f32 v[70:71], v[24:25], v[124:125]
	v_pk_fma_f32 v[24:25], v[24:25], v[124:125], v[28:29]
	s_waitcnt vmcnt(3)
	v_pk_mul_f32 v[132:133], v[22:23], v[106:107]
	v_pk_mul_f32 v[134:135], v[20:21], v[90:91]
	v_pk_add_f32 v[16:17], v[16:17], v[24:25]
	v_pk_add_f32 v[18:19], v[18:19], v[26:27]
	v_pk_fma_f32 v[22:23], v[22:23], v[106:107], v[128:129] neg_lo:[0,0,1] neg_hi:[0,0,1]
	v_pk_fma_f32 v[20:21], v[20:21], v[90:91], v[130:131] neg_lo:[0,0,1] neg_hi:[0,0,1]
	v_pk_mul_f32 v[86:87], v[14:15], v[84:85]
	v_pk_mul_f32 v[88:89], v[12:13], v[82:83]
	v_pk_fma_f32 v[24:25], v[18:19], s[6:7], v[68:69] op_sel_hi:[1,0,1] neg_lo:[0,0,1] neg_hi:[0,0,1]
	v_pk_fma_f32 v[26:27], v[16:17], s[6:7], v[70:71] op_sel_hi:[1,0,1] neg_lo:[0,0,1] neg_hi:[0,0,1]
	v_pk_add_f32 v[18:19], v[18:19], v[22:23]
	v_pk_add_f32 v[16:17], v[16:17], v[20:21]
	v_pk_fma_f32 v[14:15], v[14:15], v[84:85], v[92:93] neg_lo:[0,0,1] neg_hi:[0,0,1]
	v_pk_fma_f32 v[12:13], v[12:13], v[82:83], v[94:95] neg_lo:[0,0,1] neg_hi:[0,0,1]
	v_pk_mul_f32 v[76:77], v[8:9], v[66:67]
	v_cvt_pk_bf16_f32 v26, v26, v27
	v_cvt_pk_bf16_f32 v27, v24, v25
	v_add_co_u32_e32 v24, vcc, s7, v40
	v_pk_add_f32 v[14:15], v[18:19], v[14:15]
	v_pk_add_f32 v[12:13], v[16:17], v[12:13]
	v_pk_fma_f32 v[8:9], v[8:9], v[66:67], v[80:81] neg_lo:[0,0,1] neg_hi:[0,0,1]
	v_pk_mul_f32 v[60:61], v[4:5], v[62:63]
	v_pk_mul_f32 v[74:75], v[10:11], v[72:73]
	v_addc_co_u32_e32 v25, vcc, 0, v41, vcc
	v_pk_fma_f32 v[20:21], v[18:19], s[6:7], v[132:133] op_sel_hi:[1,0,1] neg_lo:[0,0,1] neg_hi:[0,0,1]
	v_pk_fma_f32 v[22:23], v[16:17], s[6:7], v[134:135] op_sel_hi:[1,0,1] neg_lo:[0,0,1] neg_hi:[0,0,1]
	v_pk_fma_f32 v[16:17], v[14:15], s[6:7], v[86:87] op_sel_hi:[1,0,1] neg_lo:[0,0,1] neg_hi:[0,0,1]
	v_pk_fma_f32 v[18:19], v[12:13], s[6:7], v[88:89] op_sel_hi:[1,0,1] neg_lo:[0,0,1] neg_hi:[0,0,1]
	v_pk_fma_f32 v[10:11], v[10:11], v[72:73], v[78:79] neg_lo:[0,0,1] neg_hi:[0,0,1]
	v_pk_add_f32 v[8:9], v[12:13], v[8:9]
	v_pk_fma_f32 v[4:5], v[4:5], v[62:63], v[70:71] neg_lo:[0,0,1] neg_hi:[0,0,1]
	v_pk_mul_f32 v[58:59], v[6:7], v[64:65]
	global_store_dwordx2 v[24:25], v[26:27], off offset:-4096
	v_cvt_pk_bf16_f32 v22, v22, v23
	v_cvt_pk_bf16_f32 v23, v20, v21
	global_store_dwordx2 v[24:25], v[22:23], off
	v_cvt_pk_bf16_f32 v18, v18, v19
	v_cvt_pk_bf16_f32 v19, v16, v17
	v_add_co_u32_e32 v16, vcc, s77, v40
	v_pk_add_f32 v[10:11], v[14:15], v[10:11]
	v_pk_fma_f32 v[6:7], v[6:7], v[64:65], v[68:69] neg_lo:[0,0,1] neg_hi:[0,0,1]
	v_pk_add_f32 v[4:5], v[8:9], v[4:5]
	v_addc_co_u32_e32 v17, vcc, 0, v41, vcc
	v_pk_fma_f32 v[14:15], v[8:9], s[6:7], v[76:77] op_sel_hi:[1,0,1] neg_lo:[0,0,1] neg_hi:[0,0,1]
	v_pk_add_f32 v[6:7], v[10:11], v[6:7]
	v_pk_fma_f32 v[4:5], v[4:5], s[6:7], v[60:61] op_sel_hi:[1,0,1] neg_lo:[0,0,1] neg_hi:[0,0,1]
	global_store_dwordx2 v[16:17], v[18:19], off offset:-4096
	v_pk_fma_f32 v[12:13], v[10:11], s[6:7], v[74:75] op_sel_hi:[1,0,1] neg_lo:[0,0,1] neg_hi:[0,0,1]
	v_cvt_pk_bf16_f32 v14, v14, v15
	v_pk_fma_f32 v[6:7], v[6:7], s[6:7], v[58:59] op_sel_hi:[1,0,1] neg_lo:[0,0,1] neg_hi:[0,0,1]
	v_cvt_pk_bf16_f32 v15, v12, v13
	global_store_dwordx2 v[16:17], v[14:15], off
	v_cvt_pk_bf16_f32 v4, v4, v5
	v_cvt_pk_bf16_f32 v5, v6, v7

; #define LAS __attribute__((address_space(3)))
; __device__ __forceinline__ unsigned cvt_pk_bf16(float lo, float hi) { unsigned r; asm volatile("v_cvt_pk_bf16_f32 %0, %1, %2" : "=v"(r) : "v"(lo), "v"(hi)); return r; }
; template <bool BF, int W> __device__ __forceinline__ void poolp_chunk(const void* xsrc, size_t xb0, int s_base, int s0, int c, f32x4 g4, const LAS float* rinv, bf16_t* Pout) {
;     f32x4 h[W + 8];
; #pragma unroll
;     for (int r = 0; r < W + 8; ++r) {
;         const int s = s_base - W + r;
;         if (s >= 0) h[r] = ld4<BF>(xsrc, xb0 + (size_t)s * D + c) * (g4 * rinv[s - s0 + 16]);
;         else h[r] = (f32x4){0.f, 0.f, 0.f, 0.f};
;     }
;     f32x4 S = (f32x4){0.f, 0.f, 0.f, 0.f};
; #pragma unroll
;     for (int i = 0; i < W; ++i) S += h[i];
; #pragma unroll
;     for (int tt = 0; tt < 8; ++tt) {
;         const int s = s_base + tt;
;         S += h[W + tt] - h[tt];
;         const float inv = 1.0f / (float)min(s + 1, W);
;         const f32x4 pv = S * inv - h[W + tt];
;         u32x2 o; o.x = cvt_pk_bf16(pv[0], pv[1]); o.y = cvt_pk_bf16(pv[2], pv[3]);
;         *(u32x2*)(Pout + (size_t)tt * D) = o;
.LBB0_1496:
	v_add_co_u32_e32 v4, vcc, 0xffff2000, v38
	v_mov_b32_e32 v94, s22
	s_nop 0
	v_addc_co_u32_e32 v5, vcc, -1, v39, vcc
	global_load_dwordx4 v[32:35], v[4:5], off
	v_add_co_u32_e32 v4, vcc, s50, v38
	v_pk_add_f32 v[180:181], v[68:69], 0 op_sel_hi:[1,0]
	s_nop 0
	v_addc_co_u32_e32 v5, vcc, -1, v39, vcc
	v_add_co_u32_e32 v6, vcc, s54, v38
	v_pk_add_f32 v[180:181], v[180:181], v[52:53]
	s_nop 0
	v_addc_co_u32_e32 v7, vcc, -1, v39, vcc
	global_load_dwordx4 v[28:31], v[4:5], off
	global_load_dwordx4 v[20:23], v[6:7], off
	v_add_co_u32_e32 v8, vcc, s49, v38
	global_load_dwordx4 v[4:7], v[38:39], off
	s_nop 0
	v_addc_co_u32_e32 v9, vcc, -1, v39, vcc
	v_add_co_u32_e32 v10, vcc, s94, v38
	v_pk_add_f32 v[180:181], v[180:181], v[62:63]
	s_nop 0
	v_addc_co_u32_e32 v11, vcc, -1, v39, vcc
	v_add_co_u32_e32 v16, vcc, s55, v38
	global_load_dwordx4 v[12:15], v[8:9], off
	global_load_dwordx4 v[8:11], v[10:11], off
	v_addc_co_u32_e32 v17, vcc, -1, v39, vcc
	global_load_dwordx4 v[24:27], v[16:17], off
	v_add_co_u32_e32 v16, vcc, s48, v38
	ds_read2_b32 v[82:83], v94 offset0:16 offset1:17
	s_nop 0
	v_addc_co_u32_e32 v17, vcc, -1, v39, vcc
	global_load_dwordx4 v[16:19], v[16:17], off
	s_min_i32 s19, s23, 15
	v_pk_add_f32 v[182:183], v[72:73], 0 op_sel_hi:[1,0]
	s_waitcnt vmcnt(8) lgkmcnt(0)
	v_pk_mul_f32 v[196:197], v[2:3], v[82:83] op_sel_hi:[1,0]
	v_pk_add_f32 v[180:181], v[180:181], v[46:47]
	v_xor_b32_e32 v73, 0x80000000, v73
	v_xor_b32_e32 v72, 0x80000000, v72
	s_add_i32 s19, s19, 1
	v_pk_add_f32 v[180:181], v[180:181], v[56:57]
	v_pk_add_f32 v[182:183], v[182:183], v[70:71]
	v_pk_add_f32 v[180:181], v[180:181], v[44:45]
	v_pk_add_f32 v[182:183], v[182:183], v[66:67]
	v_pk_add_f32 v[180:181], v[180:181], v[48:49]
	v_pk_add_f32 v[182:183], v[182:183], v[64:65]
	v_pk_add_f32 v[180:181], v[180:181], v[42:43]
	v_pk_add_f32 v[182:183], v[182:183], v[60:61]
	v_pk_add_f32 v[78:79], v[180:181], v[78:79]
	v_pk_add_f32 v[182:183], v[182:183], v[58:59]
	v_pk_add_f32 v[74:75], v[78:79], v[74:75]
	v_pk_add_f32 v[182:183], v[182:183], v[54:55]
	v_pk_add_f32 v[74:75], v[74:75], v[92:93]
	v_pk_add_f32 v[182:183], v[182:183], v[50:51]
	v_pk_add_f32 v[74:75], v[74:75], v[86:87]
	v_pk_mul_f32 v[184:185], v[0:1], v[82:83] op_sel_hi:[1,0]
	v_pk_add_f32 v[76:77], v[182:183], v[76:77]
	v_pk_add_f32 v[74:75], v[74:75], v[120:121]
	v_xor_b32_e32 v69, 0x80000000, v69
	v_xor_b32_e32 v68, 0x80000000, v68
	v_pk_add_f32 v[76:77], v[76:77], v[80:81]
	v_pk_add_f32 v[74:75], v[74:75], v[114:115]
	v_pk_add_f32 v[76:77], v[76:77], v[90:91]
	v_pk_add_f32 v[74:75], v[74:75], v[136:137]
	v_pk_add_f32 v[76:77], v[76:77], v[110:111]
	v_pk_add_f32 v[74:75], v[74:75], v[132:133]
	v_pk_add_f32 v[76:77], v[76:77], v[118:119]
	s_add_i32 s18, s23, 1
	v_pk_add_f32 v[76:77], v[76:77], v[128:129]
	ds_read2_b32 v[84:85], v94 offset0:18 offset1:19
	ds_read2_b32 v[88:89], v94 offset0:20 offset1:21
	ds_read2_b32 v[94:95], v94 offset0:22 offset1:23
	v_pk_add_f32 v[76:77], v[76:77], v[134:135]
	s_min_i32 s18, s18, 15
	v_pk_add_f32 v[76:77], v[76:77], v[146:147]
	v_pk_mul_f32 v[200:201], v[2:3], v[82:83] op_sel:[0,1]
	s_add_i32 s18, s18, 1
	v_pk_mul_f32 v[198:199], v[0:1], v[82:83] op_sel:[0,1]
	v_xor_b32_e32 v53, 0x80000000, v53
	v_xor_b32_e32 v52, 0x80000000, v52
	s_add_i32 s17, s23, 2
	s_waitcnt vmcnt(7)
	v_pk_mul_f32 v[208:209], v[34:35], v[196:197]
	v_pk_fma_f32 v[34:35], v[34:35], v[196:197], v[72:73]
	v_cvt_f32_u32_e32 v72, s19
	v_pk_mul_f32 v[210:211], v[32:33], v[184:185]
	v_pk_fma_f32 v[32:33], v[32:33], v[184:185], v[68:69]
	v_pk_add_f32 v[34:35], v[76:77], v[34:35]
	v_div_scale_f32 v73, s[24:25], v72, v72, 1.0
	v_rcp_f32_e32 v78, v73
	v_pk_add_f32 v[32:33], v[74:75], v[32:33]
	s_waitcnt vmcnt(6)
	v_pk_mul_f32 v[212:213], v[30:31], v[200:201]
	v_pk_mul_f32 v[214:215], v[28:29], v[198:199]
	v_fma_f32 v68, -v73, v78, 1.0
	v_fmac_f32_e32 v78, v68, v78
	v_div_scale_f32 v68, vcc, 1.0, v72, 1.0
	v_mul_f32_e32 v69, v68, v78
	v_fma_f32 v74, -v73, v69, v68
	v_fmac_f32_e32 v69, v74, v78
	v_fma_f32 v68, -v73, v69, v68
	v_div_fmas_f32 v68, v68, v78, v69
	v_div_fixup_f32 v68, v68, v72, 1.0
	v_pk_fma_f32 v[72:73], v[68:69], v[34:35], v[208:209] op_sel_hi:[0,1,1] neg_lo:[0,0,1] neg_hi:[0,0,1]
	v_pk_fma_f32 v[68:69], v[68:69], v[32:33], v[210:211] op_sel_hi:[0,1,1] neg_lo:[0,0,1] neg_hi:[0,0,1]
	v_cvt_pk_bf16_f32 v68, v68, v69
	v_cvt_pk_bf16_f32 v69, v72, v73
	global_store_dwordx2 v[40:41], v[68:69], off
	v_xor_b32_e32 v69, 0x80000000, v71
	v_xor_b32_e32 v68, 0x80000000, v70
	v_pk_fma_f32 v[30:31], v[30:31], v[200:201], v[68:69]
	v_cvt_f32_u32_e32 v68, s18
	v_pk_fma_f32 v[28:29], v[28:29], v[198:199], v[52:53]
	v_pk_add_f32 v[30:31], v[34:35], v[30:31]
	v_pk_add_f32 v[28:29], v[32:33], v[28:29]
	v_div_scale_f32 v69, s[18:19], v68, v68, 1.0
	v_rcp_f32_e32 v70, v69
	s_min_i32 s17, s17, 15
	s_add_i32 s17, s17, 1
	v_cvt_f32_u32_e32 v52, s17
	v_fma_f32 v32, -v69, v70, 1.0
	v_fmac_f32_e32 v70, v32, v70
	v_div_scale_f32 v32, vcc, 1.0, v68, 1.0
	v_mul_f32_e32 v33, v32, v70
	v_fma_f32 v34, -v69, v33, v32
	v_fmac_f32_e32 v33, v34, v70
	v_fma_f32 v32, -v69, v33, v32
	v_div_fmas_f32 v32, v32, v70, v33
	v_div_fixup_f32 v32, v32, v68, 1.0
	v_pk_fma_f32 v[34:35], v[32:33], v[30:31], v[212:213] op_sel_hi:[0,1,1] neg_lo:[0,0,1] neg_hi:[0,0,1]
	v_pk_fma_f32 v[32:33], v[32:33], v[28:29], v[214:215] op_sel_hi:[0,1,1] neg_lo:[0,0,1] neg_hi:[0,0,1]
	v_cvt_pk_bf16_f32 v32, v32, v33
	v_cvt_pk_bf16_f32 v33, v34, v35
	v_add_co_u32_e32 v34, vcc, s5, v40
	s_waitcnt lgkmcnt(2)
	v_pk_mul_f32 v[168:169], v[2:3], v[84:85] op_sel_hi:[1,0]
	v_addc_co_u32_e32 v35, vcc, 0, v41, vcc
	global_store_dwordx2 v[34:35], v[32:33], off offset:-4096
	v_xor_b32_e32 v33, 0x80000000, v67
	v_xor_b32_e32 v32, 0x80000000, v66
	v_div_scale_f32 v53, s[18:19], v52, v52, 1.0
	s_waitcnt vmcnt(7)
; __device__ __forceinline__ unsigned cvt_pk_bf16(float lo, float hi) { unsigned r; asm volatile("v_cvt_pk_bf16_f32 %0, %1, %2" : "=v"(r) : "v"(lo), "v"(hi)); return r; }
; template <bool BF, int W> __device__ __forceinline__ void poolp_chunk(const void* xsrc, size_t xb0, int s_base, int s0, int c, f32x4 g4, const LAS float* rinv, bf16_t* Pout) {
;     ...
;     for (int tt = 0; tt < 8; ++tt) {
;         const int s = s_base + tt;
;         S += h[W + tt] - h[tt];
;         const float inv = 1.0f / (float)min(s + 1, W);
;         const f32x4 pv = S * inv - h[W + tt];
;         u32x2 o; o.x = cvt_pk_bf16(pv[0], pv[1]); o.y = cvt_pk_bf16(pv[2], pv[3]);
;         *(u32x2*)(Pout + (size_t)tt * D) = o;
	v_pk_mul_f32 v[158:159], v[22:23], v[168:169]
	v_pk_fma_f32 v[22:23], v[22:23], v[168:169], v[32:33]
	v_xor_b32_e32 v32, 0x80000000, v62
	v_rcp_f32_e32 v62, v53
	v_pk_mul_f32 v[156:157], v[0:1], v[84:85] op_sel_hi:[1,0]
	v_xor_b32_e32 v33, 0x80000000, v63
	v_pk_mul_f32 v[166:167], v[20:21], v[156:157]
	v_pk_fma_f32 v[20:21], v[20:21], v[156:157], v[32:33]
	v_pk_add_f32 v[22:23], v[30:31], v[22:23]
	v_pk_add_f32 v[20:21], v[28:29], v[20:21]
	v_fma_f32 v28, -v53, v62, 1.0
	v_fmac_f32_e32 v62, v28, v62
	v_div_scale_f32 v28, vcc, 1.0, v52, 1.0
	v_mul_f32_e32 v29, v28, v62
	v_fma_f32 v30, -v53, v29, v28
	v_fmac_f32_e32 v29, v30, v62
	v_fma_f32 v28, -v53, v29, v28
	s_add_i32 s16, s23, 3
	v_div_fmas_f32 v28, v28, v62, v29
	v_div_fixup_f32 v28, v28, v52, 1.0
	s_min_i32 s16, s16, 15
	v_pk_fma_f32 v[30:31], v[28:29], v[22:23], v[158:159] op_sel_hi:[0,1,1] neg_lo:[0,0,1] neg_hi:[0,0,1]
	v_pk_fma_f32 v[28:29], v[28:29], v[20:21], v[166:167] op_sel_hi:[0,1,1] neg_lo:[0,0,1] neg_hi:[0,0,1]
	s_add_i32 s16, s16, 1
	v_cvt_pk_bf16_f32 v28, v28, v29
	v_cvt_pk_bf16_f32 v29, v30, v31
	v_cvt_f32_u32_e32 v30, s16
	v_pk_mul_f32 v[154:155], v[2:3], v[84:85] op_sel:[0,1]
	global_store_dwordx2 v[34:35], v[28:29], off
	v_xor_b32_e32 v29, 0x80000000, v65
	v_div_scale_f32 v31, s[16:17], v30, v30, 1.0
	v_rcp_f32_e32 v32, v31
	v_xor_b32_e32 v28, 0x80000000, v64
	v_pk_mul_f32 v[148:149], v[0:1], v[84:85] op_sel:[0,1]
	s_waitcnt vmcnt(4)
	v_pk_mul_f32 v[150:151], v[26:27], v[154:155]
	v_pk_fma_f32 v[26:27], v[26:27], v[154:155], v[28:29]
	v_xor_b32_e32 v29, 0x80000000, v47
	v_xor_b32_e32 v28, 0x80000000, v46
	v_pk_mul_f32 v[152:153], v[24:25], v[148:149]
	v_pk_fma_f32 v[24:25], v[24:25], v[148:149], v[28:29]
	s_add_i32 s15, s23, 4
	v_pk_add_f32 v[20:21], v[20:21], v[24:25]
	v_fma_f32 v24, -v31, v32, 1.0
	v_fmac_f32_e32 v32, v24, v32
	v_div_scale_f32 v24, vcc, 1.0, v30, 1.0
	v_mul_f32_e32 v25, v24, v32
	v_pk_add_f32 v[22:23], v[22:23], v[26:27]
	v_fma_f32 v26, -v31, v25, v24
	s_min_i32 s15, s15, 15
	v_fmac_f32_e32 v25, v26, v32
	s_add_i32 s15, s15, 1
	v_fma_f32 v24, -v31, v25, v24
	v_cvt_f32_u32_e32 v28, s15
	v_div_fmas_f32 v24, v24, v32, v25
	v_div_fixup_f32 v24, v24, v30, 1.0
	v_pk_fma_f32 v[26:27], v[24:25], v[22:23], v[150:151] op_sel_hi:[0,1,1] neg_lo:[0,0,1] neg_hi:[0,0,1]
	v_pk_fma_f32 v[24:25], v[24:25], v[20:21], v[152:153] op_sel_hi:[0,1,1] neg_lo:[0,0,1] neg_hi:[0,0,1]
	v_cvt_pk_bf16_f32 v24, v24, v25
	v_cvt_pk_bf16_f32 v25, v26, v27
	v_add_co_u32_e32 v26, vcc, s7, v40
	v_div_scale_f32 v29, s[16:17], v28, v28, 1.0
	s_nop 0
	v_addc_co_u32_e32 v27, vcc, 0, v41, vcc
	v_rcp_f32_e32 v30, v29
	s_waitcnt lgkmcnt(1)
	v_pk_mul_f32 v[144:145], v[2:3], v[88:89] op_sel_hi:[1,0]
	global_store_dwordx2 v[26:27], v[24:25], off offset:-4096
	v_xor_b32_e32 v25, 0x80000000, v61
	v_xor_b32_e32 v24, 0x80000000, v60
	v_pk_mul_f32 v[138:139], v[0:1], v[88:89] op_sel_hi:[1,0]
	s_waitcnt vmcnt(4)
; __device__ __forceinline__ unsigned cvt_pk_bf16(float lo, float hi) { unsigned r; asm volatile("v_cvt_pk_bf16_f32 %0, %1, %2" : "=v"(r) : "v"(lo), "v"(hi)); return r; }
; template <bool BF, int W> __device__ __forceinline__ void poolp_chunk(const void* xsrc, size_t xb0, int s_base, int s0, int c, f32x4 g4, const LAS float* rinv, bf16_t* Pout) {
;     ...
;     for (int tt = 0; tt < 8; ++tt) {
;         const int s = s_base + tt;
;         S += h[W + tt] - h[tt];
;         const float inv = 1.0f / (float)min(s + 1, W);
;         const f32x4 pv = S * inv - h[W + tt];
;         u32x2 o; o.x = cvt_pk_bf16(pv[0], pv[1]); o.y = cvt_pk_bf16(pv[2], pv[3]);
;         *(u32x2*)(Pout + (size_t)tt * D) = o;
;     }
	v_pk_mul_f32 v[140:141], v[18:19], v[144:145]
	v_pk_fma_f32 v[18:19], v[18:19], v[144:145], v[24:25]
	v_xor_b32_e32 v25, 0x80000000, v57
	v_xor_b32_e32 v24, 0x80000000, v56
	v_pk_mul_f32 v[142:143], v[16:17], v[138:139]
	v_pk_fma_f32 v[16:17], v[16:17], v[138:139], v[24:25]
	v_pk_add_f32 v[18:19], v[22:23], v[18:19]
	v_pk_add_f32 v[16:17], v[20:21], v[16:17]
	v_fma_f32 v20, -v29, v30, 1.0
	v_fmac_f32_e32 v30, v20, v30
	v_div_scale_f32 v20, vcc, 1.0, v28, 1.0
	v_mul_f32_e32 v21, v20, v30
	v_fma_f32 v22, -v29, v21, v20
	v_fmac_f32_e32 v21, v22, v30
	v_fma_f32 v20, -v29, v21, v20
	s_add_i32 s14, s23, 5
	v_div_fmas_f32 v20, v20, v30, v21
	v_div_fixup_f32 v20, v20, v28, 1.0
	s_min_i32 s14, s14, 15
	v_pk_fma_f32 v[22:23], v[20:21], v[18:19], v[140:141] op_sel_hi:[0,1,1] neg_lo:[0,0,1] neg_hi:[0,0,1]
	v_pk_fma_f32 v[20:21], v[20:21], v[16:17], v[142:143] op_sel_hi:[0,1,1] neg_lo:[0,0,1] neg_hi:[0,0,1]
	s_add_i32 s14, s14, 1
	v_cvt_pk_bf16_f32 v20, v20, v21
	v_cvt_pk_bf16_f32 v21, v22, v23
	v_cvt_f32_u32_e32 v22, s14
	v_pk_mul_f32 v[130:131], v[2:3], v[88:89] op_sel:[0,1]
	global_store_dwordx2 v[26:27], v[20:21], off
	v_xor_b32_e32 v21, 0x80000000, v59
	v_div_scale_f32 v23, s[14:15], v22, v22, 1.0
	v_rcp_f32_e32 v24, v23
	v_xor_b32_e32 v20, 0x80000000, v58
	v_pk_mul_f32 v[126:127], v[0:1], v[88:89] op_sel:[0,1]
	v_pk_mul_f32 v[122:123], v[14:15], v[130:131]
	v_pk_fma_f32 v[14:15], v[14:15], v[130:131], v[20:21]
	v_xor_b32_e32 v21, 0x80000000, v45
	v_xor_b32_e32 v20, 0x80000000, v44
	v_pk_mul_f32 v[124:125], v[12:13], v[126:127]
	v_pk_fma_f32 v[12:13], v[12:13], v[126:127], v[20:21]
	s_add_i32 s11, s23, 6
	v_pk_add_f32 v[12:13], v[16:17], v[12:13]
	v_fma_f32 v16, -v23, v24, 1.0
	v_fmac_f32_e32 v24, v16, v24
	v_div_scale_f32 v16, vcc, 1.0, v22, 1.0
	v_mul_f32_e32 v17, v16, v24
	v_pk_add_f32 v[14:15], v[18:19], v[14:15]
	v_fma_f32 v18, -v23, v17, v16
	s_min_i32 s11, s11, 15
	v_fmac_f32_e32 v17, v18, v24
	s_add_i32 s11, s11, 1
	v_fma_f32 v16, -v23, v17, v16
	v_cvt_f32_u32_e32 v20, s11
	v_div_fmas_f32 v16, v16, v24, v17
	v_div_fixup_f32 v16, v16, v22, 1.0
	v_pk_fma_f32 v[18:19], v[16:17], v[14:15], v[122:123] op_sel_hi:[0,1,1] neg_lo:[0,0,1] neg_hi:[0,0,1]
	v_pk_fma_f32 v[16:17], v[16:17], v[12:13], v[124:125] op_sel_hi:[0,1,1] neg_lo:[0,0,1] neg_hi:[0,0,1]
	v_cvt_pk_bf16_f32 v16, v16, v17
	v_cvt_pk_bf16_f32 v17, v18, v19
	v_add_co_u32_e32 v18, vcc, s77, v40
	v_div_scale_f32 v21, s[14:15], v20, v20, 1.0
	s_nop 0
	v_addc_co_u32_e32 v19, vcc, 0, v41, vcc
	v_rcp_f32_e32 v22, v21
	s_waitcnt lgkmcnt(0)
	v_pk_mul_f32 v[116:117], v[2:3], v[94:95] op_sel_hi:[1,0]
	global_store_dwordx2 v[18:19], v[16:17], off offset:-4096
	v_xor_b32_e32 v17, 0x80000000, v55
	v_xor_b32_e32 v16, 0x80000000, v54
	v_pk_mul_f32 v[112:113], v[0:1], v[94:95] op_sel_hi:[1,0]
	v_pk_mul_f32 v[106:107], v[10:11], v[116:117]
	v_pk_fma_f32 v[10:11], v[10:11], v[116:117], v[16:17]
	v_xor_b32_e32 v17, 0x80000000, v49
	v_xor_b32_e32 v16, 0x80000000, v48
	v_pk_mul_f32 v[108:109], v[8:9], v[112:113]
	v_pk_fma_f32 v[8:9], v[8:9], v[112:113], v[16:17]
	v_pk_add_f32 v[10:11], v[14:15], v[10:11]
	v_pk_add_f32 v[8:9], v[12:13], v[8:9]
	v_fma_f32 v12, -v21, v22, 1.0
	v_fmac_f32_e32 v22, v12, v22
	v_div_scale_f32 v12, vcc, 1.0, v20, 1.0
	v_mul_f32_e32 v13, v12, v22
	v_fma_f32 v14, -v21, v13, v12
	v_fmac_f32_e32 v13, v14, v22
	v_fma_f32 v12, -v21, v13, v12
	s_add_i32 s10, s23, 7
	v_div_fmas_f32 v12, v12, v22, v13
	v_div_fixup_f32 v12, v12, v20, 1.0
	s_min_i32 s10, s10, 15
	v_pk_fma_f32 v[14:15], v[12:13], v[10:11], v[106:107] op_sel_hi:[0,1,1] neg_lo:[0,0,1] neg_hi:[0,0,1]
	v_pk_fma_f32 v[12:13], v[12:13], v[8:9], v[108:109] op_sel_hi:[0,1,1] neg_lo:[0,0,1] neg_hi:[0,0,1]
	s_add_i32 s10, s10, 1
	v_cvt_pk_bf16_f32 v12, v12, v13
	v_cvt_pk_bf16_f32 v13, v14, v15
	v_cvt_f32_u32_e32 v14, s10
	v_pk_mul_f32 v[88:89], v[0:1], v[94:95] op_sel:[0,1]
	v_pk_mul_f32 v[94:95], v[2:3], v[94:95] op_sel:[0,1]
	global_store_dwordx2 v[18:19], v[12:13], off
	v_div_scale_f32 v15, s[10:11], v14, v14, 1.0
	v_rcp_f32_e32 v16, v15
	v_xor_b32_e32 v13, 0x80000000, v51
	v_xor_b32_e32 v12, 0x80000000, v50
	v_pk_mul_f32 v[82:83], v[6:7], v[94:95]
	v_pk_fma_f32 v[6:7], v[6:7], v[94:95], v[12:13]
	v_xor_b32_e32 v13, 0x80000000, v43
	v_xor_b32_e32 v12, 0x80000000, v42
	v_pk_mul_f32 v[84:85], v[4:5], v[88:89]
	v_pk_fma_f32 v[4:5], v[4:5], v[88:89], v[12:13]
	v_pk_add_f32 v[6:7], v[10:11], v[6:7]
	v_pk_add_f32 v[4:5], v[8:9], v[4:5]
	v_fma_f32 v8, -v15, v16, 1.0
	v_fmac_f32_e32 v16, v8, v16
	v_div_scale_f32 v8, vcc, 1.0, v14, 1.0
	v_mul_f32_e32 v9, v8, v16
	v_fma_f32 v10, -v15, v9, v8
	v_fmac_f32_e32 v9, v10, v16
	v_fma_f32 v8, -v15, v9, v8
	v_div_fmas_f32 v8, v8, v16, v9
	v_div_fixup_f32 v8, v8, v14, 1.0
	v_pk_fma_f32 v[4:5], v[8:9], v[4:5], v[84:85] op_sel_hi:[0,1,1] neg_lo:[0,0,1] neg_hi:[0,0,1]
	s_andn2_b64 s[0:1], s[0:1], exec
	v_pk_fma_f32 v[6:7], v[8:9], v[6:7], v[82:83] op_sel_hi:[0,1,1] neg_lo:[0,0,1] neg_hi:[0,0,1]
	v_cvt_pk_bf16_f32 v4, v4, v5
	v_cvt_pk_bf16_f32 v5, v6, v7
	s_or_b64 exec, exec, s[2:3]
	s_and_saveexec_b64 s[2:3], s[0:1]
	s_xor_b64 s[0:1], exec, s[2:3]
	s_cbranch_execz .LBB0_1427
